# Hyena FFT stagger: waves 4-7 sleep 6x64 cycles at the head of the two three-pass chains per channel
# speedup vs baseline: 1.0088x; 1.0088x over previous
; #define WG_SYNC() do { asm volatile("s_waitcnt lgkmcnt(0)" ::: "memory"); __builtin_amdgcn_s_barrier(); asm volatile("" ::: "memory"); } while (0)
; template <bool INV> __device__ __forceinline__ void dft16(f32x2 (&x)[16]) {
;     ...
;     for (int b = 0; b < 4; ++b) dft4<INV>(x[b], x[4 + b], x[8 + b], x[12 + b]);
;     const f32x2 w1 = {C1, -S1}, w2 = {C2, -C2}, w3 = {S1, -C1}, w4 = {0.f, -1.f}, w6 = {-C2, -C2}, w9 = {-C1, S1};
; __device__ __forceinline__ void hyena_fft(LAS unsigned char* lds, int layer, int G, const int wave_s) {
;     ...
;         for (int c = c_lo; c < c_hi; ++c) { const int unit = c >> 2, jc = c & 3;
;             WG_SYNC();
;             { f32x2 x[16]; const unsigned* tf = TF + (size_t)c * SEQ; const unsigned* tb = TB + (size_t)c * SEQ;
; #pragma unroll
;               for (int r = 0; r < 8; ++r) { const unsigned w = tf[n2 + 512 * r]; x[r] = (f32x2){bf_lo(w), bf_hi(w)}; }
; #pragma unroll
;               for (int r = 8; r < 16; ++r) { const int l = FN - 512 * r - n2; const unsigned w = l < SEQ ? tb[l] : 0u; x[r] = (f32x2){bf_lo(w), bf_hi(w)}; }
.Lhfft_loop:
	s_lshr_b32 s43, s80, 2
	s_mul_i32 s73, s43, 0x11000
	s_and_b32 s43, s80, 2
	s_lshl_b32 s43, s43, 1
	s_add_u32 s73, s73, s43
	s_and_b32 s43, s80, 1
	s_mov_b32 s15, 0x1000c0c
	s_cmp_eq_u32 s43, 0
	s_cselect_b32 s15, s15, 0x3020c0c
	s_lshl_b32 s43, s80, 14
	s_add_u32 s46, s36, s43
	s_addc_u32 s47, s37, 0
	s_add_u32 s50, s46, 0x4000000
	s_addc_u32 s51, s47, 0
	s_waitcnt lgkmcnt(0)
	s_barrier
	s_add_u32 s60, s46, 0
	s_addc_u32 s61, s47, 0
	global_load_dword v176, v212, s[60:61]
	global_load_dword v178, v212, s[60:61] offset:2048
	s_add_u32 s60, s46, 0x1000
	s_addc_u32 s61, s47, 0
	global_load_dword v180, v212, s[60:61]
	global_load_dword v182, v212, s[60:61] offset:2048
	s_add_u32 s60, s46, 0x2000
	s_addc_u32 s61, s47, 0
	global_load_dword v184, v212, s[60:61]
	global_load_dword v186, v212, s[60:61] offset:2048
	s_add_u32 s60, s46, 0x3000
	s_addc_u32 s61, s47, 0
	global_load_dword v188, v212, s[60:61]
	global_load_dword v166, v212, s[60:61] offset:2048
	s_add_u32 s62, s50, 0x3000
	s_addc_u32 s63, s51, 0
	global_load_dword v177, v214, s[62:63] offset:2048
	global_load_dword v179, v214, s[62:63]
	s_add_u32 s62, s50, 0x2000
	s_addc_u32 s63, s51, 0
	global_load_dword v181, v214, s[62:63] offset:2048
	global_load_dword v183, v214, s[62:63]
	s_add_u32 s62, s50, 0x1000
	s_addc_u32 s63, s51, 0
	global_load_dword v185, v214, s[62:63] offset:2048
	global_load_dword v187, v214, s[62:63]
	s_add_u32 s62, s50, 0
	s_addc_u32 s63, s51, 0
	global_load_dword v189, v214, s[62:63] offset:2048
	global_load_dword v167, v214, s[62:63]
	s_add_u32 s56, s38, s73
	s_addc_u32 s57, s39, 0
	s_add_u32 s56, s56, 0x2200000
	s_addc_u32 s57, s57, 0
	global_load_dwordx3 v[58:60], v216, s[56:57]
	global_load_dwordx3 v[62:64], v218, s[56:57]
	global_load_dwordx3 v[66:68], v220, s[56:57]
	global_load_dwordx3 v[70:72], v222, s[56:57]
	global_load_dwordx3 v[74:76], v240, s[56:57]
	global_load_dwordx3 v[78:80], v242, s[56:57]
	global_load_dwordx3 v[82:84], v244, s[56:57]
	global_load_dwordx3 v[86:88], v61, s[56:57]
	s_waitcnt vmcnt(23)
	v_and_b32_e32 v101, 0xffff0000, v176
	v_lshlrev_b32_e32 v100, 16, v176
	s_waitcnt vmcnt(22)
	v_and_b32_e32 v103, 0xffff0000, v178
	v_lshlrev_b32_e32 v102, 16, v178
	s_waitcnt vmcnt(21)
	v_and_b32_e32 v105, 0xffff0000, v180
	v_lshlrev_b32_e32 v104, 16, v180
	s_waitcnt vmcnt(20)
	v_and_b32_e32 v107, 0xffff0000, v182
	v_lshlrev_b32_e32 v106, 16, v182
	s_waitcnt vmcnt(19)
	v_and_b32_e32 v109, 0xffff0000, v184
	v_lshlrev_b32_e32 v108, 16, v184
	s_waitcnt vmcnt(18)
	v_and_b32_e32 v111, 0xffff0000, v186
	v_lshlrev_b32_e32 v110, 16, v186
	s_waitcnt vmcnt(17)
	v_and_b32_e32 v113, 0xffff0000, v188
	v_lshlrev_b32_e32 v112, 16, v188
	s_waitcnt vmcnt(16)
	v_and_b32_e32 v115, 0xffff0000, v166
	v_lshlrev_b32_e32 v114, 16, v166
	s_waitcnt vmcnt(15)
	v_cndmask_b32_e64 v177, v177, 0, s[10:11]
	v_and_b32_e32 v117, 0xffff0000, v177
	v_lshlrev_b32_e32 v116, 16, v177
	s_waitcnt vmcnt(14)
	v_and_b32_e32 v119, 0xffff0000, v179
	v_lshlrev_b32_e32 v118, 16, v179
	s_waitcnt vmcnt(13)
	v_and_b32_e32 v121, 0xffff0000, v181
	v_lshlrev_b32_e32 v120, 16, v181
	s_waitcnt vmcnt(12)
	v_and_b32_e32 v123, 0xffff0000, v183
	v_lshlrev_b32_e32 v122, 16, v183
	s_waitcnt vmcnt(11)
	v_and_b32_e32 v125, 0xffff0000, v185
	v_lshlrev_b32_e32 v124, 16, v185
	s_waitcnt vmcnt(10)
	v_and_b32_e32 v127, 0xffff0000, v187
	v_lshlrev_b32_e32 v126, 16, v187
	s_waitcnt vmcnt(9)
	v_and_b32_e32 v129, 0xffff0000, v189
	v_lshlrev_b32_e32 v128, 16, v189
	s_waitcnt vmcnt(8)
	v_and_b32_e32 v131, 0xffff0000, v167
	v_lshlrev_b32_e32 v130, 16, v167
	v_pk_add_f32 v[168:169], v[100:101], v[116:117]
	v_pk_add_f32 v[174:175], v[100:101], v[116:117] neg_lo:[0,1] neg_hi:[0,1]
	v_pk_add_f32 v[176:177], v[108:109], v[124:125]
	v_pk_add_f32 v[178:179], v[108:109], v[124:125] neg_lo:[0,1] neg_hi:[0,1]
	v_pk_add_f32 v[100:101], v[168:169], v[176:177]
	v_pk_add_f32 v[116:117], v[168:169], v[176:177] neg_lo:[0,1] neg_hi:[0,1]
	v_pk_add_f32 v[108:109], v[174:175], v[178:179] op_sel:[0,1] op_sel_hi:[1,0] neg_hi:[0,1]
	v_pk_add_f32 v[124:125], v[174:175], v[178:179] op_sel:[0,1] op_sel_hi:[1,0] neg_lo:[0,1]
	v_pk_add_f32 v[180:181], v[102:103], v[118:119]
	v_pk_add_f32 v[182:183], v[102:103], v[118:119] neg_lo:[0,1] neg_hi:[0,1]
	v_pk_add_f32 v[184:185], v[110:111], v[126:127]
	v_pk_add_f32 v[186:187], v[110:111], v[126:127] neg_lo:[0,1] neg_hi:[0,1]
	v_pk_add_f32 v[102:103], v[180:181], v[184:185]
	v_pk_add_f32 v[118:119], v[180:181], v[184:185] neg_lo:[0,1] neg_hi:[0,1]
	v_pk_add_f32 v[110:111], v[182:183], v[186:187] op_sel:[0,1] op_sel_hi:[1,0] neg_hi:[0,1]
	v_pk_add_f32 v[126:127], v[182:183], v[186:187] op_sel:[0,1] op_sel_hi:[1,0] neg_lo:[0,1]
	v_pk_add_f32 v[188:189], v[104:105], v[120:121]
	v_pk_add_f32 v[166:167], v[104:105], v[120:121] neg_lo:[0,1] neg_hi:[0,1]
	v_pk_add_f32 v[168:169], v[112:113], v[128:129]
	v_pk_add_f32 v[174:175], v[112:113], v[128:129] neg_lo:[0,1] neg_hi:[0,1]
	v_pk_add_f32 v[104:105], v[188:189], v[168:169]
	v_pk_add_f32 v[120:121], v[188:189], v[168:169] neg_lo:[0,1] neg_hi:[0,1]
	v_pk_add_f32 v[112:113], v[166:167], v[174:175] op_sel:[0,1] op_sel_hi:[1,0] neg_hi:[0,1]
	v_pk_add_f32 v[128:129], v[166:167], v[174:175] op_sel:[0,1] op_sel_hi:[1,0] neg_lo:[0,1]
	v_pk_add_f32 v[176:177], v[106:107], v[122:123]
	v_pk_add_f32 v[178:179], v[106:107], v[122:123] neg_lo:[0,1] neg_hi:[0,1]
	v_pk_add_f32 v[180:181], v[114:115], v[130:131]
	v_pk_add_f32 v[182:183], v[114:115], v[130:131] neg_lo:[0,1] neg_hi:[0,1]
	v_pk_add_f32 v[106:107], v[176:177], v[180:181]
	v_pk_add_f32 v[122:123], v[176:177], v[180:181] neg_lo:[0,1] neg_hi:[0,1]
	v_pk_add_f32 v[114:115], v[178:179], v[182:183] op_sel:[0,1] op_sel_hi:[1,0] neg_hi:[0,1]
; __device__ __forceinline__ f32x2 cmul(f32x2 a, f32x2 b) { return (f32x2){a.x * b.x - a.y * b.y, a.x * b.y + a.y * b.x}; }
; template <bool INV> __device__ __forceinline__ f32x2 cmul_tw(f32x2 a, f32x2 w) { return INV ? cmulc(a, w) : cmul(a, w); }
; template <bool INV> __device__ __forceinline__ void dft16(f32x2 (&x)[16]) {
;     ...
;     const f32x2 w1 = {C1, -S1}, w2 = {C2, -C2}, w3 = {S1, -C1}, w4 = {0.f, -1.f}, w6 = {-C2, -C2}, w9 = {-C1, S1};
;     x[4 * 1 + 1] = cmul_tw<INV>(x[5], w1); x[4 * 1 + 2] = cmul_tw<INV>(x[6], w2); x[4 * 1 + 3] = cmul_tw<INV>(x[7], w3);
;     x[4 * 2 + 1] = cmul_tw<INV>(x[9], w2); x[4 * 2 + 2] = cmul_tw<INV>(x[10], w4); x[4 * 2 + 3] = cmul_tw<INV>(x[11], w6);
;     x[4 * 3 + 1] = cmul_tw<INV>(x[13], w3); x[4 * 3 + 2] = cmul_tw<INV>(x[14], w6); x[4 * 3 + 3] = cmul_tw<INV>(x[15], w9);
; #pragma unroll
;     for (int c = 0; c < 4; ++c) dft4<INV>(x[4 * c], x[4 * c + 1], x[4 * c + 2], x[4 * c + 3]);
;     f32x2 y[16];
; #pragma unroll
;     for (int k = 0; k < 16; ++k) y[k] = x[4 * (k & 3) + (k >> 2)];
; #pragma unroll
;     for (int k = 0; k < 16; ++k) x[k] = y[k];
; template <bool LO> __device__ __forceinline__ void fft_fwd1(f32x2 (&x)[16], LAS f32x2* B, int n2, const f32x2 (&w)[16]) {
;     ...
;     B[fpad(n2)] = x[0];
; #pragma unroll
;     for (int k = 1; k < 16; ++k) B[fpad(512 * k + n2)] = cmul(x[k], w[k]);
	v_pk_add_f32 v[130:131], v[178:179], v[182:183] op_sel:[0,1] op_sel_hi:[1,0] neg_lo:[0,1]
	v_pk_mul_f32 v[184:185], v[110:111], s[68:69] op_sel:[1,1] op_sel_hi:[0,1]
	v_pk_fma_f32 v[110:111], v[110:111], s[68:69], v[184:185] op_sel_hi:[1,0,1] neg_lo:[0,0,1]
	v_pk_mul_f32 v[186:187], v[112:113], s[84:85] op_sel:[1,1] op_sel_hi:[0,1]
	v_pk_fma_f32 v[112:113], v[112:113], s[84:85], v[186:187] op_sel_hi:[1,0,1] neg_lo:[0,0,1]
	v_pk_mul_f32 v[188:189], v[114:115], s[88:89] op_sel:[1,1] op_sel_hi:[0,1]
	v_pk_fma_f32 v[114:115], v[114:115], s[88:89], v[188:189] op_sel_hi:[1,0,1] neg_lo:[0,0,1]
	v_pk_mul_f32 v[166:167], v[118:119], s[84:85] op_sel:[1,1] op_sel_hi:[0,1]
	v_pk_fma_f32 v[118:119], v[118:119], s[84:85], v[166:167] op_sel_hi:[1,0,1] neg_lo:[0,0,1]
	v_pk_mul_f32 v[168:169], v[122:123], s[90:91] op_sel:[1,1] op_sel_hi:[0,1]
	v_pk_fma_f32 v[122:123], v[122:123], s[90:91], v[168:169] op_sel_hi:[1,0,1] neg_lo:[0,0,1]
	v_pk_mul_f32 v[174:175], v[126:127], s[88:89] op_sel:[1,1] op_sel_hi:[0,1]
	v_pk_fma_f32 v[126:127], v[126:127], s[88:89], v[174:175] op_sel_hi:[1,0,1] neg_lo:[0,0,1]
	v_pk_mul_f32 v[176:177], v[128:129], s[90:91] op_sel:[1,1] op_sel_hi:[0,1]
	v_pk_fma_f32 v[128:129], v[128:129], s[90:91], v[176:177] op_sel_hi:[1,0,1] neg_lo:[0,0,1]
	v_pk_mul_f32 v[178:179], v[130:131], s[98:99] op_sel:[1,1] op_sel_hi:[0,1]
	v_pk_fma_f32 v[130:131], v[130:131], s[98:99], v[178:179] op_sel_hi:[1,0,1] neg_lo:[0,0,1]
	v_pk_add_f32 v[180:181], v[100:101], v[104:105]
	v_pk_add_f32 v[182:183], v[100:101], v[104:105] neg_lo:[0,1] neg_hi:[0,1]
	v_pk_add_f32 v[184:185], v[102:103], v[106:107]
	v_pk_add_f32 v[186:187], v[102:103], v[106:107] neg_lo:[0,1] neg_hi:[0,1]
	v_pk_add_f32 v[100:101], v[180:181], v[184:185]
	v_pk_add_f32 v[104:105], v[180:181], v[184:185] neg_lo:[0,1] neg_hi:[0,1]
	v_pk_add_f32 v[102:103], v[182:183], v[186:187] op_sel:[0,1] op_sel_hi:[1,0] neg_hi:[0,1]
	v_pk_add_f32 v[106:107], v[182:183], v[186:187] op_sel:[0,1] op_sel_hi:[1,0] neg_lo:[0,1]
	v_pk_add_f32 v[188:189], v[108:109], v[112:113]
	v_pk_add_f32 v[166:167], v[108:109], v[112:113] neg_lo:[0,1] neg_hi:[0,1]
	v_pk_add_f32 v[168:169], v[110:111], v[114:115]
	v_pk_add_f32 v[174:175], v[110:111], v[114:115] neg_lo:[0,1] neg_hi:[0,1]
	v_pk_add_f32 v[108:109], v[188:189], v[168:169]
	v_pk_add_f32 v[112:113], v[188:189], v[168:169] neg_lo:[0,1] neg_hi:[0,1]
	v_pk_add_f32 v[110:111], v[166:167], v[174:175] op_sel:[0,1] op_sel_hi:[1,0] neg_hi:[0,1]
	v_pk_add_f32 v[114:115], v[166:167], v[174:175] op_sel:[0,1] op_sel_hi:[1,0] neg_lo:[0,1]
	v_pk_add_f32 v[176:177], v[116:117], v[120:121] op_sel:[0,1] op_sel_hi:[1,0] neg_hi:[0,1]
	v_pk_add_f32 v[178:179], v[116:117], v[120:121] op_sel:[0,1] op_sel_hi:[1,0] neg_lo:[0,1]
	v_pk_add_f32 v[180:181], v[118:119], v[122:123]
	v_pk_add_f32 v[182:183], v[118:119], v[122:123] neg_lo:[0,1] neg_hi:[0,1]
	v_pk_add_f32 v[116:117], v[176:177], v[180:181]
	v_pk_add_f32 v[120:121], v[176:177], v[180:181] neg_lo:[0,1] neg_hi:[0,1]
	v_pk_add_f32 v[118:119], v[178:179], v[182:183] op_sel:[0,1] op_sel_hi:[1,0] neg_hi:[0,1]
	v_pk_add_f32 v[122:123], v[178:179], v[182:183] op_sel:[0,1] op_sel_hi:[1,0] neg_lo:[0,1]
	v_pk_add_f32 v[184:185], v[124:125], v[128:129]
	v_pk_add_f32 v[186:187], v[124:125], v[128:129] neg_lo:[0,1] neg_hi:[0,1]
	v_pk_add_f32 v[188:189], v[126:127], v[130:131]
	v_pk_add_f32 v[166:167], v[126:127], v[130:131] neg_lo:[0,1] neg_hi:[0,1]
	v_pk_add_f32 v[124:125], v[184:185], v[188:189]
	v_pk_add_f32 v[128:129], v[184:185], v[188:189] neg_lo:[0,1] neg_hi:[0,1]
	v_pk_add_f32 v[126:127], v[186:187], v[166:167] op_sel:[0,1] op_sel_hi:[1,0] neg_hi:[0,1]
	v_pk_add_f32 v[130:131], v[186:187], v[166:167] op_sel:[0,1] op_sel_hi:[1,0] neg_lo:[0,1]
	v_add_u32_e32 v65, 0x10800, v3
	ds_write_b64 v65, v[100:101]
	v_pk_mul_f32 v[174:175], v[108:109], v[6:7] op_sel:[1,1] op_sel_hi:[0,1]
	v_pk_fma_f32 v[168:169], v[108:109], v[6:7], v[174:175] op_sel_hi:[1,0,1] neg_lo:[0,0,1]
	ds_write_b64 v65, v[168:169] offset:4224
	v_pk_mul_f32 v[178:179], v[116:117], v[8:9] op_sel:[1,1] op_sel_hi:[0,1]
	v_pk_fma_f32 v[176:177], v[116:117], v[8:9], v[178:179] op_sel_hi:[1,0,1] neg_lo:[0,0,1]
	ds_write_b64 v65, v[176:177] offset:8448
	v_pk_mul_f32 v[182:183], v[124:125], v[10:11] op_sel:[1,1] op_sel_hi:[0,1]
	v_pk_fma_f32 v[180:181], v[124:125], v[10:11], v[182:183] op_sel_hi:[1,0,1] neg_lo:[0,0,1]
	ds_write_b64 v65, v[180:181] offset:12672
	v_pk_mul_f32 v[186:187], v[102:103], v[12:13] op_sel:[1,1] op_sel_hi:[0,1]
	v_pk_fma_f32 v[184:185], v[102:103], v[12:13], v[186:187] op_sel_hi:[1,0,1] neg_lo:[0,0,1]
	ds_write_b64 v65, v[184:185] offset:16896
	v_pk_mul_f32 v[166:167], v[110:111], v[14:15] op_sel:[1,1] op_sel_hi:[0,1]
	v_pk_fma_f32 v[188:189], v[110:111], v[14:15], v[166:167] op_sel_hi:[1,0,1] neg_lo:[0,0,1]
	ds_write_b64 v65, v[188:189] offset:21120
	v_pk_mul_f32 v[168:169], v[118:119], v[16:17] op_sel:[1,1] op_sel_hi:[0,1]
	v_pk_fma_f32 v[174:175], v[118:119], v[16:17], v[168:169] op_sel_hi:[1,0,1] neg_lo:[0,0,1]
	ds_write_b64 v65, v[174:175] offset:25344
	v_pk_mul_f32 v[176:177], v[126:127], v[18:19] op_sel:[1,1] op_sel_hi:[0,1]
	v_pk_fma_f32 v[178:179], v[126:127], v[18:19], v[176:177] op_sel_hi:[1,0,1] neg_lo:[0,0,1]
	ds_write_b64 v65, v[178:179] offset:29568
	v_pk_mul_f32 v[180:181], v[104:105], v[20:21] op_sel:[1,1] op_sel_hi:[0,1]
	v_pk_fma_f32 v[182:183], v[104:105], v[20:21], v[180:181] op_sel_hi:[1,0,1] neg_lo:[0,0,1]
	ds_write_b64 v65, v[182:183] offset:33792
	v_pk_mul_f32 v[184:185], v[112:113], v[22:23] op_sel:[1,1] op_sel_hi:[0,1]
	v_pk_fma_f32 v[186:187], v[112:113], v[22:23], v[184:185] op_sel_hi:[1,0,1] neg_lo:[0,0,1]
	ds_write_b64 v65, v[186:187] offset:38016
	v_pk_mul_f32 v[188:189], v[120:121], v[24:25] op_sel:[1,1] op_sel_hi:[0,1]
	v_pk_fma_f32 v[166:167], v[120:121], v[24:25], v[188:189] op_sel_hi:[1,0,1] neg_lo:[0,0,1]
	ds_write_b64 v65, v[166:167] offset:42240
	v_pk_mul_f32 v[174:175], v[128:129], v[26:27] op_sel:[1,1] op_sel_hi:[0,1]
	v_pk_fma_f32 v[168:169], v[128:129], v[26:27], v[174:175] op_sel_hi:[1,0,1] neg_lo:[0,0,1]
	ds_write_b64 v65, v[168:169] offset:46464
	v_pk_mul_f32 v[178:179], v[106:107], v[28:29] op_sel:[1,1] op_sel_hi:[0,1]
	v_pk_fma_f32 v[176:177], v[106:107], v[28:29], v[178:179] op_sel_hi:[1,0,1] neg_lo:[0,0,1]
	ds_write_b64 v65, v[176:177] offset:50688
	v_pk_mul_f32 v[182:183], v[114:115], v[30:31] op_sel:[1,1] op_sel_hi:[0,1]
	v_pk_fma_f32 v[180:181], v[114:115], v[30:31], v[182:183] op_sel_hi:[1,0,1] neg_lo:[0,0,1]
	ds_write_b64 v65, v[180:181] offset:54912
	v_pk_mul_f32 v[186:187], v[122:123], v[32:33] op_sel:[1,1] op_sel_hi:[0,1]
	v_pk_fma_f32 v[184:185], v[122:123], v[32:33], v[186:187] op_sel_hi:[1,0,1] neg_lo:[0,0,1]
	ds_write_b64 v65, v[184:185] offset:59136
	v_pk_mul_f32 v[166:167], v[130:131], v[34:35] op_sel:[1,1] op_sel_hi:[0,1]
	v_pk_fma_f32 v[188:189], v[130:131], v[34:35], v[166:167] op_sel_hi:[1,0,1] neg_lo:[0,0,1]
	ds_write_b64 v65, v[188:189] offset:63360
	s_waitcnt vmcnt(7)
; #define LAS __attribute__((address_space(3)))
; __device__ __forceinline__ void hy_stage(LAS float* plane, const bf16_t* PHY, int cg, int jc, int tid) {
;     asm volatile("" : "+v"(tid));
;     const u32x4* src = (const u32x4*)(PHY + (size_t)cg * MT * 4);
; #pragma unroll
;     for (int k = 0; k < 8; ++k) { const int i = tid + 512 * k; const u32x4 v = src[i];
;         const unsigned w0 = (jc & 2) ? v.y : v.x, w1 = (jc & 2) ? v.w : v.z;
;         f32x2 o; o.x = (jc & 1) ? bf_hi(w0) : bf_lo(w0); o.y = (jc & 1) ? bf_hi(w1) : bf_lo(w1);
;         *(LAS f32x2*)(plane + 2 * i) = o; }
; }
; __device__ __forceinline__ void hy_sconv(const LAS float* plane, float w0, float w1, float w2, float cb, int n2, float (&u)[8][2]) {
;     asm volatile("" : "+v"(n2));
; #pragma unroll
;     for (int r = 0; r < 8; ++r)
; #pragma unroll
;         for (int b = 0; b < 2; ++b) { const int t = n2 + 512 * r, row = b * SEQ + t;
;             float a = cb + w1 * plane[row];
;             if (t > 0) a += w0 * plane[row - 1];
;             if (t < SEQ - 1) a += w2 * plane[row + 1];
;             u[r][b] = a; }
; }
	v_perm_b32 v174, 0, v58, s15
	v_perm_b32 v175, 0, v60, s15
	ds_write_b64 v206, v[174:175]
	s_waitcnt vmcnt(6)
	v_perm_b32 v168, 0, v62, s15
	v_perm_b32 v169, 0, v64, s15
	ds_write_b64 v206, v[168:169] offset:4096
	s_waitcnt vmcnt(5)
	v_perm_b32 v178, 0, v66, s15
	v_perm_b32 v179, 0, v68, s15
	ds_write_b64 v206, v[178:179] offset:8192
	s_waitcnt vmcnt(4)
	v_perm_b32 v176, 0, v70, s15
	v_perm_b32 v177, 0, v72, s15
	ds_write_b64 v206, v[176:177] offset:12288
	s_waitcnt vmcnt(3)
	v_perm_b32 v182, 0, v74, s15
	v_perm_b32 v183, 0, v76, s15
	ds_write_b64 v206, v[182:183] offset:16384
	s_waitcnt vmcnt(2)
	v_perm_b32 v180, 0, v78, s15
	v_perm_b32 v181, 0, v80, s15
	ds_write_b64 v206, v[180:181] offset:20480
	s_waitcnt vmcnt(1)
	v_perm_b32 v186, 0, v82, s15
	v_perm_b32 v187, 0, v84, s15
	ds_write_b64 v206, v[186:187] offset:24576
	s_waitcnt vmcnt(0)
	v_perm_b32 v184, 0, v86, s15
	v_perm_b32 v185, 0, v88, s15
	ds_write_b64 v206, v[184:185] offset:28672
	s_add_u32 s56, s38, s73
	s_addc_u32 s57, s39, 0
	global_load_dwordx3 v[58:60], v216, s[56:57]
	global_load_dwordx3 v[62:64], v218, s[56:57]
	global_load_dwordx3 v[66:68], v220, s[56:57]
	global_load_dwordx3 v[70:72], v222, s[56:57]
	global_load_dwordx3 v[74:76], v240, s[56:57]
	global_load_dwordx3 v[78:80], v242, s[56:57]
	global_load_dwordx3 v[82:84], v244, s[56:57]
	global_load_dwordx3 v[86:88], v61, s[56:57]
	s_load_dwordx2 s[60:61], s[94:95], 0x48
	s_load_dwordx2 s[62:63], s[94:95], 0x50
	s_load_dwordx2 s[50:51], s[94:95], 0x88
	s_lshl_b32 s43, s80, 2
	s_mul_i32 s53, s76, 0x9000
	s_add_u32 s53, s53, s43
	s_mul_i32 s55, s76, 0x3000
	s_add_u32 s55, s55, s43
	s_waitcnt lgkmcnt(0)
	s_add_u32 s60, s60, s53
	s_addc_u32 s61, s61, 0
	s_add_u32 s62, s62, s55
	s_addc_u32 s63, s63, 0
	s_mul_i32 s53, s76, 0x2000
	s_add_u32 s53, s53, s43
	s_add_u32 s50, s50, s53
	s_addc_u32 s51, s51, 0
	s_load_dword s17, s[60:61], 0x2000
	s_load_dword s23, s[60:61], 0x5000
	s_load_dword s25, s[60:61], 0x8000
	s_load_dword s26, s[62:63], 0x2000
	s_waitcnt lgkmcnt(0)
	s_barrier
	v_mov_b32_e32 v166, s17
	v_mov_b32_e32 v167, s23
	v_mov_b32_e32 v188, s25
	v_mov_b32_e32 v189, s26
	ds_read_b32 v174, v208
	ds_read_b32 v168, v210
	ds_read_b32 v178, v208 offset:4
	ds_read_b32 v175, v208 offset:16384
	ds_read_b32 v169, v210 offset:16384
	ds_read_b32 v179, v208 offset:16388
	ds_read_b32 v176, v208 offset:2048
	ds_read_b32 v182, v208 offset:2044
	ds_read_b32 v180, v208 offset:2052
	ds_read_b32 v177, v208 offset:18432
	ds_read_b32 v183, v208 offset:18428
	ds_read_b32 v181, v208 offset:18436
	s_waitcnt lgkmcnt(10)
	v_cndmask_b32_e64 v168, v168, 0, s[10:11]
	s_waitcnt lgkmcnt(7)
	v_cndmask_b32_e64 v169, v169, 0, s[10:11]
	v_pk_fma_f32 v[132:133], v[166:167], v[174:175], v[188:189] op_sel:[1,0,1]
	v_pk_fma_f32 v[132:133], v[166:167], v[168:169], v[132:133] op_sel_hi:[0,1,1]
	s_waitcnt lgkmcnt(6)
	v_pk_fma_f32 v[132:133], v[188:189], v[178:179], v[132:133] op_sel_hi:[0,1,1]
	s_waitcnt lgkmcnt(2)
	v_pk_fma_f32 v[134:135], v[166:167], v[176:177], v[188:189] op_sel:[1,0,1]
	s_waitcnt lgkmcnt(1)
	v_pk_fma_f32 v[134:135], v[166:167], v[182:183], v[134:135] op_sel_hi:[0,1,1]
	s_waitcnt lgkmcnt(0)
	v_pk_fma_f32 v[134:135], v[188:189], v[180:181], v[134:135] op_sel_hi:[0,1,1]
	ds_read_b32 v186, v208 offset:4096
	ds_read_b32 v184, v208 offset:4092
	ds_read_b32 v174, v208 offset:4100
	ds_read_b32 v187, v208 offset:20480
	ds_read_b32 v185, v208 offset:20476
	ds_read_b32 v175, v208 offset:20484
	ds_read_b32 v168, v208 offset:6144
	ds_read_b32 v178, v208 offset:6140
	ds_read_b32 v176, v208 offset:6148
	ds_read_b32 v169, v208 offset:22528
	ds_read_b32 v179, v208 offset:22524
	ds_read_b32 v177, v208 offset:22532
	s_waitcnt lgkmcnt(8)
	v_pk_fma_f32 v[136:137], v[166:167], v[186:187], v[188:189] op_sel:[1,0,1]
	s_waitcnt lgkmcnt(7)
	v_pk_fma_f32 v[136:137], v[166:167], v[184:185], v[136:137] op_sel_hi:[0,1,1]
	s_waitcnt lgkmcnt(6)
	v_pk_fma_f32 v[136:137], v[188:189], v[174:175], v[136:137] op_sel_hi:[0,1,1]
	s_waitcnt lgkmcnt(2)
	v_pk_fma_f32 v[138:139], v[166:167], v[168:169], v[188:189] op_sel:[1,0,1]
	s_waitcnt lgkmcnt(1)
	v_pk_fma_f32 v[138:139], v[166:167], v[178:179], v[138:139] op_sel_hi:[0,1,1]
	s_waitcnt lgkmcnt(0)
	v_pk_fma_f32 v[138:139], v[188:189], v[176:177], v[138:139] op_sel_hi:[0,1,1]
	ds_read_b32 v182, v208 offset:8192
	ds_read_b32 v180, v208 offset:8188
	ds_read_b32 v186, v208 offset:8196
	ds_read_b32 v183, v208 offset:24576
	ds_read_b32 v181, v208 offset:24572
	ds_read_b32 v187, v208 offset:24580
	ds_read_b32 v184, v208 offset:10240
	ds_read_b32 v174, v208 offset:10236
	ds_read_b32 v168, v208 offset:10244
	ds_read_b32 v185, v208 offset:26624
	ds_read_b32 v175, v208 offset:26620
	ds_read_b32 v169, v208 offset:26628
	s_waitcnt lgkmcnt(8)
	v_pk_fma_f32 v[140:141], v[166:167], v[182:183], v[188:189] op_sel:[1,0,1]
	s_waitcnt lgkmcnt(7)
	v_pk_fma_f32 v[140:141], v[166:167], v[180:181], v[140:141] op_sel_hi:[0,1,1]
	s_waitcnt lgkmcnt(6)
	v_pk_fma_f32 v[140:141], v[188:189], v[186:187], v[140:141] op_sel_hi:[0,1,1]
	s_waitcnt lgkmcnt(2)
	v_pk_fma_f32 v[142:143], v[166:167], v[184:185], v[188:189] op_sel:[1,0,1]
	s_waitcnt lgkmcnt(1)
	v_pk_fma_f32 v[142:143], v[166:167], v[174:175], v[142:143] op_sel_hi:[0,1,1]
	s_waitcnt lgkmcnt(0)
	v_pk_fma_f32 v[142:143], v[188:189], v[168:169], v[142:143] op_sel_hi:[0,1,1]
	ds_read_b32 v178, v208 offset:12288
	ds_read_b32 v176, v208 offset:12284
	ds_read_b32 v182, v208 offset:12292
	ds_read_b32 v179, v208 offset:28672
	ds_read_b32 v177, v208 offset:28668
	ds_read_b32 v183, v208 offset:28676
	ds_read_b32 v180, v208 offset:14336
	ds_read_b32 v186, v208 offset:14332
	ds_read_b32 v184, v208 offset:14340
	ds_read_b32 v181, v208 offset:30720
	ds_read_b32 v187, v208 offset:30716
	ds_read_b32 v185, v208 offset:30724
	s_waitcnt lgkmcnt(8)
; #define LAS __attribute__((address_space(3)))
; __device__ __forceinline__ f32x2 cmul(f32x2 a, f32x2 b) { return (f32x2){a.x * b.x - a.y * b.y, a.x * b.y + a.y * b.x}; }
; __device__ __forceinline__ void fft_fwd2(LAS f32x2* B, const LAS f32x2* TW2, int tid) {
;     asm volatile("" : "+v"(tid));
;     const int b = tid >> 5, n2 = tid & 31, base = 512 * b + n2; f32x2 x[16];
; #pragma unroll
;     for (int r = 0; r < 16; ++r) x[r] = B[fpad(base + 32 * r)];
;     dft16<false>(x);
;     B[fpad(base)] = x[0];
; #pragma unroll
;     for (int k = 1; k < 16; ++k) B[fpad(base + 32 * k)] = cmul(x[k], TW2[k * 32 + n2]);
; }
; __device__ __forceinline__ void hy_stage(LAS float* plane, const bf16_t* PHY, int cg, int jc, int tid) {
;     asm volatile("" : "+v"(tid));
;     const u32x4* src = (const u32x4*)(PHY + (size_t)cg * MT * 4);
; #pragma unroll
;     for (int k = 0; k < 8; ++k) { const int i = tid + 512 * k; const u32x4 v = src[i];
;         const unsigned w0 = (jc & 2) ? v.y : v.x, w1 = (jc & 2) ? v.w : v.z;
;         f32x2 o; o.x = (jc & 1) ? bf_hi(w0) : bf_lo(w0); o.y = (jc & 1) ? bf_hi(w1) : bf_lo(w1);
;         *(LAS f32x2*)(plane + 2 * i) = o; }
; }
	v_pk_fma_f32 v[144:145], v[166:167], v[178:179], v[188:189] op_sel:[1,0,1]
	s_waitcnt lgkmcnt(7)
	v_pk_fma_f32 v[144:145], v[166:167], v[176:177], v[144:145] op_sel_hi:[0,1,1]
	s_waitcnt lgkmcnt(6)
	v_pk_fma_f32 v[144:145], v[188:189], v[182:183], v[144:145] op_sel_hi:[0,1,1]
	s_waitcnt lgkmcnt(3)
	v_cndmask_b32_e64 v184, v184, 0, s[28:29]
	s_waitcnt lgkmcnt(0)
	v_cndmask_b32_e64 v185, v185, 0, s[28:29]
	v_pk_fma_f32 v[146:147], v[166:167], v[180:181], v[188:189] op_sel:[1,0,1]
	v_pk_fma_f32 v[146:147], v[166:167], v[186:187], v[146:147] op_sel_hi:[0,1,1]
	v_pk_fma_f32 v[146:147], v[188:189], v[184:185], v[146:147] op_sel_hi:[0,1,1]
	s_load_dword s17, s[60:61], 0x0
	s_load_dword s23, s[60:61], 0x3000
	s_load_dword s25, s[60:61], 0x6000
	s_load_dword s26, s[62:63], 0x0
	s_waitcnt vmcnt(7)
	v_perm_b32 v174, 0, v58, s15
	v_perm_b32 v175, 0, v60, s15
	ds_write_b64 v206, v[174:175] offset:32768
	s_waitcnt vmcnt(6)
	v_perm_b32 v168, 0, v62, s15
	v_perm_b32 v169, 0, v64, s15
	ds_write_b64 v206, v[168:169] offset:36864
	s_waitcnt vmcnt(5)
	v_perm_b32 v178, 0, v66, s15
	v_perm_b32 v179, 0, v68, s15
	ds_write_b64 v206, v[178:179] offset:40960
	s_waitcnt vmcnt(4)
	v_perm_b32 v176, 0, v70, s15
	v_perm_b32 v177, 0, v72, s15
	ds_write_b64 v206, v[176:177] offset:45056
	s_waitcnt vmcnt(3)
	v_perm_b32 v182, 0, v74, s15
	v_perm_b32 v183, 0, v76, s15
	ds_write_b64 v206, v[182:183] offset:49152
	s_waitcnt vmcnt(2)
	v_perm_b32 v180, 0, v78, s15
	v_perm_b32 v181, 0, v80, s15
	ds_write_b64 v206, v[180:181] offset:53248
	s_waitcnt vmcnt(1)
	v_perm_b32 v186, 0, v82, s15
	v_perm_b32 v187, 0, v84, s15
	ds_write_b64 v206, v[186:187] offset:57344
	s_waitcnt vmcnt(0)
	v_perm_b32 v184, 0, v86, s15
	v_perm_b32 v185, 0, v88, s15
	ds_write_b64 v206, v[184:185] offset:61440
	s_add_u32 s56, s38, s73
	s_addc_u32 s57, s39, 0
	s_add_u32 s56, s56, 0x1100000
	s_addc_u32 s57, s57, 0
	global_load_dwordx3 v[58:60], v216, s[56:57]
	global_load_dwordx3 v[62:64], v218, s[56:57]
	global_load_dwordx3 v[66:68], v220, s[56:57]
	global_load_dwordx3 v[70:72], v222, s[56:57]
	global_load_dwordx3 v[74:76], v240, s[56:57]
	global_load_dwordx3 v[78:80], v242, s[56:57]
	global_load_dwordx3 v[82:84], v244, s[56:57]
	global_load_dwordx3 v[86:88], v61, s[56:57]
	v_add_u32_e32 v65, 0x10800, v5
	ds_read_b64 v[100:101], v65
	ds_read_b64 v[102:103], v65 offset:1056
	ds_read_b64 v[104:105], v65 offset:2112
	ds_read_b64 v[106:107], v65 offset:3168
	ds_read_b64 v[108:109], v65 offset:264
	ds_read_b64 v[110:111], v65 offset:1320
	ds_read_b64 v[112:113], v65 offset:2376
	ds_read_b64 v[114:115], v65 offset:3432
	ds_read_b64 v[116:117], v65 offset:528
	ds_read_b64 v[118:119], v65 offset:1584
	ds_read_b64 v[120:121], v65 offset:2640
	ds_read_b64 v[122:123], v65 offset:3696
	s_waitcnt lgkmcnt(8)
	ds_read_b64 v[124:125], v65 offset:792
	ds_read_b64 v[126:127], v65 offset:1848
	ds_read_b64 v[128:129], v65 offset:2904
	ds_read_b64 v[130:131], v65 offset:3960
	v_pk_add_f32 v[166:167], v[100:101], v[104:105]
	v_pk_add_f32 v[188:189], v[100:101], v[104:105] neg_lo:[0,1] neg_hi:[0,1]
	v_pk_add_f32 v[174:175], v[102:103], v[106:107]
	v_pk_add_f32 v[168:169], v[102:103], v[106:107] neg_lo:[0,1] neg_hi:[0,1]
	v_pk_add_f32 v[100:101], v[166:167], v[174:175]
	v_pk_add_f32 v[104:105], v[166:167], v[174:175] neg_lo:[0,1] neg_hi:[0,1]
	v_pk_add_f32 v[102:103], v[188:189], v[168:169] op_sel:[0,1] op_sel_hi:[1,0] neg_hi:[0,1]
	v_pk_add_f32 v[106:107], v[188:189], v[168:169] op_sel:[0,1] op_sel_hi:[1,0] neg_lo:[0,1]
	s_waitcnt lgkmcnt(9)
	v_pk_add_f32 v[178:179], v[108:109], v[112:113]
	v_pk_add_f32 v[176:177], v[108:109], v[112:113] neg_lo:[0,1] neg_hi:[0,1]
	s_waitcnt lgkmcnt(8)
	v_pk_add_f32 v[182:183], v[110:111], v[114:115]
	v_pk_add_f32 v[180:181], v[110:111], v[114:115] neg_lo:[0,1] neg_hi:[0,1]
	v_pk_add_f32 v[108:109], v[178:179], v[182:183]
	v_pk_add_f32 v[112:113], v[178:179], v[182:183] neg_lo:[0,1] neg_hi:[0,1]
	v_pk_add_f32 v[110:111], v[176:177], v[180:181] op_sel:[0,1] op_sel_hi:[1,0] neg_hi:[0,1]
	v_pk_add_f32 v[114:115], v[176:177], v[180:181] op_sel:[0,1] op_sel_hi:[1,0] neg_lo:[0,1]
	s_waitcnt lgkmcnt(5)
	v_pk_add_f32 v[186:187], v[116:117], v[120:121]
	v_pk_add_f32 v[184:185], v[116:117], v[120:121] neg_lo:[0,1] neg_hi:[0,1]
	s_waitcnt lgkmcnt(4)
	v_pk_add_f32 v[166:167], v[118:119], v[122:123]
	v_pk_add_f32 v[188:189], v[118:119], v[122:123] neg_lo:[0,1] neg_hi:[0,1]
	v_pk_add_f32 v[116:117], v[186:187], v[166:167]
	v_pk_add_f32 v[120:121], v[186:187], v[166:167] neg_lo:[0,1] neg_hi:[0,1]
	v_pk_add_f32 v[118:119], v[184:185], v[188:189] op_sel:[0,1] op_sel_hi:[1,0] neg_hi:[0,1]
	v_pk_add_f32 v[122:123], v[184:185], v[188:189] op_sel:[0,1] op_sel_hi:[1,0] neg_lo:[0,1]
	s_waitcnt lgkmcnt(1)
	v_pk_add_f32 v[174:175], v[124:125], v[128:129]
	v_pk_add_f32 v[168:169], v[124:125], v[128:129] neg_lo:[0,1] neg_hi:[0,1]
	s_waitcnt lgkmcnt(0)
; #define LAS __attribute__((address_space(3)))
; __device__ __forceinline__ f32x2 cmul(f32x2 a, f32x2 b) { return (f32x2){a.x * b.x - a.y * b.y, a.x * b.y + a.y * b.x}; }
; template <bool INV> __device__ __forceinline__ f32x2 cmul_tw(f32x2 a, f32x2 w) { return INV ? cmulc(a, w) : cmul(a, w); }
; template <bool INV> __device__ __forceinline__ void dft16(f32x2 (&x)[16]) {
;     constexpr float C1 = 0.92387953251128674f, S1 = 0.38268343236508977f, C2 = 0.70710678118654752f;
; #pragma unroll
;     for (int b = 0; b < 4; ++b) dft4<INV>(x[b], x[4 + b], x[8 + b], x[12 + b]);
;     const f32x2 w1 = {C1, -S1}, w2 = {C2, -C2}, w3 = {S1, -C1}, w4 = {0.f, -1.f}, w6 = {-C2, -C2}, w9 = {-C1, S1};
;     x[4 * 1 + 1] = cmul_tw<INV>(x[5], w1); x[4 * 1 + 2] = cmul_tw<INV>(x[6], w2); x[4 * 1 + 3] = cmul_tw<INV>(x[7], w3);
;     x[4 * 2 + 1] = cmul_tw<INV>(x[9], w2); x[4 * 2 + 2] = cmul_tw<INV>(x[10], w4); x[4 * 2 + 3] = cmul_tw<INV>(x[11], w6);
;     x[4 * 3 + 1] = cmul_tw<INV>(x[13], w3); x[4 * 3 + 2] = cmul_tw<INV>(x[14], w6); x[4 * 3 + 3] = cmul_tw<INV>(x[15], w9);
; #pragma unroll
;     for (int c = 0; c < 4; ++c) dft4<INV>(x[4 * c], x[4 * c + 1], x[4 * c + 2], x[4 * c + 3]);
;     f32x2 y[16];
; #pragma unroll
;     for (int k = 0; k < 16; ++k) y[k] = x[4 * (k & 3) + (k >> 2)];
; #pragma unroll
;     for (int k = 0; k < 16; ++k) x[k] = y[k];
; }
; __device__ __forceinline__ void fft_fwd2(LAS f32x2* B, const LAS f32x2* TW2, int tid) {
;     asm volatile("" : "+v"(tid));
;     const int b = tid >> 5, n2 = tid & 31, base = 512 * b + n2; f32x2 x[16];
; #pragma unroll
;     for (int r = 0; r < 16; ++r) x[r] = B[fpad(base + 32 * r)];
;     dft16<false>(x);
;     B[fpad(base)] = x[0];
; #pragma unroll
;     for (int k = 1; k < 16; ++k) B[fpad(base + 32 * k)] = cmul(x[k], TW2[k * 32 + n2]);
; }
	v_pk_add_f32 v[178:179], v[126:127], v[130:131]
	v_pk_add_f32 v[176:177], v[126:127], v[130:131] neg_lo:[0,1] neg_hi:[0,1]
	v_pk_add_f32 v[124:125], v[174:175], v[178:179]
	v_pk_add_f32 v[128:129], v[174:175], v[178:179] neg_lo:[0,1] neg_hi:[0,1]
	v_pk_add_f32 v[126:127], v[168:169], v[176:177] op_sel:[0,1] op_sel_hi:[1,0] neg_hi:[0,1]
	v_pk_add_f32 v[130:131], v[168:169], v[176:177] op_sel:[0,1] op_sel_hi:[1,0] neg_lo:[0,1]
	v_pk_mul_f32 v[182:183], v[110:111], s[68:69] op_sel:[1,1] op_sel_hi:[0,1]
	v_pk_fma_f32 v[110:111], v[110:111], s[68:69], v[182:183] op_sel_hi:[1,0,1] neg_lo:[0,0,1]
	v_pk_mul_f32 v[180:181], v[118:119], s[84:85] op_sel:[1,1] op_sel_hi:[0,1]
	v_pk_fma_f32 v[118:119], v[118:119], s[84:85], v[180:181] op_sel_hi:[1,0,1] neg_lo:[0,0,1]
	v_pk_mul_f32 v[186:187], v[126:127], s[88:89] op_sel:[1,1] op_sel_hi:[0,1]
	v_pk_fma_f32 v[126:127], v[126:127], s[88:89], v[186:187] op_sel_hi:[1,0,1] neg_lo:[0,0,1]
	v_pk_mul_f32 v[184:185], v[112:113], s[84:85] op_sel:[1,1] op_sel_hi:[0,1]
	v_pk_fma_f32 v[112:113], v[112:113], s[84:85], v[184:185] op_sel_hi:[1,0,1] neg_lo:[0,0,1]
	v_pk_mul_f32 v[166:167], v[128:129], s[90:91] op_sel:[1,1] op_sel_hi:[0,1]
	v_pk_fma_f32 v[128:129], v[128:129], s[90:91], v[166:167] op_sel_hi:[1,0,1] neg_lo:[0,0,1]
	v_pk_mul_f32 v[188:189], v[114:115], s[88:89] op_sel:[1,1] op_sel_hi:[0,1]
	v_pk_fma_f32 v[114:115], v[114:115], s[88:89], v[188:189] op_sel_hi:[1,0,1] neg_lo:[0,0,1]
	v_pk_mul_f32 v[174:175], v[122:123], s[90:91] op_sel:[1,1] op_sel_hi:[0,1]
	v_pk_fma_f32 v[122:123], v[122:123], s[90:91], v[174:175] op_sel_hi:[1,0,1] neg_lo:[0,0,1]
	v_pk_mul_f32 v[168:169], v[130:131], s[98:99] op_sel:[1,1] op_sel_hi:[0,1]
	v_pk_fma_f32 v[130:131], v[130:131], s[98:99], v[168:169] op_sel_hi:[1,0,1] neg_lo:[0,0,1]
	v_pk_add_f32 v[178:179], v[100:101], v[116:117]
	v_pk_add_f32 v[176:177], v[100:101], v[116:117] neg_lo:[0,1] neg_hi:[0,1]
	v_pk_add_f32 v[182:183], v[108:109], v[124:125]
	v_pk_add_f32 v[180:181], v[108:109], v[124:125] neg_lo:[0,1] neg_hi:[0,1]
	v_pk_add_f32 v[100:101], v[178:179], v[182:183]
	v_pk_add_f32 v[116:117], v[178:179], v[182:183] neg_lo:[0,1] neg_hi:[0,1]
	v_pk_add_f32 v[108:109], v[176:177], v[180:181] op_sel:[0,1] op_sel_hi:[1,0] neg_hi:[0,1]
	v_pk_add_f32 v[124:125], v[176:177], v[180:181] op_sel:[0,1] op_sel_hi:[1,0] neg_lo:[0,1]
	v_pk_add_f32 v[186:187], v[102:103], v[118:119]
	v_pk_add_f32 v[184:185], v[102:103], v[118:119] neg_lo:[0,1] neg_hi:[0,1]
	v_pk_add_f32 v[166:167], v[110:111], v[126:127]
	v_pk_add_f32 v[188:189], v[110:111], v[126:127] neg_lo:[0,1] neg_hi:[0,1]
	v_pk_add_f32 v[102:103], v[186:187], v[166:167]
	v_pk_add_f32 v[118:119], v[186:187], v[166:167] neg_lo:[0,1] neg_hi:[0,1]
	v_pk_add_f32 v[110:111], v[184:185], v[188:189] op_sel:[0,1] op_sel_hi:[1,0] neg_hi:[0,1]
	v_pk_add_f32 v[126:127], v[184:185], v[188:189] op_sel:[0,1] op_sel_hi:[1,0] neg_lo:[0,1]
	v_pk_add_f32 v[174:175], v[104:105], v[120:121] op_sel:[0,1] op_sel_hi:[1,0] neg_hi:[0,1]
	v_pk_add_f32 v[168:169], v[104:105], v[120:121] op_sel:[0,1] op_sel_hi:[1,0] neg_lo:[0,1]
	v_pk_add_f32 v[178:179], v[112:113], v[128:129]
	v_pk_add_f32 v[176:177], v[112:113], v[128:129] neg_lo:[0,1] neg_hi:[0,1]
	v_pk_add_f32 v[104:105], v[174:175], v[178:179]
	v_pk_add_f32 v[120:121], v[174:175], v[178:179] neg_lo:[0,1] neg_hi:[0,1]
	v_pk_add_f32 v[112:113], v[168:169], v[176:177] op_sel:[0,1] op_sel_hi:[1,0] neg_hi:[0,1]
	v_pk_add_f32 v[128:129], v[168:169], v[176:177] op_sel:[0,1] op_sel_hi:[1,0] neg_lo:[0,1]
	v_pk_add_f32 v[182:183], v[106:107], v[122:123]
	v_pk_add_f32 v[180:181], v[106:107], v[122:123] neg_lo:[0,1] neg_hi:[0,1]
	v_pk_add_f32 v[186:187], v[114:115], v[130:131]
	v_pk_add_f32 v[184:185], v[114:115], v[130:131] neg_lo:[0,1] neg_hi:[0,1]
	v_pk_add_f32 v[106:107], v[182:183], v[186:187]
	v_pk_add_f32 v[122:123], v[182:183], v[186:187] neg_lo:[0,1] neg_hi:[0,1]
	v_pk_add_f32 v[114:115], v[180:181], v[184:185] op_sel:[0,1] op_sel_hi:[1,0] neg_hi:[0,1]
	v_pk_add_f32 v[130:131], v[180:181], v[184:185] op_sel:[0,1] op_sel_hi:[1,0] neg_lo:[0,1]
	ds_write_b64 v65, v[100:101]
	ds_read_b64 v[166:167], v56 offset:256
	ds_read_b64 v[188:189], v56 offset:512
	ds_read_b64 v[174:175], v56 offset:768
	ds_read_b64 v[168:169], v56 offset:1024
	s_waitcnt lgkmcnt(3)
	v_pk_mul_f32 v[178:179], v[102:103], v[166:167] op_sel:[1,1] op_sel_hi:[0,1]
	v_pk_fma_f32 v[102:103], v[102:103], v[166:167], v[178:179] op_sel_hi:[1,0,1] neg_lo:[0,0,1]
	ds_write_b64 v65, v[102:103] offset:264
	s_waitcnt lgkmcnt(3)
	v_pk_mul_f32 v[176:177], v[104:105], v[188:189] op_sel:[1,1] op_sel_hi:[0,1]
	v_pk_fma_f32 v[104:105], v[104:105], v[188:189], v[176:177] op_sel_hi:[1,0,1] neg_lo:[0,0,1]
	ds_write_b64 v65, v[104:105] offset:528
	s_waitcnt lgkmcnt(3)
	v_pk_mul_f32 v[182:183], v[106:107], v[174:175] op_sel:[1,1] op_sel_hi:[0,1]
	v_pk_fma_f32 v[106:107], v[106:107], v[174:175], v[182:183] op_sel_hi:[1,0,1] neg_lo:[0,0,1]
	ds_write_b64 v65, v[106:107] offset:792
	s_waitcnt lgkmcnt(3)
	v_pk_mul_f32 v[180:181], v[108:109], v[168:169] op_sel:[1,1] op_sel_hi:[0,1]
	v_pk_fma_f32 v[108:109], v[108:109], v[168:169], v[180:181] op_sel_hi:[1,0,1] neg_lo:[0,0,1]
	ds_write_b64 v65, v[108:109] offset:1056
	ds_read_b64 v[186:187], v56 offset:1280
	ds_read_b64 v[184:185], v56 offset:1536
	ds_read_b64 v[178:179], v56 offset:1792
	ds_read_b64 v[176:177], v56 offset:2048
	s_waitcnt lgkmcnt(3)
	v_pk_mul_f32 v[182:183], v[110:111], v[186:187] op_sel:[1,1] op_sel_hi:[0,1]
	v_pk_fma_f32 v[110:111], v[110:111], v[186:187], v[182:183] op_sel_hi:[1,0,1] neg_lo:[0,0,1]
	ds_write_b64 v65, v[110:111] offset:1320
	s_waitcnt lgkmcnt(3)
; #define LAS __attribute__((address_space(3)))
; __device__ __forceinline__ f32x2 cmul(f32x2 a, f32x2 b) { return (f32x2){a.x * b.x - a.y * b.y, a.x * b.y + a.y * b.x}; }
; __device__ __forceinline__ void fft_fwd2(LAS f32x2* B, const LAS f32x2* TW2, int tid) {
;     asm volatile("" : "+v"(tid));
;     const int b = tid >> 5, n2 = tid & 31, base = 512 * b + n2; f32x2 x[16];
; #pragma unroll
;     for (int r = 0; r < 16; ++r) x[r] = B[fpad(base + 32 * r)];
;     dft16<false>(x);
;     B[fpad(base)] = x[0];
; #pragma unroll
;     for (int k = 1; k < 16; ++k) B[fpad(base + 32 * k)] = cmul(x[k], TW2[k * 32 + n2]);
; }
; __device__ __forceinline__ void hy_sconv(const LAS float* plane, float w0, float w1, float w2, float cb, int n2, float (&u)[8][2]) {
;     asm volatile("" : "+v"(n2));
; #pragma unroll
;     for (int r = 0; r < 8; ++r)
; #pragma unroll
;         for (int b = 0; b < 2; ++b) { const int t = n2 + 512 * r, row = b * SEQ + t;
;             float a = cb + w1 * plane[row];
;             if (t > 0) a += w0 * plane[row - 1];
;             if (t < SEQ - 1) a += w2 * plane[row + 1];
;             u[r][b] = a; }
; }
	v_pk_mul_f32 v[180:181], v[112:113], v[184:185] op_sel:[1,1] op_sel_hi:[0,1]
	v_pk_fma_f32 v[112:113], v[112:113], v[184:185], v[180:181] op_sel_hi:[1,0,1] neg_lo:[0,0,1]
	ds_write_b64 v65, v[112:113] offset:1584
	s_waitcnt lgkmcnt(3)
	v_pk_mul_f32 v[166:167], v[114:115], v[178:179] op_sel:[1,1] op_sel_hi:[0,1]
	v_pk_fma_f32 v[114:115], v[114:115], v[178:179], v[166:167] op_sel_hi:[1,0,1] neg_lo:[0,0,1]
	ds_write_b64 v65, v[114:115] offset:1848
	s_waitcnt lgkmcnt(3)
	v_pk_mul_f32 v[188:189], v[116:117], v[176:177] op_sel:[1,1] op_sel_hi:[0,1]
	v_pk_fma_f32 v[116:117], v[116:117], v[176:177], v[188:189] op_sel_hi:[1,0,1] neg_lo:[0,0,1]
	ds_write_b64 v65, v[116:117] offset:2112
	ds_read_b64 v[174:175], v56 offset:2304
	ds_read_b64 v[168:169], v56 offset:2560
	ds_read_b64 v[182:183], v56 offset:2816
	ds_read_b64 v[180:181], v56 offset:3072
	s_waitcnt lgkmcnt(3)
	v_pk_mul_f32 v[166:167], v[118:119], v[174:175] op_sel:[1,1] op_sel_hi:[0,1]
	v_pk_fma_f32 v[118:119], v[118:119], v[174:175], v[166:167] op_sel_hi:[1,0,1] neg_lo:[0,0,1]
	ds_write_b64 v65, v[118:119] offset:2376
	s_waitcnt lgkmcnt(3)
	v_pk_mul_f32 v[188:189], v[120:121], v[168:169] op_sel:[1,1] op_sel_hi:[0,1]
	v_pk_fma_f32 v[120:121], v[120:121], v[168:169], v[188:189] op_sel_hi:[1,0,1] neg_lo:[0,0,1]
	ds_write_b64 v65, v[120:121] offset:2640
	s_waitcnt lgkmcnt(3)
	v_pk_mul_f32 v[186:187], v[122:123], v[182:183] op_sel:[1,1] op_sel_hi:[0,1]
	v_pk_fma_f32 v[122:123], v[122:123], v[182:183], v[186:187] op_sel_hi:[1,0,1] neg_lo:[0,0,1]
	ds_write_b64 v65, v[122:123] offset:2904
	s_waitcnt lgkmcnt(3)
	v_pk_mul_f32 v[184:185], v[124:125], v[180:181] op_sel:[1,1] op_sel_hi:[0,1]
	v_pk_fma_f32 v[124:125], v[124:125], v[180:181], v[184:185] op_sel_hi:[1,0,1] neg_lo:[0,0,1]
	ds_write_b64 v65, v[124:125] offset:3168
	ds_read_b64 v[178:179], v56 offset:3328
	ds_read_b64 v[176:177], v56 offset:3584
	ds_read_b64 v[166:167], v56 offset:3840
	s_waitcnt lgkmcnt(2)
	v_pk_mul_f32 v[188:189], v[126:127], v[178:179] op_sel:[1,1] op_sel_hi:[0,1]
	v_pk_fma_f32 v[126:127], v[126:127], v[178:179], v[188:189] op_sel_hi:[1,0,1] neg_lo:[0,0,1]
	ds_write_b64 v65, v[126:127] offset:3432
	s_waitcnt lgkmcnt(2)
	v_pk_mul_f32 v[186:187], v[128:129], v[176:177] op_sel:[1,1] op_sel_hi:[0,1]
	v_pk_fma_f32 v[128:129], v[128:129], v[176:177], v[186:187] op_sel_hi:[1,0,1] neg_lo:[0,0,1]
	ds_write_b64 v65, v[128:129] offset:3696
	s_waitcnt lgkmcnt(2)
	v_pk_mul_f32 v[184:185], v[130:131], v[166:167] op_sel:[1,1] op_sel_hi:[0,1]
	v_pk_fma_f32 v[130:131], v[130:131], v[166:167], v[184:185] op_sel_hi:[1,0,1] neg_lo:[0,0,1]
	ds_write_b64 v65, v[130:131] offset:3960
	s_waitcnt lgkmcnt(0)
	s_barrier
	v_mov_b32_e32 v174, s17
	v_mov_b32_e32 v175, s23
	v_mov_b32_e32 v168, s25
	v_mov_b32_e32 v169, s26
	ds_read_b32 v182, v208 offset:32768
	ds_read_b32 v180, v210 offset:32768
	ds_read_b32 v188, v208 offset:32772
	ds_read_b32 v183, v208 offset:49152
	ds_read_b32 v181, v210 offset:49152
	ds_read_b32 v189, v208 offset:49156
	ds_read_b32 v186, v208 offset:34816
	ds_read_b32 v184, v208 offset:34812
	ds_read_b32 v178, v208 offset:34820
	ds_read_b32 v187, v208 offset:51200
	ds_read_b32 v185, v208 offset:51196
	ds_read_b32 v179, v208 offset:51204
	s_waitcnt lgkmcnt(10)
	v_cndmask_b32_e64 v180, v180, 0, s[10:11]
	s_waitcnt lgkmcnt(7)
	v_cndmask_b32_e64 v181, v181, 0, s[10:11]
	v_pk_fma_f32 v[148:149], v[174:175], v[182:183], v[168:169] op_sel:[1,0,1]
	v_pk_fma_f32 v[148:149], v[174:175], v[180:181], v[148:149] op_sel_hi:[0,1,1]
	s_waitcnt lgkmcnt(6)
	v_pk_fma_f32 v[148:149], v[168:169], v[188:189], v[148:149] op_sel_hi:[0,1,1]
	s_waitcnt lgkmcnt(2)
	v_pk_fma_f32 v[150:151], v[174:175], v[186:187], v[168:169] op_sel:[1,0,1]
	s_waitcnt lgkmcnt(1)
	v_pk_fma_f32 v[150:151], v[174:175], v[184:185], v[150:151] op_sel_hi:[0,1,1]
	s_waitcnt lgkmcnt(0)
	v_pk_fma_f32 v[150:151], v[168:169], v[178:179], v[150:151] op_sel_hi:[0,1,1]
	ds_read_b32 v176, v208 offset:36864
	ds_read_b32 v166, v208 offset:36860
	ds_read_b32 v182, v208 offset:36868
	ds_read_b32 v177, v208 offset:53248
	ds_read_b32 v167, v208 offset:53244
	ds_read_b32 v183, v208 offset:53252
	ds_read_b32 v180, v208 offset:38912
	ds_read_b32 v188, v208 offset:38908
	ds_read_b32 v186, v208 offset:38916
	ds_read_b32 v181, v208 offset:55296
	ds_read_b32 v189, v208 offset:55292
	ds_read_b32 v187, v208 offset:55300
	s_waitcnt lgkmcnt(8)
	v_pk_fma_f32 v[152:153], v[174:175], v[176:177], v[168:169] op_sel:[1,0,1]
	s_waitcnt lgkmcnt(7)
	v_pk_fma_f32 v[152:153], v[174:175], v[166:167], v[152:153] op_sel_hi:[0,1,1]
	s_waitcnt lgkmcnt(6)
	v_pk_fma_f32 v[152:153], v[168:169], v[182:183], v[152:153] op_sel_hi:[0,1,1]
	s_waitcnt lgkmcnt(2)
	v_pk_fma_f32 v[154:155], v[174:175], v[180:181], v[168:169] op_sel:[1,0,1]
	s_waitcnt lgkmcnt(1)
	v_pk_fma_f32 v[154:155], v[174:175], v[188:189], v[154:155] op_sel_hi:[0,1,1]
	s_waitcnt lgkmcnt(0)
	v_pk_fma_f32 v[154:155], v[168:169], v[186:187], v[154:155] op_sel_hi:[0,1,1]
	ds_read_b32 v184, v208 offset:40960
	ds_read_b32 v178, v208 offset:40956
	ds_read_b32 v176, v208 offset:40964
	ds_read_b32 v185, v208 offset:57344
	ds_read_b32 v179, v208 offset:57340
	ds_read_b32 v177, v208 offset:57348
	ds_read_b32 v166, v208 offset:43008
	ds_read_b32 v182, v208 offset:43004
	ds_read_b32 v180, v208 offset:43012
	ds_read_b32 v167, v208 offset:59392
	ds_read_b32 v183, v208 offset:59388
	ds_read_b32 v181, v208 offset:59396
	s_waitcnt lgkmcnt(8)
	v_pk_fma_f32 v[158:159], v[174:175], v[184:185], v[168:169] op_sel:[1,0,1]
	s_waitcnt lgkmcnt(7)
	v_pk_fma_f32 v[158:159], v[174:175], v[178:179], v[158:159] op_sel_hi:[0,1,1]
	s_waitcnt lgkmcnt(6)
; #define LAS __attribute__((address_space(3)))
; __device__ __forceinline__ f32x2 cmul(f32x2 a, f32x2 b) { return (f32x2){a.x * b.x - a.y * b.y, a.x * b.y + a.y * b.x}; }
; template <int MODE> __device__ __forceinline__ void fft_pair32(LAS f32x2* B, const LAS f32x2* F, int wave, int lane) {
;     asm volatile("" : "+v"(lane));
;     constexpr float CS[16] = {1.f, 0.98078528040323043f, 0.92387953251128674f, 0.83146961230254524f, 0.70710678118654752f, 0.55557023301960218f, 0.38268343236508977f, 0.19509032201612825f,
;                               0.f, -0.19509032201612825f, -0.38268343236508977f, -0.55557023301960218f, -0.70710678118654752f, -0.83146961230254524f, -0.92387953251128674f, -0.98078528040323043f};
;     constexpr float SN[16] = {0.f, 0.19509032201612825f, 0.38268343236508977f, 0.55557023301960218f, 0.70710678118654752f, 0.83146961230254524f, 0.92387953251128674f, 0.98078528040323043f,
;                               1.f, 0.98078528040323043f, 0.92387953251128674f, 0.83146961230254524f, 0.70710678118654752f, 0.55557023301960218f, 0.38268343236508977f, 0.19509032201612825f};
;     const int hi = lane >> 5, blk = 32 * wave + (lane & 31); const float sg = hi ? -1.f : 1.f;
;     LAS f32x2* p = B + 33 * blk; f32x2 v[16];
; #pragma unroll
;     for (int j = 0; j < 16; ++j) { const f32x2 d = p[j] + p[j + 16] * sg;
;         const f32x2 w = {hi ? CS[j] : 1.f, hi ? -SN[j] : 0.f}; v[j] = j == 0 ? d : cmul(d, w); }
;     dft16<false>(v);
;     if (MODE == 2) {
; #pragma unroll
;         for (int k = 0; k < 16; ++k) p[2 * k + hi] = v[k];
;         return; }
	v_pk_fma_f32 v[158:159], v[168:169], v[176:177], v[158:159] op_sel_hi:[0,1,1]
	s_waitcnt lgkmcnt(2)
	v_pk_fma_f32 v[160:161], v[174:175], v[166:167], v[168:169] op_sel:[1,0,1]
	s_waitcnt lgkmcnt(1)
	v_pk_fma_f32 v[160:161], v[174:175], v[182:183], v[160:161] op_sel_hi:[0,1,1]
	s_waitcnt lgkmcnt(0)
	v_pk_fma_f32 v[160:161], v[168:169], v[180:181], v[160:161] op_sel_hi:[0,1,1]
	ds_read_b32 v188, v208 offset:45056
	ds_read_b32 v186, v208 offset:45052
	ds_read_b32 v184, v208 offset:45060
	ds_read_b32 v189, v208 offset:61440
	ds_read_b32 v187, v208 offset:61436
	ds_read_b32 v185, v208 offset:61444
	ds_read_b32 v178, v208 offset:47104
	ds_read_b32 v176, v208 offset:47100
	ds_read_b32 v166, v208 offset:47108
	ds_read_b32 v179, v208 offset:63488
	ds_read_b32 v177, v208 offset:63484
	ds_read_b32 v167, v208 offset:63492
	s_waitcnt lgkmcnt(8)
	v_pk_fma_f32 v[162:163], v[174:175], v[188:189], v[168:169] op_sel:[1,0,1]
	s_waitcnt lgkmcnt(7)
	v_pk_fma_f32 v[162:163], v[174:175], v[186:187], v[162:163] op_sel_hi:[0,1,1]
	s_waitcnt lgkmcnt(6)
	v_pk_fma_f32 v[162:163], v[168:169], v[184:185], v[162:163] op_sel_hi:[0,1,1]
	s_waitcnt lgkmcnt(3)
	v_cndmask_b32_e64 v166, v166, 0, s[28:29]
	s_waitcnt lgkmcnt(0)
	v_cndmask_b32_e64 v167, v167, 0, s[28:29]
	v_pk_fma_f32 v[164:165], v[174:175], v[178:179], v[168:169] op_sel:[1,0,1]
	v_pk_fma_f32 v[164:165], v[174:175], v[176:177], v[164:165] op_sel_hi:[0,1,1]
	v_pk_fma_f32 v[164:165], v[168:169], v[166:167], v[164:165] op_sel_hi:[0,1,1]
	s_load_dword s17, s[60:61], 0x1000
	s_load_dword s23, s[60:61], 0x4000
	s_load_dword s25, s[60:61], 0x7000
	s_load_dword s26, s[62:63], 0x1000
	v_add_u32_e32 v65, 0x10800, v156
	v_add_u32_e32 v69, 0x10800, v196
	ds_read_b64 v[100:101], v65
	ds_read_b64 v[182:183], v65 offset:128
	ds_read_b64 v[102:103], v65 offset:8
	ds_read_b64 v[180:181], v65 offset:136
	ds_read_b64 v[104:105], v65 offset:16
	ds_read_b64 v[188:189], v65 offset:144
	ds_read_b64 v[106:107], v65 offset:24
	ds_read_b64 v[186:187], v65 offset:152
	s_waitcnt lgkmcnt(0)
	v_pk_fma_f32 v[100:101], v[182:183], v[190:191], v[100:101] op_sel_hi:[1,0,1]
	v_pk_fma_f32 v[102:103], v[180:181], v[190:191], v[102:103] op_sel_hi:[1,0,1]
	v_pk_mul_f32 v[184:185], v[102:103], v[36:37] op_sel:[1,1] op_sel_hi:[0,1]
	v_pk_fma_f32 v[102:103], v[102:103], v[36:37], v[184:185] op_sel_hi:[1,0,1] neg_lo:[0,0,1]
	v_pk_fma_f32 v[104:105], v[188:189], v[190:191], v[104:105] op_sel_hi:[1,0,1]
	v_pk_mul_f32 v[178:179], v[104:105], v[38:39] op_sel:[1,1] op_sel_hi:[0,1]
	v_pk_fma_f32 v[104:105], v[104:105], v[38:39], v[178:179] op_sel_hi:[1,0,1] neg_lo:[0,0,1]
	v_pk_fma_f32 v[106:107], v[186:187], v[190:191], v[106:107] op_sel_hi:[1,0,1]
	v_pk_mul_f32 v[176:177], v[106:107], v[40:41] op_sel:[1,1] op_sel_hi:[0,1]
	v_pk_fma_f32 v[106:107], v[106:107], v[40:41], v[176:177] op_sel_hi:[1,0,1] neg_lo:[0,0,1]
	ds_read_b64 v[108:109], v65 offset:32
	ds_read_b64 v[166:167], v65 offset:160
	ds_read_b64 v[110:111], v65 offset:40
	ds_read_b64 v[174:175], v65 offset:168
	ds_read_b64 v[112:113], v65 offset:48
	ds_read_b64 v[168:169], v65 offset:176
	ds_read_b64 v[114:115], v65 offset:56
	ds_read_b64 v[184:185], v65 offset:184
	s_waitcnt lgkmcnt(6)
	v_pk_fma_f32 v[108:109], v[166:167], v[190:191], v[108:109] op_sel_hi:[1,0,1]
	v_pk_mul_f32 v[178:179], v[108:109], v[42:43] op_sel:[1,1] op_sel_hi:[0,1]
	v_pk_fma_f32 v[108:109], v[108:109], v[42:43], v[178:179] op_sel_hi:[1,0,1] neg_lo:[0,0,1]
	s_waitcnt lgkmcnt(4)
	v_pk_fma_f32 v[110:111], v[174:175], v[190:191], v[110:111] op_sel_hi:[1,0,1]
	v_pk_mul_f32 v[176:177], v[110:111], v[44:45] op_sel:[1,1] op_sel_hi:[0,1]
	v_pk_fma_f32 v[110:111], v[110:111], v[44:45], v[176:177] op_sel_hi:[1,0,1] neg_lo:[0,0,1]
	s_waitcnt lgkmcnt(2)
	v_pk_fma_f32 v[112:113], v[168:169], v[190:191], v[112:113] op_sel_hi:[1,0,1]
	v_pk_mul_f32 v[182:183], v[112:113], v[46:47] op_sel:[1,1] op_sel_hi:[0,1]
	v_pk_fma_f32 v[112:113], v[112:113], v[46:47], v[182:183] op_sel_hi:[1,0,1] neg_lo:[0,0,1]
	s_waitcnt lgkmcnt(0)
	v_pk_fma_f32 v[114:115], v[184:185], v[190:191], v[114:115] op_sel_hi:[1,0,1]
	v_pk_mul_f32 v[180:181], v[114:115], v[48:49] op_sel:[1,1] op_sel_hi:[0,1]
	v_pk_fma_f32 v[114:115], v[114:115], v[48:49], v[180:181] op_sel_hi:[1,0,1] neg_lo:[0,0,1]
	ds_read_b64 v[116:117], v65 offset:64
	ds_read_b64 v[188:189], v65 offset:192
	ds_read_b64 v[118:119], v65 offset:72
	ds_read_b64 v[186:187], v65 offset:200
	ds_read_b64 v[120:121], v65 offset:80
	ds_read_b64 v[178:179], v65 offset:208
	ds_read_b64 v[122:123], v65 offset:88
	ds_read_b64 v[176:177], v65 offset:216
	s_waitcnt lgkmcnt(6)
	v_pk_fma_f32 v[116:117], v[188:189], v[190:191], v[116:117] op_sel_hi:[1,0,1]
	v_pk_mul_f32 v[182:183], v[116:117], v[50:51] op_sel:[1,1] op_sel_hi:[0,1]
	v_pk_fma_f32 v[116:117], v[116:117], v[50:51], v[182:183] op_sel_hi:[1,0,1] neg_lo:[0,0,1]
	s_waitcnt lgkmcnt(4)
	v_pk_fma_f32 v[118:119], v[186:187], v[190:191], v[118:119] op_sel_hi:[1,0,1]
	v_pk_mul_f32 v[180:181], v[118:119], v[52:53] op_sel:[1,1] op_sel_hi:[0,1]
	v_pk_fma_f32 v[118:119], v[118:119], v[52:53], v[180:181] op_sel_hi:[1,0,1] neg_lo:[0,0,1]
	s_waitcnt lgkmcnt(2)
	v_pk_fma_f32 v[120:121], v[178:179], v[190:191], v[120:121] op_sel_hi:[1,0,1]
	v_pk_mul_f32 v[166:167], v[120:121], v[54:55] op_sel:[1,1] op_sel_hi:[0,1]
	v_pk_fma_f32 v[120:121], v[120:121], v[54:55], v[166:167] op_sel_hi:[1,0,1] neg_lo:[0,0,1]
	s_waitcnt lgkmcnt(0)
; #define LAS __attribute__((address_space(3)))
; template <bool INV> __device__ __forceinline__ void dft16(f32x2 (&x)[16]) {
;     constexpr float C1 = 0.92387953251128674f, S1 = 0.38268343236508977f, C2 = 0.70710678118654752f;
; #pragma unroll
;     for (int b = 0; b < 4; ++b) dft4<INV>(x[b], x[4 + b], x[8 + b], x[12 + b]);
;     const f32x2 w1 = {C1, -S1}, w2 = {C2, -C2}, w3 = {S1, -C1}, w4 = {0.f, -1.f}, w6 = {-C2, -C2}, w9 = {-C1, S1};
;     x[4 * 1 + 1] = cmul_tw<INV>(x[5], w1); x[4 * 1 + 2] = cmul_tw<INV>(x[6], w2); x[4 * 1 + 3] = cmul_tw<INV>(x[7], w3);
;     x[4 * 2 + 1] = cmul_tw<INV>(x[9], w2); x[4 * 2 + 2] = cmul_tw<INV>(x[10], w4); x[4 * 2 + 3] = cmul_tw<INV>(x[11], w6);
;     x[4 * 3 + 1] = cmul_tw<INV>(x[13], w3); x[4 * 3 + 2] = cmul_tw<INV>(x[14], w6); x[4 * 3 + 3] = cmul_tw<INV>(x[15], w9);
; #pragma unroll
;     for (int c = 0; c < 4; ++c) dft4<INV>(x[4 * c], x[4 * c + 1], x[4 * c + 2], x[4 * c + 3]);
;     f32x2 y[16];
; #pragma unroll
; template <int MODE> __device__ __forceinline__ void fft_pair32(LAS f32x2* B, const LAS f32x2* F, int wave, int lane) {
;     asm volatile("" : "+v"(lane));
;     constexpr float CS[16] = {1.f, 0.98078528040323043f, 0.92387953251128674f, 0.83146961230254524f, 0.70710678118654752f, 0.55557023301960218f, 0.38268343236508977f, 0.19509032201612825f,
;                               0.f, -0.19509032201612825f, -0.38268343236508977f, -0.55557023301960218f, -0.70710678118654752f, -0.83146961230254524f, -0.92387953251128674f, -0.98078528040323043f};
;     constexpr float SN[16] = {0.f, 0.19509032201612825f, 0.38268343236508977f, 0.55557023301960218f, 0.70710678118654752f, 0.83146961230254524f, 0.92387953251128674f, 0.98078528040323043f,
;                               1.f, 0.98078528040323043f, 0.92387953251128674f, 0.83146961230254524f, 0.70710678118654752f, 0.55557023301960218f, 0.38268343236508977f, 0.19509032201612825f};
;     const int hi = lane >> 5, blk = 32 * wave + (lane & 31); const float sg = hi ? -1.f : 1.f;
;     LAS f32x2* p = B + 33 * blk; f32x2 v[16];
; #pragma unroll
;     for (int j = 0; j < 16; ++j) { const f32x2 d = p[j] + p[j + 16] * sg;
;         const f32x2 w = {hi ? CS[j] : 1.f, hi ? -SN[j] : 0.f}; v[j] = j == 0 ? d : cmul(d, w); }
;     dft16<false>(v);
;     if (MODE == 2) {
; #pragma unroll
;         for (int k = 0; k < 16; ++k) p[2 * k + hi] = v[k];
;         return; }
	v_pk_fma_f32 v[122:123], v[176:177], v[190:191], v[122:123] op_sel_hi:[1,0,1]
	v_pk_mul_f32 v[174:175], v[122:123], v[90:91] op_sel:[1,1] op_sel_hi:[0,1]
	v_pk_fma_f32 v[122:123], v[122:123], v[90:91], v[174:175] op_sel_hi:[1,0,1] neg_lo:[0,0,1]
	ds_read_b64 v[124:125], v65 offset:96
	ds_read_b64 v[168:169], v65 offset:224
	ds_read_b64 v[126:127], v65 offset:104
	ds_read_b64 v[184:185], v65 offset:232
	ds_read_b64 v[128:129], v65 offset:112
	ds_read_b64 v[182:183], v65 offset:240
	ds_read_b64 v[130:131], v65 offset:120
	ds_read_b64 v[180:181], v65 offset:248
	s_waitcnt lgkmcnt(6)
	v_pk_fma_f32 v[124:125], v[168:169], v[190:191], v[124:125] op_sel_hi:[1,0,1]
	v_pk_mul_f32 v[166:167], v[124:125], v[92:93] op_sel:[1,1] op_sel_hi:[0,1]
	v_pk_fma_f32 v[124:125], v[124:125], v[92:93], v[166:167] op_sel_hi:[1,0,1] neg_lo:[0,0,1]
	s_waitcnt lgkmcnt(4)
	v_pk_fma_f32 v[126:127], v[184:185], v[190:191], v[126:127] op_sel_hi:[1,0,1]
	v_pk_mul_f32 v[174:175], v[126:127], v[94:95] op_sel:[1,1] op_sel_hi:[0,1]
	v_pk_fma_f32 v[126:127], v[126:127], v[94:95], v[174:175] op_sel_hi:[1,0,1] neg_lo:[0,0,1]
	s_waitcnt lgkmcnt(2)
	v_pk_fma_f32 v[128:129], v[182:183], v[190:191], v[128:129] op_sel_hi:[1,0,1]
	v_pk_mul_f32 v[188:189], v[128:129], v[96:97] op_sel:[1,1] op_sel_hi:[0,1]
	v_pk_fma_f32 v[128:129], v[128:129], v[96:97], v[188:189] op_sel_hi:[1,0,1] neg_lo:[0,0,1]
	s_waitcnt lgkmcnt(0)
	v_pk_fma_f32 v[130:131], v[180:181], v[190:191], v[130:131] op_sel_hi:[1,0,1]
	v_pk_mul_f32 v[186:187], v[130:131], v[98:99] op_sel:[1,1] op_sel_hi:[0,1]
	v_pk_fma_f32 v[130:131], v[130:131], v[98:99], v[186:187] op_sel_hi:[1,0,1] neg_lo:[0,0,1]
	v_pk_add_f32 v[178:179], v[100:101], v[116:117]
	v_pk_add_f32 v[176:177], v[100:101], v[116:117] neg_lo:[0,1] neg_hi:[0,1]
	v_pk_add_f32 v[166:167], v[108:109], v[124:125]
	v_pk_add_f32 v[174:175], v[108:109], v[124:125] neg_lo:[0,1] neg_hi:[0,1]
	v_pk_add_f32 v[100:101], v[178:179], v[166:167]
	v_pk_add_f32 v[116:117], v[178:179], v[166:167] neg_lo:[0,1] neg_hi:[0,1]
	v_pk_add_f32 v[108:109], v[176:177], v[174:175] op_sel:[0,1] op_sel_hi:[1,0] neg_hi:[0,1]
	v_pk_add_f32 v[124:125], v[176:177], v[174:175] op_sel:[0,1] op_sel_hi:[1,0] neg_lo:[0,1]
	v_pk_add_f32 v[188:189], v[102:103], v[118:119]
	v_pk_add_f32 v[186:187], v[102:103], v[118:119] neg_lo:[0,1] neg_hi:[0,1]
	v_pk_add_f32 v[168:169], v[110:111], v[126:127]
	v_pk_add_f32 v[184:185], v[110:111], v[126:127] neg_lo:[0,1] neg_hi:[0,1]
	v_pk_add_f32 v[102:103], v[188:189], v[168:169]
	v_pk_add_f32 v[118:119], v[188:189], v[168:169] neg_lo:[0,1] neg_hi:[0,1]
	v_pk_add_f32 v[110:111], v[186:187], v[184:185] op_sel:[0,1] op_sel_hi:[1,0] neg_hi:[0,1]
	v_pk_add_f32 v[126:127], v[186:187], v[184:185] op_sel:[0,1] op_sel_hi:[1,0] neg_lo:[0,1]
	v_pk_add_f32 v[182:183], v[104:105], v[120:121]
	v_pk_add_f32 v[180:181], v[104:105], v[120:121] neg_lo:[0,1] neg_hi:[0,1]
	v_pk_add_f32 v[178:179], v[112:113], v[128:129]
	v_pk_add_f32 v[176:177], v[112:113], v[128:129] neg_lo:[0,1] neg_hi:[0,1]
	v_pk_add_f32 v[104:105], v[182:183], v[178:179]
	v_pk_add_f32 v[120:121], v[182:183], v[178:179] neg_lo:[0,1] neg_hi:[0,1]
	v_pk_add_f32 v[112:113], v[180:181], v[176:177] op_sel:[0,1] op_sel_hi:[1,0] neg_hi:[0,1]
	v_pk_add_f32 v[128:129], v[180:181], v[176:177] op_sel:[0,1] op_sel_hi:[1,0] neg_lo:[0,1]
	v_pk_add_f32 v[166:167], v[106:107], v[122:123]
	v_pk_add_f32 v[174:175], v[106:107], v[122:123] neg_lo:[0,1] neg_hi:[0,1]
	v_pk_add_f32 v[188:189], v[114:115], v[130:131]
	v_pk_add_f32 v[186:187], v[114:115], v[130:131] neg_lo:[0,1] neg_hi:[0,1]
	v_pk_add_f32 v[106:107], v[166:167], v[188:189]
	v_pk_add_f32 v[122:123], v[166:167], v[188:189] neg_lo:[0,1] neg_hi:[0,1]
	v_pk_add_f32 v[114:115], v[174:175], v[186:187] op_sel:[0,1] op_sel_hi:[1,0] neg_hi:[0,1]
	v_pk_add_f32 v[130:131], v[174:175], v[186:187] op_sel:[0,1] op_sel_hi:[1,0] neg_lo:[0,1]
	v_pk_mul_f32 v[168:169], v[110:111], s[68:69] op_sel:[1,1] op_sel_hi:[0,1]
	v_pk_fma_f32 v[110:111], v[110:111], s[68:69], v[168:169] op_sel_hi:[1,0,1] neg_lo:[0,0,1]
	v_pk_mul_f32 v[184:185], v[112:113], s[84:85] op_sel:[1,1] op_sel_hi:[0,1]
	v_pk_fma_f32 v[112:113], v[112:113], s[84:85], v[184:185] op_sel_hi:[1,0,1] neg_lo:[0,0,1]
	v_pk_mul_f32 v[182:183], v[114:115], s[88:89] op_sel:[1,1] op_sel_hi:[0,1]
	v_pk_fma_f32 v[114:115], v[114:115], s[88:89], v[182:183] op_sel_hi:[1,0,1] neg_lo:[0,0,1]
	v_pk_mul_f32 v[180:181], v[118:119], s[84:85] op_sel:[1,1] op_sel_hi:[0,1]
	v_pk_fma_f32 v[118:119], v[118:119], s[84:85], v[180:181] op_sel_hi:[1,0,1] neg_lo:[0,0,1]
	v_pk_mul_f32 v[178:179], v[122:123], s[90:91] op_sel:[1,1] op_sel_hi:[0,1]
	v_pk_fma_f32 v[122:123], v[122:123], s[90:91], v[178:179] op_sel_hi:[1,0,1] neg_lo:[0,0,1]
	v_pk_mul_f32 v[176:177], v[126:127], s[88:89] op_sel:[1,1] op_sel_hi:[0,1]
	v_pk_fma_f32 v[126:127], v[126:127], s[88:89], v[176:177] op_sel_hi:[1,0,1] neg_lo:[0,0,1]
	v_pk_mul_f32 v[166:167], v[128:129], s[90:91] op_sel:[1,1] op_sel_hi:[0,1]
	v_pk_fma_f32 v[128:129], v[128:129], s[90:91], v[166:167] op_sel_hi:[1,0,1] neg_lo:[0,0,1]
	v_pk_mul_f32 v[174:175], v[130:131], s[98:99] op_sel:[1,1] op_sel_hi:[0,1]
	v_pk_fma_f32 v[130:131], v[130:131], s[98:99], v[174:175] op_sel_hi:[1,0,1] neg_lo:[0,0,1]
	v_pk_add_f32 v[188:189], v[100:101], v[104:105]
	v_pk_add_f32 v[186:187], v[100:101], v[104:105] neg_lo:[0,1] neg_hi:[0,1]
	v_pk_add_f32 v[168:169], v[102:103], v[106:107]
	v_pk_add_f32 v[184:185], v[102:103], v[106:107] neg_lo:[0,1] neg_hi:[0,1]
	v_pk_add_f32 v[100:101], v[188:189], v[168:169]
	v_pk_add_f32 v[104:105], v[188:189], v[168:169] neg_lo:[0,1] neg_hi:[0,1]
	v_pk_add_f32 v[102:103], v[186:187], v[184:185] op_sel:[0,1] op_sel_hi:[1,0] neg_hi:[0,1]
; __device__ __forceinline__ f32x2 cmul(f32x2 a, f32x2 b) { return (f32x2){a.x * b.x - a.y * b.y, a.x * b.y + a.y * b.x}; }
; __device__ __forceinline__ void dft16_fwd_lo(f32x2 (&x)[16]) {
;     constexpr float C1 = 0.92387953251128674f, S1 = 0.38268343236508977f, C2 = 0.70710678118654752f;
; #pragma unroll
;     for (int b = 0; b < 4; ++b) { const f32x2 x0 = x[b], x1 = x[4 + b]; const f32x2 j1 = {x1.y, -x1.x};
;         x[b] = x0 + x1; x[4 + b] = x0 + j1; x[8 + b] = x0 - x1; x[12 + b] = x0 - j1; }
;     const f32x2 w1 = {C1, -S1}, w2 = {C2, -C2}, w3 = {S1, -C1}, w4 = {0.f, -1.f}, w6 = {-C2, -C2}, w9 = {-C1, S1};
;     x[5] = cmul(x[5], w1); x[6] = cmul(x[6], w2); x[7] = cmul(x[7], w3);
;     x[9] = cmul(x[9], w2); x[10] = cmul(x[10], w4); x[11] = cmul(x[11], w6);
;     x[13] = cmul(x[13], w3); x[14] = cmul(x[14], w6); x[15] = cmul(x[15], w9);
; #pragma unroll
;     for (int c = 0; c < 4; ++c) dft4<false>(x[4 * c], x[4 * c + 1], x[4 * c + 2], x[4 * c + 3]);
;     f32x2 y[16];
; #pragma unroll
;     for (int k = 0; k < 16; ++k) y[k] = x[4 * (k & 3) + (k >> 2)];
; #pragma unroll
;     for (int k = 0; k < 16; ++k) x[k] = y[k];
; }
; template <int MODE> __device__ __forceinline__ void fft_pair32(LAS f32x2* B, const LAS f32x2* F, int wave, int lane) {
;     ...
;     if (MODE == 2) {
; #pragma unroll
;         for (int k = 0; k < 16; ++k) p[2 * k + hi] = v[k];
;         return; }
	v_pk_add_f32 v[106:107], v[186:187], v[184:185] op_sel:[0,1] op_sel_hi:[1,0] neg_lo:[0,1]
	v_pk_add_f32 v[182:183], v[108:109], v[112:113]
	v_pk_add_f32 v[180:181], v[108:109], v[112:113] neg_lo:[0,1] neg_hi:[0,1]
	v_pk_add_f32 v[178:179], v[110:111], v[114:115]
	v_pk_add_f32 v[176:177], v[110:111], v[114:115] neg_lo:[0,1] neg_hi:[0,1]
	v_pk_add_f32 v[108:109], v[182:183], v[178:179]
	v_pk_add_f32 v[112:113], v[182:183], v[178:179] neg_lo:[0,1] neg_hi:[0,1]
	v_pk_add_f32 v[110:111], v[180:181], v[176:177] op_sel:[0,1] op_sel_hi:[1,0] neg_hi:[0,1]
	v_pk_add_f32 v[114:115], v[180:181], v[176:177] op_sel:[0,1] op_sel_hi:[1,0] neg_lo:[0,1]
	v_pk_add_f32 v[166:167], v[116:117], v[120:121] op_sel:[0,1] op_sel_hi:[1,0] neg_hi:[0,1]
	v_pk_add_f32 v[174:175], v[116:117], v[120:121] op_sel:[0,1] op_sel_hi:[1,0] neg_lo:[0,1]
	v_pk_add_f32 v[188:189], v[118:119], v[122:123]
	v_pk_add_f32 v[186:187], v[118:119], v[122:123] neg_lo:[0,1] neg_hi:[0,1]
	v_pk_add_f32 v[116:117], v[166:167], v[188:189]
	v_pk_add_f32 v[120:121], v[166:167], v[188:189] neg_lo:[0,1] neg_hi:[0,1]
	v_pk_add_f32 v[118:119], v[174:175], v[186:187] op_sel:[0,1] op_sel_hi:[1,0] neg_hi:[0,1]
	v_pk_add_f32 v[122:123], v[174:175], v[186:187] op_sel:[0,1] op_sel_hi:[1,0] neg_lo:[0,1]
	v_pk_add_f32 v[168:169], v[124:125], v[128:129]
	v_pk_add_f32 v[184:185], v[124:125], v[128:129] neg_lo:[0,1] neg_hi:[0,1]
	v_pk_add_f32 v[182:183], v[126:127], v[130:131]
	v_pk_add_f32 v[180:181], v[126:127], v[130:131] neg_lo:[0,1] neg_hi:[0,1]
	v_pk_add_f32 v[124:125], v[168:169], v[182:183]
	v_pk_add_f32 v[128:129], v[168:169], v[182:183] neg_lo:[0,1] neg_hi:[0,1]
	v_pk_add_f32 v[126:127], v[184:185], v[180:181] op_sel:[0,1] op_sel_hi:[1,0] neg_hi:[0,1]
	v_pk_add_f32 v[130:131], v[184:185], v[180:181] op_sel:[0,1] op_sel_hi:[1,0] neg_lo:[0,1]
	v_pk_mul_f32 v[100:101], v[100:101], v[192:193] op_sel_hi:[1,0]
	ds_write_b64 v69, v[100:101]
	v_pk_mul_f32 v[108:109], v[108:109], v[192:193] op_sel_hi:[1,0]
	ds_write_b64 v69, v[108:109] offset:16
	v_pk_mul_f32 v[116:117], v[116:117], v[192:193] op_sel_hi:[1,0]
	ds_write_b64 v69, v[116:117] offset:32
	v_pk_mul_f32 v[124:125], v[124:125], v[192:193] op_sel_hi:[1,0]
	ds_write_b64 v69, v[124:125] offset:48
	v_pk_mul_f32 v[102:103], v[102:103], v[192:193] op_sel_hi:[1,0]
	ds_write_b64 v69, v[102:103] offset:64
	v_pk_mul_f32 v[110:111], v[110:111], v[192:193] op_sel_hi:[1,0]
	ds_write_b64 v69, v[110:111] offset:80
	v_pk_mul_f32 v[118:119], v[118:119], v[192:193] op_sel_hi:[1,0]
	ds_write_b64 v69, v[118:119] offset:96
	v_pk_mul_f32 v[126:127], v[126:127], v[192:193] op_sel_hi:[1,0]
	ds_write_b64 v69, v[126:127] offset:112
	v_pk_mul_f32 v[104:105], v[104:105], v[192:193] op_sel_hi:[1,0]
	ds_write_b64 v69, v[104:105] offset:128
	v_pk_mul_f32 v[112:113], v[112:113], v[192:193] op_sel_hi:[1,0]
	ds_write_b64 v69, v[112:113] offset:144
	v_pk_mul_f32 v[120:121], v[120:121], v[192:193] op_sel_hi:[1,0]
	ds_write_b64 v69, v[120:121] offset:160
	v_pk_mul_f32 v[128:129], v[128:129], v[192:193] op_sel_hi:[1,0]
	ds_write_b64 v69, v[128:129] offset:176
	v_pk_mul_f32 v[106:107], v[106:107], v[192:193] op_sel_hi:[1,0]
	ds_write_b64 v69, v[106:107] offset:192
	v_pk_mul_f32 v[114:115], v[114:115], v[192:193] op_sel_hi:[1,0]
	ds_write_b64 v69, v[114:115] offset:208
	v_pk_mul_f32 v[122:123], v[122:123], v[192:193] op_sel_hi:[1,0]
	ds_write_b64 v69, v[122:123] offset:224
	v_pk_mul_f32 v[130:131], v[130:131], v[192:193] op_sel_hi:[1,0]
	ds_write_b64 v69, v[130:131] offset:240
	s_waitcnt lgkmcnt(0)
	s_barrier
	v_pk_add_f32 v[104:105], v[132:133], v[140:141] neg_lo:[0,1] neg_hi:[0,1]
	v_pk_add_f32 v[106:107], v[132:133], v[140:141] op_sel:[0,1] op_sel_hi:[1,0] neg_lo:[0,1]
	v_pk_add_f32 v[178:179], v[132:133], v[140:141] op_sel:[0,1] op_sel_hi:[1,0] neg_hi:[0,1]
	v_pk_add_f32 v[100:101], v[132:133], v[140:141]
	v_pk_add_f32 v[112:113], v[134:135], v[142:143] neg_lo:[0,1] neg_hi:[0,1]
	v_pk_add_f32 v[114:115], v[134:135], v[142:143] op_sel:[0,1] op_sel_hi:[1,0] neg_lo:[0,1]
	v_pk_add_f32 v[176:177], v[134:135], v[142:143] op_sel:[0,1] op_sel_hi:[1,0] neg_hi:[0,1]
	v_pk_add_f32 v[108:109], v[134:135], v[142:143]
	v_pk_add_f32 v[120:121], v[136:137], v[144:145] neg_lo:[0,1] neg_hi:[0,1]
	v_pk_add_f32 v[122:123], v[136:137], v[144:145] op_sel:[0,1] op_sel_hi:[1,0] neg_lo:[0,1]
	v_pk_add_f32 v[166:167], v[136:137], v[144:145] op_sel:[0,1] op_sel_hi:[1,0] neg_hi:[0,1]
	v_pk_add_f32 v[116:117], v[136:137], v[144:145]
	v_pk_add_f32 v[128:129], v[138:139], v[146:147] neg_lo:[0,1] neg_hi:[0,1]
	v_pk_add_f32 v[130:131], v[138:139], v[146:147] op_sel:[0,1] op_sel_hi:[1,0] neg_lo:[0,1]
	v_pk_add_f32 v[174:175], v[138:139], v[146:147] op_sel:[0,1] op_sel_hi:[1,0] neg_hi:[0,1]
	v_pk_add_f32 v[124:125], v[138:139], v[146:147]
	v_pk_mul_f32 v[188:189], v[176:177], s[68:69] op_sel:[1,1] op_sel_hi:[0,1]
	v_pk_fma_f32 v[176:177], v[176:177], s[68:69], v[188:189] op_sel_hi:[1,0,1] neg_lo:[0,0,1]
	v_pk_mul_f32 v[186:187], v[166:167], s[84:85] op_sel:[1,1] op_sel_hi:[0,1]
	v_pk_fma_f32 v[166:167], v[166:167], s[84:85], v[186:187] op_sel_hi:[1,0,1] neg_lo:[0,0,1]
	v_pk_mul_f32 v[168:169], v[174:175], s[88:89] op_sel:[1,1] op_sel_hi:[0,1]
	v_pk_fma_f32 v[174:175], v[174:175], s[88:89], v[168:169] op_sel_hi:[1,0,1] neg_lo:[0,0,1]
	v_pk_mul_f32 v[184:185], v[112:113], s[84:85] op_sel:[1,1] op_sel_hi:[0,1]
	v_pk_fma_f32 v[112:113], v[112:113], s[84:85], v[184:185] op_sel_hi:[1,0,1] neg_lo:[0,0,1]
	v_pk_mul_f32 v[182:183], v[128:129], s[90:91] op_sel:[1,1] op_sel_hi:[0,1]
	v_pk_fma_f32 v[128:129], v[128:129], s[90:91], v[182:183] op_sel_hi:[1,0,1] neg_lo:[0,0,1]
	v_pk_mul_f32 v[180:181], v[114:115], s[88:89] op_sel:[1,1] op_sel_hi:[0,1]
; #define LAS __attribute__((address_space(3)))
; __device__ __forceinline__ f32x2 cmul(f32x2 a, f32x2 b) { return (f32x2){a.x * b.x - a.y * b.y, a.x * b.y + a.y * b.x}; }
; __device__ __forceinline__ void dft16_fwd_lo(f32x2 (&x)[16]) {
;     constexpr float C1 = 0.92387953251128674f, S1 = 0.38268343236508977f, C2 = 0.70710678118654752f;
; #pragma unroll
;     for (int b = 0; b < 4; ++b) { const f32x2 x0 = x[b], x1 = x[4 + b]; const f32x2 j1 = {x1.y, -x1.x};
;         x[b] = x0 + x1; x[4 + b] = x0 + j1; x[8 + b] = x0 - x1; x[12 + b] = x0 - j1; }
;     const f32x2 w1 = {C1, -S1}, w2 = {C2, -C2}, w3 = {S1, -C1}, w4 = {0.f, -1.f}, w6 = {-C2, -C2}, w9 = {-C1, S1};
;     x[5] = cmul(x[5], w1); x[6] = cmul(x[6], w2); x[7] = cmul(x[7], w3);
;     x[9] = cmul(x[9], w2); x[10] = cmul(x[10], w4); x[11] = cmul(x[11], w6);
;     x[13] = cmul(x[13], w3); x[14] = cmul(x[14], w6); x[15] = cmul(x[15], w9);
; #pragma unroll
;     for (int c = 0; c < 4; ++c) dft4<false>(x[4 * c], x[4 * c + 1], x[4 * c + 2], x[4 * c + 3]);
;     f32x2 y[16];
; #pragma unroll
;     for (int k = 0; k < 16; ++k) y[k] = x[4 * (k & 3) + (k >> 2)];
; #pragma unroll
;     for (int k = 0; k < 16; ++k) x[k] = y[k];
; }
; template <bool LO> __device__ __forceinline__ void fft_fwd1(f32x2 (&x)[16], LAS f32x2* B, int n2, const f32x2 (&w)[16]) {
;     asm volatile("" : "+v"(n2));
;     if (LO) dft16_fwd_lo(x); else dft16<false>(x);
;     B[fpad(n2)] = x[0];
; #pragma unroll
;     for (int k = 1; k < 16; ++k) B[fpad(512 * k + n2)] = cmul(x[k], w[k]);
; }
	v_pk_fma_f32 v[114:115], v[114:115], s[88:89], v[180:181] op_sel_hi:[1,0,1] neg_lo:[0,0,1]
	v_pk_mul_f32 v[102:103], v[122:123], s[90:91] op_sel:[1,1] op_sel_hi:[0,1]
	v_pk_fma_f32 v[122:123], v[122:123], s[90:91], v[102:103] op_sel_hi:[1,0,1] neg_lo:[0,0,1]
	v_pk_mul_f32 v[110:111], v[130:131], s[98:99] op_sel:[1,1] op_sel_hi:[0,1]
	v_pk_fma_f32 v[130:131], v[130:131], s[98:99], v[110:111] op_sel_hi:[1,0,1] neg_lo:[0,0,1]
	v_pk_add_f32 v[118:119], v[100:101], v[116:117]
	v_pk_add_f32 v[126:127], v[100:101], v[116:117] neg_lo:[0,1] neg_hi:[0,1]
	v_pk_add_f32 v[188:189], v[108:109], v[124:125]
	v_pk_add_f32 v[186:187], v[108:109], v[124:125] neg_lo:[0,1] neg_hi:[0,1]
	v_pk_add_f32 v[100:101], v[118:119], v[188:189]
	v_pk_add_f32 v[116:117], v[118:119], v[188:189] neg_lo:[0,1] neg_hi:[0,1]
	v_pk_add_f32 v[108:109], v[126:127], v[186:187] op_sel:[0,1] op_sel_hi:[1,0] neg_hi:[0,1]
	v_pk_add_f32 v[124:125], v[126:127], v[186:187] op_sel:[0,1] op_sel_hi:[1,0] neg_lo:[0,1]
	v_pk_add_f32 v[168:169], v[178:179], v[166:167]
	v_pk_add_f32 v[184:185], v[178:179], v[166:167] neg_lo:[0,1] neg_hi:[0,1]
	v_pk_add_f32 v[182:183], v[176:177], v[174:175]
	v_pk_add_f32 v[180:181], v[176:177], v[174:175] neg_lo:[0,1] neg_hi:[0,1]
	v_pk_add_f32 v[178:179], v[168:169], v[182:183]
	v_pk_add_f32 v[166:167], v[168:169], v[182:183] neg_lo:[0,1] neg_hi:[0,1]
	v_pk_add_f32 v[176:177], v[184:185], v[180:181] op_sel:[0,1] op_sel_hi:[1,0] neg_hi:[0,1]
	v_pk_add_f32 v[174:175], v[184:185], v[180:181] op_sel:[0,1] op_sel_hi:[1,0] neg_lo:[0,1]
	v_pk_add_f32 v[102:103], v[104:105], v[120:121] op_sel:[0,1] op_sel_hi:[1,0] neg_hi:[0,1]
	v_pk_add_f32 v[110:111], v[104:105], v[120:121] op_sel:[0,1] op_sel_hi:[1,0] neg_lo:[0,1]
	v_pk_add_f32 v[118:119], v[112:113], v[128:129]
	v_pk_add_f32 v[126:127], v[112:113], v[128:129] neg_lo:[0,1] neg_hi:[0,1]
	v_pk_add_f32 v[104:105], v[102:103], v[118:119]
	v_pk_add_f32 v[120:121], v[102:103], v[118:119] neg_lo:[0,1] neg_hi:[0,1]
	v_pk_add_f32 v[112:113], v[110:111], v[126:127] op_sel:[0,1] op_sel_hi:[1,0] neg_hi:[0,1]
	v_pk_add_f32 v[128:129], v[110:111], v[126:127] op_sel:[0,1] op_sel_hi:[1,0] neg_lo:[0,1]
	v_pk_add_f32 v[188:189], v[106:107], v[122:123]
	v_pk_add_f32 v[186:187], v[106:107], v[122:123] neg_lo:[0,1] neg_hi:[0,1]
	v_pk_add_f32 v[168:169], v[114:115], v[130:131]
	v_pk_add_f32 v[184:185], v[114:115], v[130:131] neg_lo:[0,1] neg_hi:[0,1]
	v_pk_add_f32 v[106:107], v[188:189], v[168:169]
	v_pk_add_f32 v[122:123], v[188:189], v[168:169] neg_lo:[0,1] neg_hi:[0,1]
	v_pk_add_f32 v[114:115], v[186:187], v[184:185] op_sel:[0,1] op_sel_hi:[1,0] neg_hi:[0,1]
	v_pk_add_f32 v[130:131], v[186:187], v[184:185] op_sel:[0,1] op_sel_hi:[1,0] neg_lo:[0,1]
	ds_write_b64 v3, v[100:101]
	v_pk_mul_f32 v[180:181], v[178:179], v[6:7] op_sel:[1,1] op_sel_hi:[0,1]
	v_pk_fma_f32 v[182:183], v[178:179], v[6:7], v[180:181] op_sel_hi:[1,0,1] neg_lo:[0,0,1]
	ds_write_b64 v3, v[182:183] offset:4224
	v_pk_mul_f32 v[110:111], v[104:105], v[8:9] op_sel:[1,1] op_sel_hi:[0,1]
	v_pk_fma_f32 v[102:103], v[104:105], v[8:9], v[110:111] op_sel_hi:[1,0,1] neg_lo:[0,0,1]
	ds_write_b64 v3, v[102:103] offset:8448
	v_pk_mul_f32 v[126:127], v[106:107], v[10:11] op_sel:[1,1] op_sel_hi:[0,1]
	v_pk_fma_f32 v[118:119], v[106:107], v[10:11], v[126:127] op_sel_hi:[1,0,1] neg_lo:[0,0,1]
	ds_write_b64 v3, v[118:119] offset:12672
	v_pk_mul_f32 v[186:187], v[108:109], v[12:13] op_sel:[1,1] op_sel_hi:[0,1]
	v_pk_fma_f32 v[188:189], v[108:109], v[12:13], v[186:187] op_sel_hi:[1,0,1] neg_lo:[0,0,1]
	ds_write_b64 v3, v[188:189] offset:16896
	v_pk_mul_f32 v[184:185], v[176:177], v[14:15] op_sel:[1,1] op_sel_hi:[0,1]
	v_pk_fma_f32 v[168:169], v[176:177], v[14:15], v[184:185] op_sel_hi:[1,0,1] neg_lo:[0,0,1]
	ds_write_b64 v3, v[168:169] offset:21120
	v_pk_mul_f32 v[182:183], v[112:113], v[16:17] op_sel:[1,1] op_sel_hi:[0,1]
	v_pk_fma_f32 v[180:181], v[112:113], v[16:17], v[182:183] op_sel_hi:[1,0,1] neg_lo:[0,0,1]
	ds_write_b64 v3, v[180:181] offset:25344
	v_pk_mul_f32 v[102:103], v[114:115], v[18:19] op_sel:[1,1] op_sel_hi:[0,1]
	v_pk_fma_f32 v[110:111], v[114:115], v[18:19], v[102:103] op_sel_hi:[1,0,1] neg_lo:[0,0,1]
	ds_write_b64 v3, v[110:111] offset:29568
	v_pk_mul_f32 v[118:119], v[116:117], v[20:21] op_sel:[1,1] op_sel_hi:[0,1]
	v_pk_fma_f32 v[126:127], v[116:117], v[20:21], v[118:119] op_sel_hi:[1,0,1] neg_lo:[0,0,1]
	ds_write_b64 v3, v[126:127] offset:33792
	v_pk_mul_f32 v[188:189], v[166:167], v[22:23] op_sel:[1,1] op_sel_hi:[0,1]
	v_pk_fma_f32 v[186:187], v[166:167], v[22:23], v[188:189] op_sel_hi:[1,0,1] neg_lo:[0,0,1]
	ds_write_b64 v3, v[186:187] offset:38016
	v_pk_mul_f32 v[168:169], v[120:121], v[24:25] op_sel:[1,1] op_sel_hi:[0,1]
	v_pk_fma_f32 v[184:185], v[120:121], v[24:25], v[168:169] op_sel_hi:[1,0,1] neg_lo:[0,0,1]
	ds_write_b64 v3, v[184:185] offset:42240
	v_pk_mul_f32 v[180:181], v[122:123], v[26:27] op_sel:[1,1] op_sel_hi:[0,1]
	v_pk_fma_f32 v[182:183], v[122:123], v[26:27], v[180:181] op_sel_hi:[1,0,1] neg_lo:[0,0,1]
	ds_write_b64 v3, v[182:183] offset:46464
	v_pk_mul_f32 v[110:111], v[124:125], v[28:29] op_sel:[1,1] op_sel_hi:[0,1]
	v_pk_fma_f32 v[102:103], v[124:125], v[28:29], v[110:111] op_sel_hi:[1,0,1] neg_lo:[0,0,1]
	ds_write_b64 v3, v[102:103] offset:50688
	v_pk_mul_f32 v[126:127], v[174:175], v[30:31] op_sel:[1,1] op_sel_hi:[0,1]
	v_pk_fma_f32 v[118:119], v[174:175], v[30:31], v[126:127] op_sel_hi:[1,0,1] neg_lo:[0,0,1]
	ds_write_b64 v3, v[118:119] offset:54912
	v_pk_mul_f32 v[186:187], v[128:129], v[32:33] op_sel:[1,1] op_sel_hi:[0,1]
	v_pk_fma_f32 v[188:189], v[128:129], v[32:33], v[186:187] op_sel_hi:[1,0,1] neg_lo:[0,0,1]
	ds_write_b64 v3, v[188:189] offset:59136
	v_pk_mul_f32 v[184:185], v[130:131], v[34:35] op_sel:[1,1] op_sel_hi:[0,1]
	v_pk_fma_f32 v[168:169], v[130:131], v[34:35], v[184:185] op_sel_hi:[1,0,1] neg_lo:[0,0,1]
	ds_write_b64 v3, v[168:169] offset:63360
	s_waitcnt lgkmcnt(0)
	s_barrier
	s_cbranch_vccz .Lhfft_st5
	s_sleep 6
; #define LAS __attribute__((address_space(3)))
; __device__ __forceinline__ f32x2 cmul(f32x2 a, f32x2 b) { return (f32x2){a.x * b.x - a.y * b.y, a.x * b.y + a.y * b.x}; }
; __device__ __forceinline__ void fft_fwd2(LAS f32x2* B, const LAS f32x2* TW2, int tid) {
;     asm volatile("" : "+v"(tid));
;     const int b = tid >> 5, n2 = tid & 31, base = 512 * b + n2; f32x2 x[16];
; #pragma unroll
;     for (int r = 0; r < 16; ++r) x[r] = B[fpad(base + 32 * r)];
;     dft16<false>(x);
;     B[fpad(base)] = x[0];
; #pragma unroll
;     for (int k = 1; k < 16; ++k) B[fpad(base + 32 * k)] = cmul(x[k], TW2[k * 32 + n2]);
; }
.Lhfft_st5:
	ds_read_b64 v[100:101], v5
	ds_read_b64 v[108:109], v5 offset:1056
	ds_read_b64 v[116:117], v5 offset:2112
	ds_read_b64 v[124:125], v5 offset:3168
	ds_read_b64 v[178:179], v5 offset:264
	ds_read_b64 v[176:177], v5 offset:1320
	ds_read_b64 v[166:167], v5 offset:2376
	ds_read_b64 v[174:175], v5 offset:3432
	ds_read_b64 v[104:105], v5 offset:528
	ds_read_b64 v[112:113], v5 offset:1584
	ds_read_b64 v[120:121], v5 offset:2640
	ds_read_b64 v[128:129], v5 offset:3696
	s_waitcnt lgkmcnt(8)
	ds_read_b64 v[106:107], v5 offset:792
	ds_read_b64 v[114:115], v5 offset:1848
	ds_read_b64 v[122:123], v5 offset:2904
	ds_read_b64 v[130:131], v5 offset:3960
	v_pk_add_f32 v[180:181], v[100:101], v[116:117]
	v_pk_add_f32 v[182:183], v[100:101], v[116:117] neg_lo:[0,1] neg_hi:[0,1]
	v_pk_add_f32 v[110:111], v[108:109], v[124:125]
	v_pk_add_f32 v[102:103], v[108:109], v[124:125] neg_lo:[0,1] neg_hi:[0,1]
	v_pk_add_f32 v[100:101], v[180:181], v[110:111]
	v_pk_add_f32 v[116:117], v[180:181], v[110:111] neg_lo:[0,1] neg_hi:[0,1]
	v_pk_add_f32 v[108:109], v[182:183], v[102:103] op_sel:[0,1] op_sel_hi:[1,0] neg_hi:[0,1]
	v_pk_add_f32 v[124:125], v[182:183], v[102:103] op_sel:[0,1] op_sel_hi:[1,0] neg_lo:[0,1]
	s_waitcnt lgkmcnt(9)
	v_pk_add_f32 v[126:127], v[178:179], v[166:167]
	v_pk_add_f32 v[118:119], v[178:179], v[166:167] neg_lo:[0,1] neg_hi:[0,1]
	s_waitcnt lgkmcnt(8)
	v_pk_add_f32 v[186:187], v[176:177], v[174:175]
	v_pk_add_f32 v[188:189], v[176:177], v[174:175] neg_lo:[0,1] neg_hi:[0,1]
	v_pk_add_f32 v[178:179], v[126:127], v[186:187]
	v_pk_add_f32 v[166:167], v[126:127], v[186:187] neg_lo:[0,1] neg_hi:[0,1]
	v_pk_add_f32 v[176:177], v[118:119], v[188:189] op_sel:[0,1] op_sel_hi:[1,0] neg_hi:[0,1]
	v_pk_add_f32 v[174:175], v[118:119], v[188:189] op_sel:[0,1] op_sel_hi:[1,0] neg_lo:[0,1]
	s_waitcnt lgkmcnt(5)
	v_pk_add_f32 v[184:185], v[104:105], v[120:121]
	v_pk_add_f32 v[168:169], v[104:105], v[120:121] neg_lo:[0,1] neg_hi:[0,1]
	s_waitcnt lgkmcnt(4)
	v_pk_add_f32 v[180:181], v[112:113], v[128:129]
	v_pk_add_f32 v[182:183], v[112:113], v[128:129] neg_lo:[0,1] neg_hi:[0,1]
	v_pk_add_f32 v[104:105], v[184:185], v[180:181]
	v_pk_add_f32 v[120:121], v[184:185], v[180:181] neg_lo:[0,1] neg_hi:[0,1]
	v_pk_add_f32 v[112:113], v[168:169], v[182:183] op_sel:[0,1] op_sel_hi:[1,0] neg_hi:[0,1]
	v_pk_add_f32 v[128:129], v[168:169], v[182:183] op_sel:[0,1] op_sel_hi:[1,0] neg_lo:[0,1]
	s_waitcnt lgkmcnt(1)
	v_pk_add_f32 v[110:111], v[106:107], v[122:123]
	v_pk_add_f32 v[102:103], v[106:107], v[122:123] neg_lo:[0,1] neg_hi:[0,1]
	s_waitcnt lgkmcnt(0)
	v_pk_add_f32 v[126:127], v[114:115], v[130:131]
	v_pk_add_f32 v[118:119], v[114:115], v[130:131] neg_lo:[0,1] neg_hi:[0,1]
	v_pk_add_f32 v[106:107], v[110:111], v[126:127]
	v_pk_add_f32 v[122:123], v[110:111], v[126:127] neg_lo:[0,1] neg_hi:[0,1]
	v_pk_add_f32 v[114:115], v[102:103], v[118:119] op_sel:[0,1] op_sel_hi:[1,0] neg_hi:[0,1]
	v_pk_add_f32 v[130:131], v[102:103], v[118:119] op_sel:[0,1] op_sel_hi:[1,0] neg_lo:[0,1]
	v_pk_mul_f32 v[186:187], v[176:177], s[68:69] op_sel:[1,1] op_sel_hi:[0,1]
	v_pk_fma_f32 v[176:177], v[176:177], s[68:69], v[186:187] op_sel_hi:[1,0,1] neg_lo:[0,0,1]
	v_pk_mul_f32 v[188:189], v[112:113], s[84:85] op_sel:[1,1] op_sel_hi:[0,1]
	v_pk_fma_f32 v[112:113], v[112:113], s[84:85], v[188:189] op_sel_hi:[1,0,1] neg_lo:[0,0,1]
	v_pk_mul_f32 v[184:185], v[114:115], s[88:89] op_sel:[1,1] op_sel_hi:[0,1]
	v_pk_fma_f32 v[114:115], v[114:115], s[88:89], v[184:185] op_sel_hi:[1,0,1] neg_lo:[0,0,1]
	v_pk_mul_f32 v[168:169], v[166:167], s[84:85] op_sel:[1,1] op_sel_hi:[0,1]
	v_pk_fma_f32 v[166:167], v[166:167], s[84:85], v[168:169] op_sel_hi:[1,0,1] neg_lo:[0,0,1]
	v_pk_mul_f32 v[180:181], v[122:123], s[90:91] op_sel:[1,1] op_sel_hi:[0,1]
	v_pk_fma_f32 v[122:123], v[122:123], s[90:91], v[180:181] op_sel_hi:[1,0,1] neg_lo:[0,0,1]
	v_pk_mul_f32 v[182:183], v[174:175], s[88:89] op_sel:[1,1] op_sel_hi:[0,1]
	v_pk_fma_f32 v[174:175], v[174:175], s[88:89], v[182:183] op_sel_hi:[1,0,1] neg_lo:[0,0,1]
	v_pk_mul_f32 v[110:111], v[128:129], s[90:91] op_sel:[1,1] op_sel_hi:[0,1]
	v_pk_fma_f32 v[128:129], v[128:129], s[90:91], v[110:111] op_sel_hi:[1,0,1] neg_lo:[0,0,1]
	v_pk_mul_f32 v[102:103], v[130:131], s[98:99] op_sel:[1,1] op_sel_hi:[0,1]
	v_pk_fma_f32 v[130:131], v[130:131], s[98:99], v[102:103] op_sel_hi:[1,0,1] neg_lo:[0,0,1]
	v_pk_add_f32 v[126:127], v[100:101], v[104:105]
	v_pk_add_f32 v[118:119], v[100:101], v[104:105] neg_lo:[0,1] neg_hi:[0,1]
	v_pk_add_f32 v[186:187], v[178:179], v[106:107]
	v_pk_add_f32 v[188:189], v[178:179], v[106:107] neg_lo:[0,1] neg_hi:[0,1]
	v_pk_add_f32 v[100:101], v[126:127], v[186:187]
	v_pk_add_f32 v[104:105], v[126:127], v[186:187] neg_lo:[0,1] neg_hi:[0,1]
	v_pk_add_f32 v[178:179], v[118:119], v[188:189] op_sel:[0,1] op_sel_hi:[1,0] neg_hi:[0,1]
	v_pk_add_f32 v[106:107], v[118:119], v[188:189] op_sel:[0,1] op_sel_hi:[1,0] neg_lo:[0,1]
	v_pk_add_f32 v[184:185], v[108:109], v[112:113]
	v_pk_add_f32 v[168:169], v[108:109], v[112:113] neg_lo:[0,1] neg_hi:[0,1]
	v_pk_add_f32 v[180:181], v[176:177], v[114:115]
	v_pk_add_f32 v[182:183], v[176:177], v[114:115] neg_lo:[0,1] neg_hi:[0,1]
	v_pk_add_f32 v[108:109], v[184:185], v[180:181]
	v_pk_add_f32 v[112:113], v[184:185], v[180:181] neg_lo:[0,1] neg_hi:[0,1]
	v_pk_add_f32 v[176:177], v[168:169], v[182:183] op_sel:[0,1] op_sel_hi:[1,0] neg_hi:[0,1]
	v_pk_add_f32 v[114:115], v[168:169], v[182:183] op_sel:[0,1] op_sel_hi:[1,0] neg_lo:[0,1]
	v_pk_add_f32 v[110:111], v[116:117], v[120:121] op_sel:[0,1] op_sel_hi:[1,0] neg_hi:[0,1]
	v_pk_add_f32 v[102:103], v[116:117], v[120:121] op_sel:[0,1] op_sel_hi:[1,0] neg_lo:[0,1]
	v_pk_add_f32 v[126:127], v[166:167], v[122:123]
	v_pk_add_f32 v[118:119], v[166:167], v[122:123] neg_lo:[0,1] neg_hi:[0,1]
	v_pk_add_f32 v[116:117], v[110:111], v[126:127]
	v_pk_add_f32 v[120:121], v[110:111], v[126:127] neg_lo:[0,1] neg_hi:[0,1]
	v_pk_add_f32 v[166:167], v[102:103], v[118:119] op_sel:[0,1] op_sel_hi:[1,0] neg_hi:[0,1]
	v_pk_add_f32 v[122:123], v[102:103], v[118:119] op_sel:[0,1] op_sel_hi:[1,0] neg_lo:[0,1]
	v_pk_add_f32 v[186:187], v[124:125], v[128:129]
	v_pk_add_f32 v[188:189], v[124:125], v[128:129] neg_lo:[0,1] neg_hi:[0,1]
	v_pk_add_f32 v[184:185], v[174:175], v[130:131]
	v_pk_add_f32 v[168:169], v[174:175], v[130:131] neg_lo:[0,1] neg_hi:[0,1]
	v_pk_add_f32 v[124:125], v[186:187], v[184:185]
	v_pk_add_f32 v[128:129], v[186:187], v[184:185] neg_lo:[0,1] neg_hi:[0,1]
	v_pk_add_f32 v[174:175], v[188:189], v[168:169] op_sel:[0,1] op_sel_hi:[1,0] neg_hi:[0,1]
	v_pk_add_f32 v[130:131], v[188:189], v[168:169] op_sel:[0,1] op_sel_hi:[1,0] neg_lo:[0,1]
	ds_write_b64 v5, v[100:101]
	ds_read_b64 v[180:181], v56 offset:256
	ds_read_b64 v[182:183], v56 offset:512
	ds_read_b64 v[110:111], v56 offset:768
	ds_read_b64 v[102:103], v56 offset:1024
	s_waitcnt lgkmcnt(3)
; #define LAS __attribute__((address_space(3)))
; __device__ __forceinline__ f32x2 cmul(f32x2 a, f32x2 b) { return (f32x2){a.x * b.x - a.y * b.y, a.x * b.y + a.y * b.x}; }
; __device__ __forceinline__ void fft_fwd2(LAS f32x2* B, const LAS f32x2* TW2, int tid) {
;     asm volatile("" : "+v"(tid));
;     const int b = tid >> 5, n2 = tid & 31, base = 512 * b + n2; f32x2 x[16];
; #pragma unroll
;     for (int r = 0; r < 16; ++r) x[r] = B[fpad(base + 32 * r)];
;     dft16<false>(x);
;     B[fpad(base)] = x[0];
; #pragma unroll
;     for (int k = 1; k < 16; ++k) B[fpad(base + 32 * k)] = cmul(x[k], TW2[k * 32 + n2]);
; }
; template <int MODE> __device__ __forceinline__ void fft_pair32(LAS f32x2* B, const LAS f32x2* F, int wave, int lane) {
;     asm volatile("" : "+v"(lane));
;     constexpr float CS[16] = {1.f, 0.98078528040323043f, 0.92387953251128674f, 0.83146961230254524f, 0.70710678118654752f, 0.55557023301960218f, 0.38268343236508977f, 0.19509032201612825f,
;                               0.f, -0.19509032201612825f, -0.38268343236508977f, -0.55557023301960218f, -0.70710678118654752f, -0.83146961230254524f, -0.92387953251128674f, -0.98078528040323043f};
;     constexpr float SN[16] = {0.f, 0.19509032201612825f, 0.38268343236508977f, 0.55557023301960218f, 0.70710678118654752f, 0.83146961230254524f, 0.92387953251128674f, 0.98078528040323043f,
;                               1.f, 0.98078528040323043f, 0.92387953251128674f, 0.83146961230254524f, 0.70710678118654752f, 0.55557023301960218f, 0.38268343236508977f, 0.19509032201612825f};
;     const int hi = lane >> 5, blk = 32 * wave + (lane & 31); const float sg = hi ? -1.f : 1.f;
;     LAS f32x2* p = B + 33 * blk; f32x2 v[16];
; #pragma unroll
;     for (int j = 0; j < 16; ++j) { const f32x2 d = p[j] + p[j + 16] * sg;
;         const f32x2 w = {hi ? CS[j] : 1.f, hi ? -SN[j] : 0.f}; v[j] = j == 0 ? d : cmul(d, w); }
;     dft16<false>(v);
	v_pk_mul_f32 v[126:127], v[108:109], v[180:181] op_sel:[1,1] op_sel_hi:[0,1]
	v_pk_fma_f32 v[108:109], v[108:109], v[180:181], v[126:127] op_sel_hi:[1,0,1] neg_lo:[0,0,1]
	ds_write_b64 v5, v[108:109] offset:264
	s_waitcnt lgkmcnt(3)
	v_pk_mul_f32 v[118:119], v[116:117], v[182:183] op_sel:[1,1] op_sel_hi:[0,1]
	v_pk_fma_f32 v[116:117], v[116:117], v[182:183], v[118:119] op_sel_hi:[1,0,1] neg_lo:[0,0,1]
	ds_write_b64 v5, v[116:117] offset:528
	s_waitcnt lgkmcnt(3)
	v_pk_mul_f32 v[186:187], v[124:125], v[110:111] op_sel:[1,1] op_sel_hi:[0,1]
	v_pk_fma_f32 v[124:125], v[124:125], v[110:111], v[186:187] op_sel_hi:[1,0,1] neg_lo:[0,0,1]
	ds_write_b64 v5, v[124:125] offset:792
	s_waitcnt lgkmcnt(3)
	v_pk_mul_f32 v[188:189], v[178:179], v[102:103] op_sel:[1,1] op_sel_hi:[0,1]
	v_pk_fma_f32 v[178:179], v[178:179], v[102:103], v[188:189] op_sel_hi:[1,0,1] neg_lo:[0,0,1]
	ds_write_b64 v5, v[178:179] offset:1056
	ds_read_b64 v[184:185], v56 offset:1280
	ds_read_b64 v[168:169], v56 offset:1536
	ds_read_b64 v[126:127], v56 offset:1792
	ds_read_b64 v[118:119], v56 offset:2048
	s_waitcnt lgkmcnt(3)
	v_pk_mul_f32 v[186:187], v[176:177], v[184:185] op_sel:[1,1] op_sel_hi:[0,1]
	v_pk_fma_f32 v[176:177], v[176:177], v[184:185], v[186:187] op_sel_hi:[1,0,1] neg_lo:[0,0,1]
	ds_write_b64 v5, v[176:177] offset:1320
	s_waitcnt lgkmcnt(3)
	v_pk_mul_f32 v[188:189], v[166:167], v[168:169] op_sel:[1,1] op_sel_hi:[0,1]
	v_pk_fma_f32 v[166:167], v[166:167], v[168:169], v[188:189] op_sel_hi:[1,0,1] neg_lo:[0,0,1]
	ds_write_b64 v5, v[166:167] offset:1584
	s_waitcnt lgkmcnt(3)
	v_pk_mul_f32 v[180:181], v[174:175], v[126:127] op_sel:[1,1] op_sel_hi:[0,1]
	v_pk_fma_f32 v[174:175], v[174:175], v[126:127], v[180:181] op_sel_hi:[1,0,1] neg_lo:[0,0,1]
	ds_write_b64 v5, v[174:175] offset:1848
	s_waitcnt lgkmcnt(3)
	v_pk_mul_f32 v[182:183], v[104:105], v[118:119] op_sel:[1,1] op_sel_hi:[0,1]
	v_pk_fma_f32 v[104:105], v[104:105], v[118:119], v[182:183] op_sel_hi:[1,0,1] neg_lo:[0,0,1]
	ds_write_b64 v5, v[104:105] offset:2112
	ds_read_b64 v[110:111], v56 offset:2304
	ds_read_b64 v[102:103], v56 offset:2560
	ds_read_b64 v[186:187], v56 offset:2816
	ds_read_b64 v[188:189], v56 offset:3072
	s_waitcnt lgkmcnt(3)
	v_pk_mul_f32 v[180:181], v[112:113], v[110:111] op_sel:[1,1] op_sel_hi:[0,1]
	v_pk_fma_f32 v[112:113], v[112:113], v[110:111], v[180:181] op_sel_hi:[1,0,1] neg_lo:[0,0,1]
	ds_write_b64 v5, v[112:113] offset:2376
	s_waitcnt lgkmcnt(3)
	v_pk_mul_f32 v[182:183], v[120:121], v[102:103] op_sel:[1,1] op_sel_hi:[0,1]
	v_pk_fma_f32 v[120:121], v[120:121], v[102:103], v[182:183] op_sel_hi:[1,0,1] neg_lo:[0,0,1]
	ds_write_b64 v5, v[120:121] offset:2640
	s_waitcnt lgkmcnt(3)
	v_pk_mul_f32 v[184:185], v[128:129], v[186:187] op_sel:[1,1] op_sel_hi:[0,1]
	v_pk_fma_f32 v[128:129], v[128:129], v[186:187], v[184:185] op_sel_hi:[1,0,1] neg_lo:[0,0,1]
	ds_write_b64 v5, v[128:129] offset:2904
	s_waitcnt lgkmcnt(3)
	v_pk_mul_f32 v[168:169], v[106:107], v[188:189] op_sel:[1,1] op_sel_hi:[0,1]
	v_pk_fma_f32 v[106:107], v[106:107], v[188:189], v[168:169] op_sel_hi:[1,0,1] neg_lo:[0,0,1]
	ds_write_b64 v5, v[106:107] offset:3168
	ds_read_b64 v[126:127], v56 offset:3328
	ds_read_b64 v[118:119], v56 offset:3584
	ds_read_b64 v[180:181], v56 offset:3840
	s_waitcnt lgkmcnt(2)
	v_pk_mul_f32 v[182:183], v[114:115], v[126:127] op_sel:[1,1] op_sel_hi:[0,1]
	v_pk_fma_f32 v[114:115], v[114:115], v[126:127], v[182:183] op_sel_hi:[1,0,1] neg_lo:[0,0,1]
	ds_write_b64 v5, v[114:115] offset:3432
	s_waitcnt lgkmcnt(2)
	v_pk_mul_f32 v[184:185], v[122:123], v[118:119] op_sel:[1,1] op_sel_hi:[0,1]
	v_pk_fma_f32 v[122:123], v[122:123], v[118:119], v[184:185] op_sel_hi:[1,0,1] neg_lo:[0,0,1]
	ds_write_b64 v5, v[122:123] offset:3696
	s_waitcnt lgkmcnt(2)
	v_pk_mul_f32 v[168:169], v[130:131], v[180:181] op_sel:[1,1] op_sel_hi:[0,1]
	v_pk_fma_f32 v[130:131], v[130:131], v[180:181], v[168:169] op_sel_hi:[1,0,1] neg_lo:[0,0,1]
	ds_write_b64 v5, v[130:131] offset:3960
	s_waitcnt lgkmcnt(0)
	ds_read_b64 v[100:101], v156
	ds_read_b64 v[110:111], v156 offset:128
	ds_read_b64 v[108:109], v156 offset:8
	ds_read_b64 v[102:103], v156 offset:136
	ds_read_b64 v[116:117], v156 offset:16
	ds_read_b64 v[186:187], v156 offset:144
	ds_read_b64 v[124:125], v156 offset:24
	ds_read_b64 v[188:189], v156 offset:152
	s_waitcnt lgkmcnt(6)
	v_pk_fma_f32 v[100:101], v[110:111], v[190:191], v[100:101] op_sel_hi:[1,0,1]
	s_waitcnt lgkmcnt(4)
	v_pk_fma_f32 v[108:109], v[102:103], v[190:191], v[108:109] op_sel_hi:[1,0,1]
	v_pk_mul_f32 v[182:183], v[108:109], v[36:37] op_sel:[1,1] op_sel_hi:[0,1]
	v_pk_fma_f32 v[108:109], v[108:109], v[36:37], v[182:183] op_sel_hi:[1,0,1] neg_lo:[0,0,1]
	s_waitcnt lgkmcnt(2)
	v_pk_fma_f32 v[116:117], v[186:187], v[190:191], v[116:117] op_sel_hi:[1,0,1]
	v_pk_mul_f32 v[184:185], v[116:117], v[38:39] op_sel:[1,1] op_sel_hi:[0,1]
	v_pk_fma_f32 v[116:117], v[116:117], v[38:39], v[184:185] op_sel_hi:[1,0,1] neg_lo:[0,0,1]
	s_waitcnt lgkmcnt(0)
	v_pk_fma_f32 v[124:125], v[188:189], v[190:191], v[124:125] op_sel_hi:[1,0,1]
	v_pk_mul_f32 v[168:169], v[124:125], v[40:41] op_sel:[1,1] op_sel_hi:[0,1]
	v_pk_fma_f32 v[124:125], v[124:125], v[40:41], v[168:169] op_sel_hi:[1,0,1] neg_lo:[0,0,1]
	ds_read_b64 v[178:179], v156 offset:32
	ds_read_b64 v[126:127], v156 offset:160
	ds_read_b64 v[176:177], v156 offset:40
	ds_read_b64 v[118:119], v156 offset:168
	ds_read_b64 v[166:167], v156 offset:48
	ds_read_b64 v[180:181], v156 offset:176
	ds_read_b64 v[174:175], v156 offset:56
	ds_read_b64 v[182:183], v156 offset:184
	s_waitcnt lgkmcnt(6)
; #define LAS __attribute__((address_space(3)))
; template <bool INV> __device__ __forceinline__ void dft16(f32x2 (&x)[16]) {
;     constexpr float C1 = 0.92387953251128674f, S1 = 0.38268343236508977f, C2 = 0.70710678118654752f;
; #pragma unroll
;     for (int b = 0; b < 4; ++b) dft4<INV>(x[b], x[4 + b], x[8 + b], x[12 + b]);
;     const f32x2 w1 = {C1, -S1}, w2 = {C2, -C2}, w3 = {S1, -C1}, w4 = {0.f, -1.f}, w6 = {-C2, -C2}, w9 = {-C1, S1};
;     x[4 * 1 + 1] = cmul_tw<INV>(x[5], w1); x[4 * 1 + 2] = cmul_tw<INV>(x[6], w2); x[4 * 1 + 3] = cmul_tw<INV>(x[7], w3);
;     x[4 * 2 + 1] = cmul_tw<INV>(x[9], w2); x[4 * 2 + 2] = cmul_tw<INV>(x[10], w4); x[4 * 2 + 3] = cmul_tw<INV>(x[11], w6);
;     x[4 * 3 + 1] = cmul_tw<INV>(x[13], w3); x[4 * 3 + 2] = cmul_tw<INV>(x[14], w6); x[4 * 3 + 3] = cmul_tw<INV>(x[15], w9);
; #pragma unroll
;     for (int c = 0; c < 4; ++c) dft4<INV>(x[4 * c], x[4 * c + 1], x[4 * c + 2], x[4 * c + 3]);
;     f32x2 y[16];
; #pragma unroll
;     for (int k = 0; k < 16; ++k) y[k] = x[4 * (k & 3) + (k >> 2)];
; #pragma unroll
;     for (int k = 0; k < 16; ++k) x[k] = y[k];
; }
; template <int MODE> __device__ __forceinline__ void fft_pair32(LAS f32x2* B, const LAS f32x2* F, int wave, int lane) {
;     asm volatile("" : "+v"(lane));
;     constexpr float CS[16] = {1.f, 0.98078528040323043f, 0.92387953251128674f, 0.83146961230254524f, 0.70710678118654752f, 0.55557023301960218f, 0.38268343236508977f, 0.19509032201612825f,
;                               0.f, -0.19509032201612825f, -0.38268343236508977f, -0.55557023301960218f, -0.70710678118654752f, -0.83146961230254524f, -0.92387953251128674f, -0.98078528040323043f};
;     constexpr float SN[16] = {0.f, 0.19509032201612825f, 0.38268343236508977f, 0.55557023301960218f, 0.70710678118654752f, 0.83146961230254524f, 0.92387953251128674f, 0.98078528040323043f,
;                               1.f, 0.98078528040323043f, 0.92387953251128674f, 0.83146961230254524f, 0.70710678118654752f, 0.55557023301960218f, 0.38268343236508977f, 0.19509032201612825f};
;     const int hi = lane >> 5, blk = 32 * wave + (lane & 31); const float sg = hi ? -1.f : 1.f;
;     LAS f32x2* p = B + 33 * blk; f32x2 v[16];
; #pragma unroll
;     for (int j = 0; j < 16; ++j) { const f32x2 d = p[j] + p[j + 16] * sg;
;         const f32x2 w = {hi ? CS[j] : 1.f, hi ? -SN[j] : 0.f}; v[j] = j == 0 ? d : cmul(d, w); }
;     dft16<false>(v);
	v_pk_fma_f32 v[178:179], v[126:127], v[190:191], v[178:179] op_sel_hi:[1,0,1]
	v_pk_mul_f32 v[184:185], v[178:179], v[42:43] op_sel:[1,1] op_sel_hi:[0,1]
	v_pk_fma_f32 v[178:179], v[178:179], v[42:43], v[184:185] op_sel_hi:[1,0,1] neg_lo:[0,0,1]
	s_waitcnt lgkmcnt(4)
	v_pk_fma_f32 v[176:177], v[118:119], v[190:191], v[176:177] op_sel_hi:[1,0,1]
	v_pk_mul_f32 v[168:169], v[176:177], v[44:45] op_sel:[1,1] op_sel_hi:[0,1]
	v_pk_fma_f32 v[176:177], v[176:177], v[44:45], v[168:169] op_sel_hi:[1,0,1] neg_lo:[0,0,1]
	s_waitcnt lgkmcnt(2)
	v_pk_fma_f32 v[166:167], v[180:181], v[190:191], v[166:167] op_sel_hi:[1,0,1]
	v_pk_mul_f32 v[110:111], v[166:167], v[46:47] op_sel:[1,1] op_sel_hi:[0,1]
	v_pk_fma_f32 v[166:167], v[166:167], v[46:47], v[110:111] op_sel_hi:[1,0,1] neg_lo:[0,0,1]
	s_waitcnt lgkmcnt(0)
	v_pk_fma_f32 v[174:175], v[182:183], v[190:191], v[174:175] op_sel_hi:[1,0,1]
	v_pk_mul_f32 v[102:103], v[174:175], v[48:49] op_sel:[1,1] op_sel_hi:[0,1]
	v_pk_fma_f32 v[174:175], v[174:175], v[48:49], v[102:103] op_sel_hi:[1,0,1] neg_lo:[0,0,1]
	ds_read_b64 v[104:105], v156 offset:64
	ds_read_b64 v[186:187], v156 offset:192
	ds_read_b64 v[112:113], v156 offset:72
	ds_read_b64 v[188:189], v156 offset:200
	ds_read_b64 v[120:121], v156 offset:80
	ds_read_b64 v[184:185], v156 offset:208
	ds_read_b64 v[128:129], v156 offset:88
	ds_read_b64 v[168:169], v156 offset:216
	s_waitcnt lgkmcnt(6)
	v_pk_fma_f32 v[104:105], v[186:187], v[190:191], v[104:105] op_sel_hi:[1,0,1]
	v_pk_mul_f32 v[110:111], v[104:105], v[50:51] op_sel:[1,1] op_sel_hi:[0,1]
	v_pk_fma_f32 v[104:105], v[104:105], v[50:51], v[110:111] op_sel_hi:[1,0,1] neg_lo:[0,0,1]
	s_waitcnt lgkmcnt(4)
	v_pk_fma_f32 v[112:113], v[188:189], v[190:191], v[112:113] op_sel_hi:[1,0,1]
	v_pk_mul_f32 v[102:103], v[112:113], v[52:53] op_sel:[1,1] op_sel_hi:[0,1]
	v_pk_fma_f32 v[112:113], v[112:113], v[52:53], v[102:103] op_sel_hi:[1,0,1] neg_lo:[0,0,1]
	s_waitcnt lgkmcnt(2)
	v_pk_fma_f32 v[120:121], v[184:185], v[190:191], v[120:121] op_sel_hi:[1,0,1]
	v_pk_mul_f32 v[126:127], v[120:121], v[54:55] op_sel:[1,1] op_sel_hi:[0,1]
	v_pk_fma_f32 v[120:121], v[120:121], v[54:55], v[126:127] op_sel_hi:[1,0,1] neg_lo:[0,0,1]
	s_waitcnt lgkmcnt(0)
	v_pk_fma_f32 v[128:129], v[168:169], v[190:191], v[128:129] op_sel_hi:[1,0,1]
	v_pk_mul_f32 v[118:119], v[128:129], v[90:91] op_sel:[1,1] op_sel_hi:[0,1]
	v_pk_fma_f32 v[128:129], v[128:129], v[90:91], v[118:119] op_sel_hi:[1,0,1] neg_lo:[0,0,1]
	ds_read_b64 v[106:107], v156 offset:96
	ds_read_b64 v[180:181], v156 offset:224
	ds_read_b64 v[114:115], v156 offset:104
	ds_read_b64 v[182:183], v156 offset:232
	ds_read_b64 v[122:123], v156 offset:112
	ds_read_b64 v[110:111], v156 offset:240
	ds_read_b64 v[130:131], v156 offset:120
	ds_read_b64 v[102:103], v156 offset:248
	s_waitcnt lgkmcnt(6)
	v_pk_fma_f32 v[106:107], v[180:181], v[190:191], v[106:107] op_sel_hi:[1,0,1]
	v_pk_mul_f32 v[126:127], v[106:107], v[92:93] op_sel:[1,1] op_sel_hi:[0,1]
	v_pk_fma_f32 v[106:107], v[106:107], v[92:93], v[126:127] op_sel_hi:[1,0,1] neg_lo:[0,0,1]
	s_waitcnt lgkmcnt(4)
	v_pk_fma_f32 v[114:115], v[182:183], v[190:191], v[114:115] op_sel_hi:[1,0,1]
	v_pk_mul_f32 v[118:119], v[114:115], v[94:95] op_sel:[1,1] op_sel_hi:[0,1]
	v_pk_fma_f32 v[114:115], v[114:115], v[94:95], v[118:119] op_sel_hi:[1,0,1] neg_lo:[0,0,1]
	s_waitcnt lgkmcnt(2)
	v_pk_fma_f32 v[122:123], v[110:111], v[190:191], v[122:123] op_sel_hi:[1,0,1]
	v_pk_mul_f32 v[186:187], v[122:123], v[96:97] op_sel:[1,1] op_sel_hi:[0,1]
	v_pk_fma_f32 v[122:123], v[122:123], v[96:97], v[186:187] op_sel_hi:[1,0,1] neg_lo:[0,0,1]
	s_waitcnt lgkmcnt(0)
	v_pk_fma_f32 v[130:131], v[102:103], v[190:191], v[130:131] op_sel_hi:[1,0,1]
	v_pk_mul_f32 v[188:189], v[130:131], v[98:99] op_sel:[1,1] op_sel_hi:[0,1]
	v_pk_fma_f32 v[130:131], v[130:131], v[98:99], v[188:189] op_sel_hi:[1,0,1] neg_lo:[0,0,1]
	v_pk_add_f32 v[184:185], v[100:101], v[104:105]
	v_pk_add_f32 v[168:169], v[100:101], v[104:105] neg_lo:[0,1] neg_hi:[0,1]
	v_pk_add_f32 v[126:127], v[178:179], v[106:107]
	v_pk_add_f32 v[118:119], v[178:179], v[106:107] neg_lo:[0,1] neg_hi:[0,1]
	v_pk_add_f32 v[100:101], v[184:185], v[126:127]
	v_pk_add_f32 v[104:105], v[184:185], v[126:127] neg_lo:[0,1] neg_hi:[0,1]
	v_pk_add_f32 v[178:179], v[168:169], v[118:119] op_sel:[0,1] op_sel_hi:[1,0] neg_hi:[0,1]
	v_pk_add_f32 v[106:107], v[168:169], v[118:119] op_sel:[0,1] op_sel_hi:[1,0] neg_lo:[0,1]
	v_pk_add_f32 v[186:187], v[108:109], v[112:113]
	v_pk_add_f32 v[188:189], v[108:109], v[112:113] neg_lo:[0,1] neg_hi:[0,1]
	v_pk_add_f32 v[180:181], v[176:177], v[114:115]
	v_pk_add_f32 v[182:183], v[176:177], v[114:115] neg_lo:[0,1] neg_hi:[0,1]
	v_pk_add_f32 v[108:109], v[186:187], v[180:181]
	v_pk_add_f32 v[112:113], v[186:187], v[180:181] neg_lo:[0,1] neg_hi:[0,1]
	v_pk_add_f32 v[176:177], v[188:189], v[182:183] op_sel:[0,1] op_sel_hi:[1,0] neg_hi:[0,1]
	v_pk_add_f32 v[114:115], v[188:189], v[182:183] op_sel:[0,1] op_sel_hi:[1,0] neg_lo:[0,1]
	v_pk_add_f32 v[110:111], v[116:117], v[120:121]
	v_pk_add_f32 v[102:103], v[116:117], v[120:121] neg_lo:[0,1] neg_hi:[0,1]
	v_pk_add_f32 v[184:185], v[166:167], v[122:123]
	v_pk_add_f32 v[168:169], v[166:167], v[122:123] neg_lo:[0,1] neg_hi:[0,1]
	v_pk_add_f32 v[116:117], v[110:111], v[184:185]
	v_pk_add_f32 v[120:121], v[110:111], v[184:185] neg_lo:[0,1] neg_hi:[0,1]
	v_pk_add_f32 v[166:167], v[102:103], v[168:169] op_sel:[0,1] op_sel_hi:[1,0] neg_hi:[0,1]
	v_pk_add_f32 v[122:123], v[102:103], v[168:169] op_sel:[0,1] op_sel_hi:[1,0] neg_lo:[0,1]
	v_pk_add_f32 v[126:127], v[124:125], v[128:129]
	v_pk_add_f32 v[118:119], v[124:125], v[128:129] neg_lo:[0,1] neg_hi:[0,1]
; #define LAS __attribute__((address_space(3)))
; __device__ __forceinline__ f32x2 cmul(f32x2 a, f32x2 b) { return (f32x2){a.x * b.x - a.y * b.y, a.x * b.y + a.y * b.x}; }
; template <int MODE> __device__ __forceinline__ void fft_pair32(LAS f32x2* B, const LAS f32x2* F, int wave, int lane) {
;     ...
;     const int k1 = blk >> 4, k2 = blk & 15, kb1 = (16 - k1) & 15, b1 = k1 != 0 ? 1 : 0, kb2 = (16 - k2 - b1) & 15, b2 = (k2 != 0 || b1) ? 1 : 0;
;     const LAS f32x2* fa = F + 33 * blk; const LAS f32x2* fb = F + 33 * (16 * kb1 + kb2);
;     const LAS f32x2* fah = fa + hi; const LAS f32x2* fbh = fb + (1 - b2) - hi;
;     constexpr float SC = 1.0f / (2.0f * (float)FN);
; #pragma unroll
;     for (int k = 0; k < 16; ++k) { const f32x2 A = fah[2 * k]; f32x2 Bm = fbh[31 - 2 * k];
;         if (k == 0) { const f32x2 m0 = b2 ? fb[31] : fa[0]; Bm = hi ? Bm : m0; }
;         const f32x2 H = MODE == 0 ? (f32x2){(A.x + Bm.x) * SC, (A.y - Bm.y) * SC} : (f32x2){(A.y + Bm.y) * SC, (Bm.x - A.x) * SC};
;         v[k] = cmul(v[k], H); }
	v_pk_add_f32 v[186:187], v[174:175], v[130:131]
	v_pk_add_f32 v[188:189], v[174:175], v[130:131] neg_lo:[0,1] neg_hi:[0,1]
	v_pk_add_f32 v[124:125], v[126:127], v[186:187]
	v_pk_add_f32 v[128:129], v[126:127], v[186:187] neg_lo:[0,1] neg_hi:[0,1]
	v_pk_add_f32 v[174:175], v[118:119], v[188:189] op_sel:[0,1] op_sel_hi:[1,0] neg_hi:[0,1]
	v_pk_add_f32 v[130:131], v[118:119], v[188:189] op_sel:[0,1] op_sel_hi:[1,0] neg_lo:[0,1]
	v_pk_mul_f32 v[180:181], v[176:177], s[68:69] op_sel:[1,1] op_sel_hi:[0,1]
	v_pk_fma_f32 v[176:177], v[176:177], s[68:69], v[180:181] op_sel_hi:[1,0,1] neg_lo:[0,0,1]
	v_pk_mul_f32 v[182:183], v[166:167], s[84:85] op_sel:[1,1] op_sel_hi:[0,1]
	v_pk_fma_f32 v[166:167], v[166:167], s[84:85], v[182:183] op_sel_hi:[1,0,1] neg_lo:[0,0,1]
	v_pk_mul_f32 v[110:111], v[174:175], s[88:89] op_sel:[1,1] op_sel_hi:[0,1]
	v_pk_fma_f32 v[174:175], v[174:175], s[88:89], v[110:111] op_sel_hi:[1,0,1] neg_lo:[0,0,1]
	v_pk_mul_f32 v[102:103], v[112:113], s[84:85] op_sel:[1,1] op_sel_hi:[0,1]
	v_pk_fma_f32 v[112:113], v[112:113], s[84:85], v[102:103] op_sel_hi:[1,0,1] neg_lo:[0,0,1]
	v_pk_mul_f32 v[184:185], v[128:129], s[90:91] op_sel:[1,1] op_sel_hi:[0,1]
	v_pk_fma_f32 v[128:129], v[128:129], s[90:91], v[184:185] op_sel_hi:[1,0,1] neg_lo:[0,0,1]
	v_pk_mul_f32 v[168:169], v[114:115], s[88:89] op_sel:[1,1] op_sel_hi:[0,1]
	v_pk_fma_f32 v[114:115], v[114:115], s[88:89], v[168:169] op_sel_hi:[1,0,1] neg_lo:[0,0,1]
	v_pk_mul_f32 v[126:127], v[122:123], s[90:91] op_sel:[1,1] op_sel_hi:[0,1]
	v_pk_fma_f32 v[122:123], v[122:123], s[90:91], v[126:127] op_sel_hi:[1,0,1] neg_lo:[0,0,1]
	v_pk_mul_f32 v[118:119], v[130:131], s[98:99] op_sel:[1,1] op_sel_hi:[0,1]
	v_pk_fma_f32 v[130:131], v[130:131], s[98:99], v[118:119] op_sel_hi:[1,0,1] neg_lo:[0,0,1]
	v_pk_add_f32 v[186:187], v[100:101], v[116:117]
	v_pk_add_f32 v[188:189], v[100:101], v[116:117] neg_lo:[0,1] neg_hi:[0,1]
	v_pk_add_f32 v[180:181], v[108:109], v[124:125]
	v_pk_add_f32 v[182:183], v[108:109], v[124:125] neg_lo:[0,1] neg_hi:[0,1]
	v_pk_add_f32 v[100:101], v[186:187], v[180:181]
	v_pk_add_f32 v[116:117], v[186:187], v[180:181] neg_lo:[0,1] neg_hi:[0,1]
	v_pk_add_f32 v[108:109], v[188:189], v[182:183] op_sel:[0,1] op_sel_hi:[1,0] neg_hi:[0,1]
	v_pk_add_f32 v[124:125], v[188:189], v[182:183] op_sel:[0,1] op_sel_hi:[1,0] neg_lo:[0,1]
	v_pk_add_f32 v[110:111], v[178:179], v[166:167]
	v_pk_add_f32 v[102:103], v[178:179], v[166:167] neg_lo:[0,1] neg_hi:[0,1]
	v_pk_add_f32 v[184:185], v[176:177], v[174:175]
	v_pk_add_f32 v[168:169], v[176:177], v[174:175] neg_lo:[0,1] neg_hi:[0,1]
	v_pk_add_f32 v[178:179], v[110:111], v[184:185]
	v_pk_add_f32 v[166:167], v[110:111], v[184:185] neg_lo:[0,1] neg_hi:[0,1]
	v_pk_add_f32 v[176:177], v[102:103], v[168:169] op_sel:[0,1] op_sel_hi:[1,0] neg_hi:[0,1]
	v_pk_add_f32 v[174:175], v[102:103], v[168:169] op_sel:[0,1] op_sel_hi:[1,0] neg_lo:[0,1]
	v_pk_add_f32 v[126:127], v[104:105], v[120:121] op_sel:[0,1] op_sel_hi:[1,0] neg_hi:[0,1]
	v_pk_add_f32 v[118:119], v[104:105], v[120:121] op_sel:[0,1] op_sel_hi:[1,0] neg_lo:[0,1]
	v_pk_add_f32 v[186:187], v[112:113], v[128:129]
	v_pk_add_f32 v[188:189], v[112:113], v[128:129] neg_lo:[0,1] neg_hi:[0,1]
	v_pk_add_f32 v[104:105], v[126:127], v[186:187]
	v_pk_add_f32 v[120:121], v[126:127], v[186:187] neg_lo:[0,1] neg_hi:[0,1]
	v_pk_add_f32 v[112:113], v[118:119], v[188:189] op_sel:[0,1] op_sel_hi:[1,0] neg_hi:[0,1]
	v_pk_add_f32 v[128:129], v[118:119], v[188:189] op_sel:[0,1] op_sel_hi:[1,0] neg_lo:[0,1]
	v_pk_add_f32 v[180:181], v[106:107], v[122:123]
	v_pk_add_f32 v[182:183], v[106:107], v[122:123] neg_lo:[0,1] neg_hi:[0,1]
	v_pk_add_f32 v[110:111], v[114:115], v[130:131]
	v_pk_add_f32 v[102:103], v[114:115], v[130:131] neg_lo:[0,1] neg_hi:[0,1]
	v_pk_add_f32 v[106:107], v[180:181], v[110:111]
	v_pk_add_f32 v[122:123], v[180:181], v[110:111] neg_lo:[0,1] neg_hi:[0,1]
	v_pk_add_f32 v[114:115], v[182:183], v[102:103] op_sel:[0,1] op_sel_hi:[1,0] neg_hi:[0,1]
	v_pk_add_f32 v[130:131], v[182:183], v[102:103] op_sel:[0,1] op_sel_hi:[1,0] neg_lo:[0,1]
	ds_read_b64 v[184:185], v200
	ds_read_b64 v[186:187], v204
	ds_read_b64 v[168:169], v200 offset:16
	ds_read_b64 v[188:189], v202 offset:232
	ds_read_b64 v[126:127], v200 offset:32
	ds_read_b64 v[180:181], v202 offset:216
	ds_read_b64 v[118:119], v200 offset:48
	ds_read_b64 v[182:183], v202 offset:200
	s_waitcnt lgkmcnt(6)
	v_pk_add_f32 v[184:185], v[184:185], v[186:187] neg_hi:[0,1]
	v_pk_mul_f32 v[110:111], v[100:101], v[184:185] op_sel:[1,1] op_sel_hi:[0,1]
	v_pk_fma_f32 v[100:101], v[100:101], v[184:185], v[110:111] op_sel_hi:[1,0,1] neg_lo:[0,0,1]
	s_waitcnt lgkmcnt(4)
	v_pk_add_f32 v[168:169], v[168:169], v[188:189] neg_hi:[0,1]
	v_pk_mul_f32 v[102:103], v[178:179], v[168:169] op_sel:[1,1] op_sel_hi:[0,1]
	v_pk_fma_f32 v[178:179], v[178:179], v[168:169], v[102:103] op_sel_hi:[1,0,1] neg_lo:[0,0,1]
	s_waitcnt lgkmcnt(2)
	v_pk_add_f32 v[126:127], v[126:127], v[180:181] neg_hi:[0,1]
	v_pk_mul_f32 v[110:111], v[104:105], v[126:127] op_sel:[1,1] op_sel_hi:[0,1]
	v_pk_fma_f32 v[104:105], v[104:105], v[126:127], v[110:111] op_sel_hi:[1,0,1] neg_lo:[0,0,1]
	s_waitcnt lgkmcnt(0)
	v_pk_add_f32 v[118:119], v[118:119], v[182:183] neg_hi:[0,1]
	v_pk_mul_f32 v[102:103], v[106:107], v[118:119] op_sel:[1,1] op_sel_hi:[0,1]
	v_pk_fma_f32 v[106:107], v[106:107], v[118:119], v[102:103] op_sel_hi:[1,0,1] neg_lo:[0,0,1]
	ds_read_b64 v[110:111], v200 offset:64
	ds_read_b64 v[126:127], v202 offset:184
	ds_read_b64 v[102:103], v200 offset:80
	ds_read_b64 v[118:119], v202 offset:168
	ds_read_b64 v[184:185], v200 offset:96
	ds_read_b64 v[186:187], v202 offset:152
	ds_read_b64 v[168:169], v200 offset:112
	ds_read_b64 v[188:189], v202 offset:136
	s_waitcnt lgkmcnt(6)
; #define LAS __attribute__((address_space(3)))
; __device__ __forceinline__ f32x2 cmul(f32x2 a, f32x2 b) { return (f32x2){a.x * b.x - a.y * b.y, a.x * b.y + a.y * b.x}; }
; template <int MODE> __device__ __forceinline__ void fft_pair32(LAS f32x2* B, const LAS f32x2* F, int wave, int lane) {
;     ...
;     const int k1 = blk >> 4, k2 = blk & 15, kb1 = (16 - k1) & 15, b1 = k1 != 0 ? 1 : 0, kb2 = (16 - k2 - b1) & 15, b2 = (k2 != 0 || b1) ? 1 : 0;
;     const LAS f32x2* fa = F + 33 * blk; const LAS f32x2* fb = F + 33 * (16 * kb1 + kb2);
;     const LAS f32x2* fah = fa + hi; const LAS f32x2* fbh = fb + (1 - b2) - hi;
;     constexpr float SC = 1.0f / (2.0f * (float)FN);
; #pragma unroll
;     for (int k = 0; k < 16; ++k) { const f32x2 A = fah[2 * k]; f32x2 Bm = fbh[31 - 2 * k];
;         if (k == 0) { const f32x2 m0 = b2 ? fb[31] : fa[0]; Bm = hi ? Bm : m0; }
;         const f32x2 H = MODE == 0 ? (f32x2){(A.x + Bm.x) * SC, (A.y - Bm.y) * SC} : (f32x2){(A.y + Bm.y) * SC, (Bm.x - A.x) * SC};
;         v[k] = cmul(v[k], H); }
;     dft16<true>(v);
	v_pk_add_f32 v[110:111], v[110:111], v[126:127] neg_hi:[0,1]
	v_pk_mul_f32 v[180:181], v[108:109], v[110:111] op_sel:[1,1] op_sel_hi:[0,1]
	v_pk_fma_f32 v[108:109], v[108:109], v[110:111], v[180:181] op_sel_hi:[1,0,1] neg_lo:[0,0,1]
	s_waitcnt lgkmcnt(4)
	v_pk_add_f32 v[102:103], v[102:103], v[118:119] neg_hi:[0,1]
	v_pk_mul_f32 v[182:183], v[176:177], v[102:103] op_sel:[1,1] op_sel_hi:[0,1]
	v_pk_fma_f32 v[176:177], v[176:177], v[102:103], v[182:183] op_sel_hi:[1,0,1] neg_lo:[0,0,1]
	s_waitcnt lgkmcnt(2)
	v_pk_add_f32 v[184:185], v[184:185], v[186:187] neg_hi:[0,1]
	v_pk_mul_f32 v[180:181], v[112:113], v[184:185] op_sel:[1,1] op_sel_hi:[0,1]
	v_pk_fma_f32 v[112:113], v[112:113], v[184:185], v[180:181] op_sel_hi:[1,0,1] neg_lo:[0,0,1]
	s_waitcnt lgkmcnt(0)
	v_pk_add_f32 v[168:169], v[168:169], v[188:189] neg_hi:[0,1]
	v_pk_mul_f32 v[182:183], v[114:115], v[168:169] op_sel:[1,1] op_sel_hi:[0,1]
	v_pk_fma_f32 v[114:115], v[114:115], v[168:169], v[182:183] op_sel_hi:[1,0,1] neg_lo:[0,0,1]
	ds_read_b64 v[180:181], v200 offset:128
	ds_read_b64 v[184:185], v202 offset:120
	ds_read_b64 v[182:183], v200 offset:144
	ds_read_b64 v[168:169], v202 offset:104
	ds_read_b64 v[110:111], v200 offset:160
	ds_read_b64 v[126:127], v202 offset:88
	ds_read_b64 v[102:103], v200 offset:176
	ds_read_b64 v[118:119], v202 offset:72
	s_waitcnt lgkmcnt(6)
	v_pk_add_f32 v[180:181], v[180:181], v[184:185] neg_hi:[0,1]
	v_pk_mul_f32 v[186:187], v[116:117], v[180:181] op_sel:[1,1] op_sel_hi:[0,1]
	v_pk_fma_f32 v[116:117], v[116:117], v[180:181], v[186:187] op_sel_hi:[1,0,1] neg_lo:[0,0,1]
	s_waitcnt lgkmcnt(4)
	v_pk_add_f32 v[182:183], v[182:183], v[168:169] neg_hi:[0,1]
	v_pk_mul_f32 v[188:189], v[166:167], v[182:183] op_sel:[1,1] op_sel_hi:[0,1]
	v_pk_fma_f32 v[166:167], v[166:167], v[182:183], v[188:189] op_sel_hi:[1,0,1] neg_lo:[0,0,1]
	s_waitcnt lgkmcnt(2)
	v_pk_add_f32 v[110:111], v[110:111], v[126:127] neg_hi:[0,1]
	v_pk_mul_f32 v[186:187], v[120:121], v[110:111] op_sel:[1,1] op_sel_hi:[0,1]
	v_pk_fma_f32 v[120:121], v[120:121], v[110:111], v[186:187] op_sel_hi:[1,0,1] neg_lo:[0,0,1]
	s_waitcnt lgkmcnt(0)
	v_pk_add_f32 v[102:103], v[102:103], v[118:119] neg_hi:[0,1]
	v_pk_mul_f32 v[188:189], v[122:123], v[102:103] op_sel:[1,1] op_sel_hi:[0,1]
	v_pk_fma_f32 v[122:123], v[122:123], v[102:103], v[188:189] op_sel_hi:[1,0,1] neg_lo:[0,0,1]
	ds_read_b64 v[186:187], v200 offset:192
	ds_read_b64 v[110:111], v202 offset:56
	ds_read_b64 v[188:189], v200 offset:208
	ds_read_b64 v[102:103], v202 offset:40
	ds_read_b64 v[180:181], v200 offset:224
	ds_read_b64 v[184:185], v202 offset:24
	ds_read_b64 v[182:183], v200 offset:240
	ds_read_b64 v[168:169], v202 offset:8
	s_waitcnt lgkmcnt(6)
	v_pk_add_f32 v[186:187], v[186:187], v[110:111] neg_hi:[0,1]
	v_pk_mul_f32 v[126:127], v[124:125], v[186:187] op_sel:[1,1] op_sel_hi:[0,1]
	v_pk_fma_f32 v[124:125], v[124:125], v[186:187], v[126:127] op_sel_hi:[1,0,1] neg_lo:[0,0,1]
	s_waitcnt lgkmcnt(4)
	v_pk_add_f32 v[188:189], v[188:189], v[102:103] neg_hi:[0,1]
	v_pk_mul_f32 v[118:119], v[174:175], v[188:189] op_sel:[1,1] op_sel_hi:[0,1]
	v_pk_fma_f32 v[174:175], v[174:175], v[188:189], v[118:119] op_sel_hi:[1,0,1] neg_lo:[0,0,1]
	s_waitcnt lgkmcnt(2)
	v_pk_add_f32 v[180:181], v[180:181], v[184:185] neg_hi:[0,1]
	v_pk_mul_f32 v[126:127], v[128:129], v[180:181] op_sel:[1,1] op_sel_hi:[0,1]
	v_pk_fma_f32 v[128:129], v[128:129], v[180:181], v[126:127] op_sel_hi:[1,0,1] neg_lo:[0,0,1]
	s_waitcnt lgkmcnt(0)
	v_pk_add_f32 v[182:183], v[182:183], v[168:169] neg_hi:[0,1]
	v_pk_mul_f32 v[118:119], v[130:131], v[182:183] op_sel:[1,1] op_sel_hi:[0,1]
	v_pk_fma_f32 v[130:131], v[130:131], v[182:183], v[118:119] op_sel_hi:[1,0,1] neg_lo:[0,0,1]
	v_pk_add_f32 v[126:127], v[100:101], v[116:117]
	v_pk_add_f32 v[118:119], v[100:101], v[116:117] neg_lo:[0,1] neg_hi:[0,1]
	v_pk_add_f32 v[186:187], v[108:109], v[124:125]
	v_pk_add_f32 v[188:189], v[108:109], v[124:125] neg_lo:[0,1] neg_hi:[0,1]
	v_pk_add_f32 v[100:101], v[126:127], v[186:187]
	v_pk_add_f32 v[116:117], v[126:127], v[186:187] neg_lo:[0,1] neg_hi:[0,1]
	v_pk_add_f32 v[108:109], v[118:119], v[188:189] op_sel:[0,1] op_sel_hi:[1,0] neg_lo:[0,1]
	v_pk_add_f32 v[124:125], v[118:119], v[188:189] op_sel:[0,1] op_sel_hi:[1,0] neg_hi:[0,1]
	v_pk_add_f32 v[180:181], v[178:179], v[166:167]
	v_pk_add_f32 v[182:183], v[178:179], v[166:167] neg_lo:[0,1] neg_hi:[0,1]
	v_pk_add_f32 v[110:111], v[176:177], v[174:175]
	v_pk_add_f32 v[102:103], v[176:177], v[174:175] neg_lo:[0,1] neg_hi:[0,1]
	v_pk_add_f32 v[178:179], v[180:181], v[110:111]
	v_pk_add_f32 v[166:167], v[180:181], v[110:111] neg_lo:[0,1] neg_hi:[0,1]
	v_pk_add_f32 v[176:177], v[182:183], v[102:103] op_sel:[0,1] op_sel_hi:[1,0] neg_lo:[0,1]
	v_pk_add_f32 v[174:175], v[182:183], v[102:103] op_sel:[0,1] op_sel_hi:[1,0] neg_hi:[0,1]
	v_pk_add_f32 v[184:185], v[104:105], v[120:121]
	v_pk_add_f32 v[168:169], v[104:105], v[120:121] neg_lo:[0,1] neg_hi:[0,1]
	v_pk_add_f32 v[126:127], v[112:113], v[128:129]
	v_pk_add_f32 v[118:119], v[112:113], v[128:129] neg_lo:[0,1] neg_hi:[0,1]
	v_pk_add_f32 v[104:105], v[184:185], v[126:127]
	v_pk_add_f32 v[120:121], v[184:185], v[126:127] neg_lo:[0,1] neg_hi:[0,1]
	v_pk_add_f32 v[112:113], v[168:169], v[118:119] op_sel:[0,1] op_sel_hi:[1,0] neg_lo:[0,1]
	v_pk_add_f32 v[128:129], v[168:169], v[118:119] op_sel:[0,1] op_sel_hi:[1,0] neg_hi:[0,1]
	v_pk_add_f32 v[186:187], v[106:107], v[122:123]
	v_pk_add_f32 v[188:189], v[106:107], v[122:123] neg_lo:[0,1] neg_hi:[0,1]
	v_pk_add_f32 v[180:181], v[114:115], v[130:131]
	v_pk_add_f32 v[182:183], v[114:115], v[130:131] neg_lo:[0,1] neg_hi:[0,1]
	v_pk_add_f32 v[106:107], v[186:187], v[180:181]
; __device__ __forceinline__ f32x2 cmulc(f32x2 a, f32x2 b) { return (f32x2){a.x * b.x + a.y * b.y, a.y * b.x - a.x * b.y}; }
; template <int MODE> __device__ __forceinline__ void fft_pair32(LAS f32x2* B, const LAS f32x2* F, int wave, int lane) {
;     ...
;     dft16<true>(v);
; #pragma unroll
;     for (int j = 0; j < 16; ++j) { const f32x2 w = {hi ? CS[j] : 1.f, hi ? -SN[j] : 0.f}; const f32x2 u = j == 0 ? v[j] : cmulc(v[j], w);
;         const auto rx = __builtin_amdgcn_permlane32_swap(__float_as_uint(u.x), __float_as_uint(u.x), false, false);
;         const auto ry = __builtin_amdgcn_permlane32_swap(__float_as_uint(u.y), __float_as_uint(u.y), false, false);
;         const f32x2 a = {__uint_as_float(rx[0]), __uint_as_float(ry[0])}, b = {__uint_as_float(rx[1]), __uint_as_float(ry[1])};
;         p[16 * hi + j] = a + b * sg; }
	v_pk_add_f32 v[122:123], v[186:187], v[180:181] neg_lo:[0,1] neg_hi:[0,1]
	v_pk_add_f32 v[114:115], v[188:189], v[182:183] op_sel:[0,1] op_sel_hi:[1,0] neg_lo:[0,1]
	v_pk_add_f32 v[130:131], v[188:189], v[182:183] op_sel:[0,1] op_sel_hi:[1,0] neg_hi:[0,1]
	v_pk_mul_f32 v[110:111], v[176:177], s[68:69] op_sel:[1,1] op_sel_hi:[0,1]
	v_pk_fma_f32 v[176:177], v[176:177], s[68:69], v[110:111] op_sel_hi:[1,0,1] neg_hi:[0,0,1]
	v_pk_mul_f32 v[102:103], v[112:113], s[84:85] op_sel:[1,1] op_sel_hi:[0,1]
	v_pk_fma_f32 v[112:113], v[112:113], s[84:85], v[102:103] op_sel_hi:[1,0,1] neg_hi:[0,0,1]
	v_pk_mul_f32 v[184:185], v[114:115], s[88:89] op_sel:[1,1] op_sel_hi:[0,1]
	v_pk_fma_f32 v[114:115], v[114:115], s[88:89], v[184:185] op_sel_hi:[1,0,1] neg_hi:[0,0,1]
	v_pk_mul_f32 v[168:169], v[166:167], s[84:85] op_sel:[1,1] op_sel_hi:[0,1]
	v_pk_fma_f32 v[166:167], v[166:167], s[84:85], v[168:169] op_sel_hi:[1,0,1] neg_hi:[0,0,1]
	v_pk_mul_f32 v[126:127], v[122:123], s[90:91] op_sel:[1,1] op_sel_hi:[0,1]
	v_pk_fma_f32 v[122:123], v[122:123], s[90:91], v[126:127] op_sel_hi:[1,0,1] neg_hi:[0,0,1]
	v_pk_mul_f32 v[118:119], v[174:175], s[88:89] op_sel:[1,1] op_sel_hi:[0,1]
	v_pk_fma_f32 v[174:175], v[174:175], s[88:89], v[118:119] op_sel_hi:[1,0,1] neg_hi:[0,0,1]
	v_pk_mul_f32 v[186:187], v[128:129], s[90:91] op_sel:[1,1] op_sel_hi:[0,1]
	v_pk_fma_f32 v[128:129], v[128:129], s[90:91], v[186:187] op_sel_hi:[1,0,1] neg_hi:[0,0,1]
	v_pk_mul_f32 v[188:189], v[130:131], s[98:99] op_sel:[1,1] op_sel_hi:[0,1]
	v_pk_fma_f32 v[130:131], v[130:131], s[98:99], v[188:189] op_sel_hi:[1,0,1] neg_hi:[0,0,1]
	v_pk_add_f32 v[180:181], v[100:101], v[104:105]
	v_pk_add_f32 v[182:183], v[100:101], v[104:105] neg_lo:[0,1] neg_hi:[0,1]
	v_pk_add_f32 v[110:111], v[178:179], v[106:107]
	v_pk_add_f32 v[102:103], v[178:179], v[106:107] neg_lo:[0,1] neg_hi:[0,1]
	v_pk_add_f32 v[100:101], v[180:181], v[110:111]
	v_pk_add_f32 v[104:105], v[180:181], v[110:111] neg_lo:[0,1] neg_hi:[0,1]
	v_pk_add_f32 v[178:179], v[182:183], v[102:103] op_sel:[0,1] op_sel_hi:[1,0] neg_lo:[0,1]
	v_pk_add_f32 v[106:107], v[182:183], v[102:103] op_sel:[0,1] op_sel_hi:[1,0] neg_hi:[0,1]
	v_pk_add_f32 v[184:185], v[108:109], v[112:113]
	v_pk_add_f32 v[168:169], v[108:109], v[112:113] neg_lo:[0,1] neg_hi:[0,1]
	v_pk_add_f32 v[126:127], v[176:177], v[114:115]
	v_pk_add_f32 v[118:119], v[176:177], v[114:115] neg_lo:[0,1] neg_hi:[0,1]
	v_pk_add_f32 v[108:109], v[184:185], v[126:127]
	v_pk_add_f32 v[112:113], v[184:185], v[126:127] neg_lo:[0,1] neg_hi:[0,1]
	v_pk_add_f32 v[176:177], v[168:169], v[118:119] op_sel:[0,1] op_sel_hi:[1,0] neg_lo:[0,1]
	v_pk_add_f32 v[114:115], v[168:169], v[118:119] op_sel:[0,1] op_sel_hi:[1,0] neg_hi:[0,1]
	v_pk_add_f32 v[186:187], v[116:117], v[120:121] op_sel:[0,1] op_sel_hi:[1,0] neg_lo:[0,1]
	v_pk_add_f32 v[188:189], v[116:117], v[120:121] op_sel:[0,1] op_sel_hi:[1,0] neg_hi:[0,1]
	v_pk_add_f32 v[180:181], v[166:167], v[122:123]
	v_pk_add_f32 v[182:183], v[166:167], v[122:123] neg_lo:[0,1] neg_hi:[0,1]
	v_pk_add_f32 v[116:117], v[186:187], v[180:181]
	v_pk_add_f32 v[120:121], v[186:187], v[180:181] neg_lo:[0,1] neg_hi:[0,1]
	v_pk_add_f32 v[166:167], v[188:189], v[182:183] op_sel:[0,1] op_sel_hi:[1,0] neg_lo:[0,1]
	v_pk_add_f32 v[122:123], v[188:189], v[182:183] op_sel:[0,1] op_sel_hi:[1,0] neg_hi:[0,1]
	v_pk_add_f32 v[110:111], v[124:125], v[128:129]
	v_pk_add_f32 v[102:103], v[124:125], v[128:129] neg_lo:[0,1] neg_hi:[0,1]
	v_pk_add_f32 v[184:185], v[174:175], v[130:131]
	v_pk_add_f32 v[168:169], v[174:175], v[130:131] neg_lo:[0,1] neg_hi:[0,1]
	v_pk_add_f32 v[124:125], v[110:111], v[184:185]
	v_pk_add_f32 v[128:129], v[110:111], v[184:185] neg_lo:[0,1] neg_hi:[0,1]
	v_pk_add_f32 v[174:175], v[102:103], v[168:169] op_sel:[0,1] op_sel_hi:[1,0] neg_lo:[0,1]
	v_pk_add_f32 v[130:131], v[102:103], v[168:169] op_sel:[0,1] op_sel_hi:[1,0] neg_hi:[0,1]
	v_mov_b32_e32 v126, v100
	v_mov_b32_e32 v127, v101
	v_pk_mul_f32 v[180:181], v[108:109], v[36:37] op_sel:[1,1] op_sel_hi:[0,1]
	v_pk_fma_f32 v[118:119], v[108:109], v[36:37], v[180:181] op_sel_hi:[1,0,1] neg_hi:[0,0,1]
	v_pk_fma_f32 v[108:109], v[108:109], v[36:37], v[180:181] op_sel_hi:[1,0,1] neg_hi:[0,0,1]
	v_pk_mul_f32 v[182:183], v[116:117], v[38:39] op_sel:[1,1] op_sel_hi:[0,1]
	v_pk_fma_f32 v[186:187], v[116:117], v[38:39], v[182:183] op_sel_hi:[1,0,1] neg_hi:[0,0,1]
	v_pk_fma_f32 v[116:117], v[116:117], v[38:39], v[182:183] op_sel_hi:[1,0,1] neg_hi:[0,0,1]
	v_pk_mul_f32 v[110:111], v[124:125], v[40:41] op_sel:[1,1] op_sel_hi:[0,1]
	v_pk_fma_f32 v[188:189], v[124:125], v[40:41], v[110:111] op_sel_hi:[1,0,1] neg_hi:[0,0,1]
	v_pk_fma_f32 v[124:125], v[124:125], v[40:41], v[110:111] op_sel_hi:[1,0,1] neg_hi:[0,0,1]
	s_nop 1
	v_permlane32_swap_b32_e32 v100, v126
	v_permlane32_swap_b32_e32 v101, v127
	v_permlane32_swap_b32_e32 v108, v118
	v_permlane32_swap_b32_e32 v109, v119
	v_permlane32_swap_b32_e32 v116, v186
	v_permlane32_swap_b32_e32 v117, v187
	v_permlane32_swap_b32_e32 v124, v188
	v_permlane32_swap_b32_e32 v125, v189
	v_pk_fma_f32 v[100:101], v[126:127], v[190:191], v[100:101] op_sel_hi:[1,0,1]
	ds_write_b64 v198, v[100:101]
	v_pk_fma_f32 v[108:109], v[118:119], v[190:191], v[108:109] op_sel_hi:[1,0,1]
	ds_write_b64 v198, v[108:109] offset:8
	v_pk_fma_f32 v[116:117], v[186:187], v[190:191], v[116:117] op_sel_hi:[1,0,1]
	ds_write_b64 v198, v[116:117] offset:16
	v_pk_fma_f32 v[124:125], v[188:189], v[190:191], v[124:125] op_sel_hi:[1,0,1]
	ds_write_b64 v198, v[124:125] offset:24
	v_pk_mul_f32 v[182:183], v[178:179], v[42:43] op_sel:[1,1] op_sel_hi:[0,1]
	v_pk_fma_f32 v[102:103], v[178:179], v[42:43], v[182:183] op_sel_hi:[1,0,1] neg_hi:[0,0,1]
; #define LAS __attribute__((address_space(3)))
; __device__ __forceinline__ f32x2 cmulc(f32x2 a, f32x2 b) { return (f32x2){a.x * b.x + a.y * b.y, a.y * b.x - a.x * b.y}; }
; __device__ __forceinline__ void fft_inv2(LAS f32x2* B, const LAS f32x2* TW2, int tid) {
;     asm volatile("" : "+v"(tid));
;     const int b = tid >> 5, n2 = tid & 31, base = 512 * b + n2; f32x2 x[16];
;     x[0] = B[fpad(base)];
; #pragma unroll
;     for (int k = 1; k < 16; ++k) x[k] = cmulc(B[fpad(base + 32 * k)], TW2[k * 32 + n2]);
;     dft16<true>(x);
; #pragma unroll
;     for (int r = 0; r < 16; ++r) B[fpad(base + 32 * r)] = x[r];
; }
; template <int MODE> __device__ __forceinline__ void fft_pair32(LAS f32x2* B, const LAS f32x2* F, int wave, int lane) {
;     ...
;     for (int j = 0; j < 16; ++j) { const f32x2 w = {hi ? CS[j] : 1.f, hi ? -SN[j] : 0.f}; const f32x2 u = j == 0 ? v[j] : cmulc(v[j], w);
;         const auto rx = __builtin_amdgcn_permlane32_swap(__float_as_uint(u.x), __float_as_uint(u.x), false, false);
;         const auto ry = __builtin_amdgcn_permlane32_swap(__float_as_uint(u.y), __float_as_uint(u.y), false, false);
;         const f32x2 a = {__uint_as_float(rx[0]), __uint_as_float(ry[0])}, b = {__uint_as_float(rx[1]), __uint_as_float(ry[1])};
;         p[16 * hi + j] = a + b * sg; }
	v_pk_fma_f32 v[178:179], v[178:179], v[42:43], v[182:183] op_sel_hi:[1,0,1] neg_hi:[0,0,1]
	v_pk_mul_f32 v[110:111], v[176:177], v[44:45] op_sel:[1,1] op_sel_hi:[0,1]
	v_pk_fma_f32 v[184:185], v[176:177], v[44:45], v[110:111] op_sel_hi:[1,0,1] neg_hi:[0,0,1]
	v_pk_fma_f32 v[176:177], v[176:177], v[44:45], v[110:111] op_sel_hi:[1,0,1] neg_hi:[0,0,1]
	v_pk_mul_f32 v[126:127], v[166:167], v[46:47] op_sel:[1,1] op_sel_hi:[0,1]
	v_pk_fma_f32 v[168:169], v[166:167], v[46:47], v[126:127] op_sel_hi:[1,0,1] neg_hi:[0,0,1]
	v_pk_fma_f32 v[166:167], v[166:167], v[46:47], v[126:127] op_sel_hi:[1,0,1] neg_hi:[0,0,1]
	v_pk_mul_f32 v[118:119], v[174:175], v[48:49] op_sel:[1,1] op_sel_hi:[0,1]
	v_pk_fma_f32 v[180:181], v[174:175], v[48:49], v[118:119] op_sel_hi:[1,0,1] neg_hi:[0,0,1]
	v_pk_fma_f32 v[174:175], v[174:175], v[48:49], v[118:119] op_sel_hi:[1,0,1] neg_hi:[0,0,1]
	s_nop 1
	v_permlane32_swap_b32_e32 v178, v102
	v_permlane32_swap_b32_e32 v179, v103
	v_permlane32_swap_b32_e32 v176, v184
	v_permlane32_swap_b32_e32 v177, v185
	v_permlane32_swap_b32_e32 v166, v168
	v_permlane32_swap_b32_e32 v167, v169
	v_permlane32_swap_b32_e32 v174, v180
	v_permlane32_swap_b32_e32 v175, v181
	v_pk_fma_f32 v[178:179], v[102:103], v[190:191], v[178:179] op_sel_hi:[1,0,1]
	ds_write_b64 v198, v[178:179] offset:32
	v_pk_fma_f32 v[176:177], v[184:185], v[190:191], v[176:177] op_sel_hi:[1,0,1]
	ds_write_b64 v198, v[176:177] offset:40
	v_pk_fma_f32 v[166:167], v[168:169], v[190:191], v[166:167] op_sel_hi:[1,0,1]
	ds_write_b64 v198, v[166:167] offset:48
	v_pk_fma_f32 v[174:175], v[180:181], v[190:191], v[174:175] op_sel_hi:[1,0,1]
	ds_write_b64 v198, v[174:175] offset:56
	v_pk_mul_f32 v[126:127], v[104:105], v[50:51] op_sel:[1,1] op_sel_hi:[0,1]
	v_pk_fma_f32 v[186:187], v[104:105], v[50:51], v[126:127] op_sel_hi:[1,0,1] neg_hi:[0,0,1]
	v_pk_fma_f32 v[104:105], v[104:105], v[50:51], v[126:127] op_sel_hi:[1,0,1] neg_hi:[0,0,1]
	v_pk_mul_f32 v[118:119], v[112:113], v[52:53] op_sel:[1,1] op_sel_hi:[0,1]
	v_pk_fma_f32 v[188:189], v[112:113], v[52:53], v[118:119] op_sel_hi:[1,0,1] neg_hi:[0,0,1]
	v_pk_fma_f32 v[112:113], v[112:113], v[52:53], v[118:119] op_sel_hi:[1,0,1] neg_hi:[0,0,1]
	v_pk_mul_f32 v[102:103], v[120:121], v[54:55] op_sel:[1,1] op_sel_hi:[0,1]
	v_pk_fma_f32 v[182:183], v[120:121], v[54:55], v[102:103] op_sel_hi:[1,0,1] neg_hi:[0,0,1]
	v_pk_fma_f32 v[120:121], v[120:121], v[54:55], v[102:103] op_sel_hi:[1,0,1] neg_hi:[0,0,1]
	v_pk_mul_f32 v[184:185], v[128:129], v[90:91] op_sel:[1,1] op_sel_hi:[0,1]
	v_pk_fma_f32 v[110:111], v[128:129], v[90:91], v[184:185] op_sel_hi:[1,0,1] neg_hi:[0,0,1]
	v_pk_fma_f32 v[128:129], v[128:129], v[90:91], v[184:185] op_sel_hi:[1,0,1] neg_hi:[0,0,1]
	s_nop 1
	v_permlane32_swap_b32_e32 v104, v186
	v_permlane32_swap_b32_e32 v105, v187
	v_permlane32_swap_b32_e32 v112, v188
	v_permlane32_swap_b32_e32 v113, v189
	v_permlane32_swap_b32_e32 v120, v182
	v_permlane32_swap_b32_e32 v121, v183
	v_permlane32_swap_b32_e32 v128, v110
	v_permlane32_swap_b32_e32 v129, v111
	v_pk_fma_f32 v[104:105], v[186:187], v[190:191], v[104:105] op_sel_hi:[1,0,1]
	ds_write_b64 v198, v[104:105] offset:64
	v_pk_fma_f32 v[112:113], v[188:189], v[190:191], v[112:113] op_sel_hi:[1,0,1]
	ds_write_b64 v198, v[112:113] offset:72
	v_pk_fma_f32 v[120:121], v[182:183], v[190:191], v[120:121] op_sel_hi:[1,0,1]
	ds_write_b64 v198, v[120:121] offset:80
	v_pk_fma_f32 v[128:129], v[110:111], v[190:191], v[128:129] op_sel_hi:[1,0,1]
	ds_write_b64 v198, v[128:129] offset:88
	v_pk_mul_f32 v[102:103], v[106:107], v[92:93] op_sel:[1,1] op_sel_hi:[0,1]
	v_pk_fma_f32 v[168:169], v[106:107], v[92:93], v[102:103] op_sel_hi:[1,0,1] neg_hi:[0,0,1]
	v_pk_fma_f32 v[106:107], v[106:107], v[92:93], v[102:103] op_sel_hi:[1,0,1] neg_hi:[0,0,1]
	v_pk_mul_f32 v[184:185], v[114:115], v[94:95] op_sel:[1,1] op_sel_hi:[0,1]
	v_pk_fma_f32 v[180:181], v[114:115], v[94:95], v[184:185] op_sel_hi:[1,0,1] neg_hi:[0,0,1]
	v_pk_fma_f32 v[114:115], v[114:115], v[94:95], v[184:185] op_sel_hi:[1,0,1] neg_hi:[0,0,1]
	v_pk_mul_f32 v[186:187], v[122:123], v[96:97] op_sel:[1,1] op_sel_hi:[0,1]
	v_pk_fma_f32 v[126:127], v[122:123], v[96:97], v[186:187] op_sel_hi:[1,0,1] neg_hi:[0,0,1]
	v_pk_fma_f32 v[122:123], v[122:123], v[96:97], v[186:187] op_sel_hi:[1,0,1] neg_hi:[0,0,1]
	v_pk_mul_f32 v[188:189], v[130:131], v[98:99] op_sel:[1,1] op_sel_hi:[0,1]
	v_pk_fma_f32 v[118:119], v[130:131], v[98:99], v[188:189] op_sel_hi:[1,0,1] neg_hi:[0,0,1]
	v_pk_fma_f32 v[130:131], v[130:131], v[98:99], v[188:189] op_sel_hi:[1,0,1] neg_hi:[0,0,1]
	s_nop 1
	v_permlane32_swap_b32_e32 v106, v168
	v_permlane32_swap_b32_e32 v107, v169
	v_permlane32_swap_b32_e32 v114, v180
	v_permlane32_swap_b32_e32 v115, v181
	v_permlane32_swap_b32_e32 v122, v126
	v_permlane32_swap_b32_e32 v123, v127
	v_permlane32_swap_b32_e32 v130, v118
	v_permlane32_swap_b32_e32 v131, v119
	v_pk_fma_f32 v[106:107], v[168:169], v[190:191], v[106:107] op_sel_hi:[1,0,1]
	ds_write_b64 v198, v[106:107] offset:96
	v_pk_fma_f32 v[114:115], v[180:181], v[190:191], v[114:115] op_sel_hi:[1,0,1]
	ds_write_b64 v198, v[114:115] offset:104
	v_pk_fma_f32 v[122:123], v[126:127], v[190:191], v[122:123] op_sel_hi:[1,0,1]
	ds_write_b64 v198, v[122:123] offset:112
	v_pk_fma_f32 v[130:131], v[118:119], v[190:191], v[130:131] op_sel_hi:[1,0,1]
	ds_write_b64 v198, v[130:131] offset:120
	s_waitcnt lgkmcnt(0)
	ds_read_b64 v[100:101], v5
	ds_read_b64 v[108:109], v5 offset:264
	ds_read_b64 v[182:183], v56 offset:256
	ds_read_b64 v[116:117], v5 offset:528
	ds_read_b64 v[110:111], v56 offset:512
	ds_read_b64 v[124:125], v5 offset:792
	ds_read_b64 v[102:103], v56 offset:768
	ds_read_b64 v[178:179], v5 offset:1056
	ds_read_b64 v[184:185], v56 offset:1024
	ds_read_b64 v[176:177], v5 offset:1320
	ds_read_b64 v[186:187], v56 offset:1280
	s_waitcnt lgkmcnt(8)
; #define LAS __attribute__((address_space(3)))
; __device__ __forceinline__ f32x2 cmulc(f32x2 a, f32x2 b) { return (f32x2){a.x * b.x + a.y * b.y, a.y * b.x - a.x * b.y}; }
; __device__ __forceinline__ void fft_inv2(LAS f32x2* B, const LAS f32x2* TW2, int tid) {
;     asm volatile("" : "+v"(tid));
;     const int b = tid >> 5, n2 = tid & 31, base = 512 * b + n2; f32x2 x[16];
;     x[0] = B[fpad(base)];
; #pragma unroll
;     for (int k = 1; k < 16; ++k) x[k] = cmulc(B[fpad(base + 32 * k)], TW2[k * 32 + n2]);
;     dft16<true>(x);
; #pragma unroll
;     for (int r = 0; r < 16; ++r) B[fpad(base + 32 * r)] = x[r];
; }
	v_pk_mul_f32 v[188:189], v[108:109], v[182:183] op_sel:[1,1] op_sel_hi:[0,1]
	v_pk_fma_f32 v[108:109], v[108:109], v[182:183], v[188:189] op_sel_hi:[1,0,1] neg_hi:[0,0,1]
	s_waitcnt lgkmcnt(6)
	v_pk_mul_f32 v[168:169], v[116:117], v[110:111] op_sel:[1,1] op_sel_hi:[0,1]
	v_pk_fma_f32 v[116:117], v[116:117], v[110:111], v[168:169] op_sel_hi:[1,0,1] neg_hi:[0,0,1]
	s_waitcnt lgkmcnt(4)
	v_pk_mul_f32 v[180:181], v[124:125], v[102:103] op_sel:[1,1] op_sel_hi:[0,1]
	v_pk_fma_f32 v[124:125], v[124:125], v[102:103], v[180:181] op_sel_hi:[1,0,1] neg_hi:[0,0,1]
	s_waitcnt lgkmcnt(2)
	v_pk_mul_f32 v[126:127], v[178:179], v[184:185] op_sel:[1,1] op_sel_hi:[0,1]
	v_pk_fma_f32 v[178:179], v[178:179], v[184:185], v[126:127] op_sel_hi:[1,0,1] neg_hi:[0,0,1]
	s_waitcnt lgkmcnt(0)
	v_pk_mul_f32 v[118:119], v[176:177], v[186:187] op_sel:[1,1] op_sel_hi:[0,1]
	v_pk_fma_f32 v[176:177], v[176:177], v[186:187], v[118:119] op_sel_hi:[1,0,1] neg_hi:[0,0,1]
	ds_read_b64 v[166:167], v5 offset:1584
	ds_read_b64 v[188:189], v56 offset:1536
	ds_read_b64 v[174:175], v5 offset:1848
	ds_read_b64 v[168:169], v56 offset:1792
	ds_read_b64 v[104:105], v5 offset:2112
	ds_read_b64 v[180:181], v56 offset:2048
	ds_read_b64 v[112:113], v5 offset:2376
	ds_read_b64 v[126:127], v56 offset:2304
	ds_read_b64 v[120:121], v5 offset:2640
	ds_read_b64 v[118:119], v56 offset:2560
	s_waitcnt lgkmcnt(8)
	v_pk_mul_f32 v[182:183], v[166:167], v[188:189] op_sel:[1,1] op_sel_hi:[0,1]
	v_pk_fma_f32 v[166:167], v[166:167], v[188:189], v[182:183] op_sel_hi:[1,0,1] neg_hi:[0,0,1]
	s_waitcnt lgkmcnt(6)
	v_pk_mul_f32 v[110:111], v[174:175], v[168:169] op_sel:[1,1] op_sel_hi:[0,1]
	v_pk_fma_f32 v[174:175], v[174:175], v[168:169], v[110:111] op_sel_hi:[1,0,1] neg_hi:[0,0,1]
	s_waitcnt lgkmcnt(4)
	v_pk_mul_f32 v[102:103], v[104:105], v[180:181] op_sel:[1,1] op_sel_hi:[0,1]
	v_pk_fma_f32 v[104:105], v[104:105], v[180:181], v[102:103] op_sel_hi:[1,0,1] neg_hi:[0,0,1]
	s_waitcnt lgkmcnt(2)
	v_pk_mul_f32 v[184:185], v[112:113], v[126:127] op_sel:[1,1] op_sel_hi:[0,1]
	v_pk_fma_f32 v[112:113], v[112:113], v[126:127], v[184:185] op_sel_hi:[1,0,1] neg_hi:[0,0,1]
	s_waitcnt lgkmcnt(0)
	v_pk_mul_f32 v[186:187], v[120:121], v[118:119] op_sel:[1,1] op_sel_hi:[0,1]
	v_pk_fma_f32 v[120:121], v[120:121], v[118:119], v[186:187] op_sel_hi:[1,0,1] neg_hi:[0,0,1]
	ds_read_b64 v[128:129], v5 offset:2904
	ds_read_b64 v[182:183], v56 offset:2816
	ds_read_b64 v[106:107], v5 offset:3168
	ds_read_b64 v[110:111], v56 offset:3072
	ds_read_b64 v[114:115], v5 offset:3432
	ds_read_b64 v[102:103], v56 offset:3328
	ds_read_b64 v[122:123], v5 offset:3696
	ds_read_b64 v[184:185], v56 offset:3584
	ds_read_b64 v[130:131], v5 offset:3960
	ds_read_b64 v[186:187], v56 offset:3840
	s_waitcnt lgkmcnt(8)
	v_pk_mul_f32 v[188:189], v[128:129], v[182:183] op_sel:[1,1] op_sel_hi:[0,1]
	v_pk_fma_f32 v[128:129], v[128:129], v[182:183], v[188:189] op_sel_hi:[1,0,1] neg_hi:[0,0,1]
	s_waitcnt lgkmcnt(6)
	v_pk_mul_f32 v[168:169], v[106:107], v[110:111] op_sel:[1,1] op_sel_hi:[0,1]
	v_pk_fma_f32 v[106:107], v[106:107], v[110:111], v[168:169] op_sel_hi:[1,0,1] neg_hi:[0,0,1]
	s_waitcnt lgkmcnt(4)
	v_pk_mul_f32 v[180:181], v[114:115], v[102:103] op_sel:[1,1] op_sel_hi:[0,1]
	v_pk_fma_f32 v[114:115], v[114:115], v[102:103], v[180:181] op_sel_hi:[1,0,1] neg_hi:[0,0,1]
	s_waitcnt lgkmcnt(2)
	v_pk_mul_f32 v[126:127], v[122:123], v[184:185] op_sel:[1,1] op_sel_hi:[0,1]
	v_pk_fma_f32 v[122:123], v[122:123], v[184:185], v[126:127] op_sel_hi:[1,0,1] neg_hi:[0,0,1]
	s_waitcnt lgkmcnt(0)
	v_pk_mul_f32 v[118:119], v[130:131], v[186:187] op_sel:[1,1] op_sel_hi:[0,1]
	v_pk_fma_f32 v[130:131], v[130:131], v[186:187], v[118:119] op_sel_hi:[1,0,1] neg_hi:[0,0,1]
	v_pk_add_f32 v[188:189], v[100:101], v[104:105]
	v_pk_add_f32 v[168:169], v[100:101], v[104:105] neg_lo:[0,1] neg_hi:[0,1]
	v_pk_add_f32 v[180:181], v[178:179], v[106:107]
	v_pk_add_f32 v[126:127], v[178:179], v[106:107] neg_lo:[0,1] neg_hi:[0,1]
	v_pk_add_f32 v[100:101], v[188:189], v[180:181]
	v_pk_add_f32 v[104:105], v[188:189], v[180:181] neg_lo:[0,1] neg_hi:[0,1]
	v_pk_add_f32 v[178:179], v[168:169], v[126:127] op_sel:[0,1] op_sel_hi:[1,0] neg_lo:[0,1]
	v_pk_add_f32 v[106:107], v[168:169], v[126:127] op_sel:[0,1] op_sel_hi:[1,0] neg_hi:[0,1]
	v_pk_add_f32 v[118:119], v[108:109], v[112:113]
	v_pk_add_f32 v[182:183], v[108:109], v[112:113] neg_lo:[0,1] neg_hi:[0,1]
	v_pk_add_f32 v[110:111], v[176:177], v[114:115]
	v_pk_add_f32 v[102:103], v[176:177], v[114:115] neg_lo:[0,1] neg_hi:[0,1]
	v_pk_add_f32 v[108:109], v[118:119], v[110:111]
	v_pk_add_f32 v[112:113], v[118:119], v[110:111] neg_lo:[0,1] neg_hi:[0,1]
	v_pk_add_f32 v[176:177], v[182:183], v[102:103] op_sel:[0,1] op_sel_hi:[1,0] neg_lo:[0,1]
	v_pk_add_f32 v[114:115], v[182:183], v[102:103] op_sel:[0,1] op_sel_hi:[1,0] neg_hi:[0,1]
	v_pk_add_f32 v[184:185], v[116:117], v[120:121]
	v_pk_add_f32 v[186:187], v[116:117], v[120:121] neg_lo:[0,1] neg_hi:[0,1]
	v_pk_add_f32 v[188:189], v[166:167], v[122:123]
	v_pk_add_f32 v[168:169], v[166:167], v[122:123] neg_lo:[0,1] neg_hi:[0,1]
	v_pk_add_f32 v[116:117], v[184:185], v[188:189]
	v_pk_add_f32 v[120:121], v[184:185], v[188:189] neg_lo:[0,1] neg_hi:[0,1]
	v_pk_add_f32 v[166:167], v[186:187], v[168:169] op_sel:[0,1] op_sel_hi:[1,0] neg_lo:[0,1]
	v_pk_add_f32 v[122:123], v[186:187], v[168:169] op_sel:[0,1] op_sel_hi:[1,0] neg_hi:[0,1]
	v_pk_add_f32 v[180:181], v[124:125], v[128:129]
	v_pk_add_f32 v[126:127], v[124:125], v[128:129] neg_lo:[0,1] neg_hi:[0,1]
	v_pk_add_f32 v[118:119], v[174:175], v[130:131]
	v_pk_add_f32 v[182:183], v[174:175], v[130:131] neg_lo:[0,1] neg_hi:[0,1]
	v_pk_add_f32 v[124:125], v[180:181], v[118:119]
; #define LAS __attribute__((address_space(3)))
; __device__ __forceinline__ f32x2 cmulc(f32x2 a, f32x2 b) { return (f32x2){a.x * b.x + a.y * b.y, a.y * b.x - a.x * b.y}; }
; __device__ __forceinline__ void fft_inv2(LAS f32x2* B, const LAS f32x2* TW2, int tid) {
;     asm volatile("" : "+v"(tid));
;     const int b = tid >> 5, n2 = tid & 31, base = 512 * b + n2; f32x2 x[16];
;     x[0] = B[fpad(base)];
; #pragma unroll
;     for (int k = 1; k < 16; ++k) x[k] = cmulc(B[fpad(base + 32 * k)], TW2[k * 32 + n2]);
;     dft16<true>(x);
; #pragma unroll
;     for (int r = 0; r < 16; ++r) B[fpad(base + 32 * r)] = x[r];
; }
	v_pk_add_f32 v[128:129], v[180:181], v[118:119] neg_lo:[0,1] neg_hi:[0,1]
	v_pk_add_f32 v[174:175], v[126:127], v[182:183] op_sel:[0,1] op_sel_hi:[1,0] neg_lo:[0,1]
	v_pk_add_f32 v[130:131], v[126:127], v[182:183] op_sel:[0,1] op_sel_hi:[1,0] neg_hi:[0,1]
	v_pk_mul_f32 v[110:111], v[176:177], s[68:69] op_sel:[1,1] op_sel_hi:[0,1]
	v_pk_fma_f32 v[176:177], v[176:177], s[68:69], v[110:111] op_sel_hi:[1,0,1] neg_hi:[0,0,1]
	v_pk_mul_f32 v[102:103], v[166:167], s[84:85] op_sel:[1,1] op_sel_hi:[0,1]
	v_pk_fma_f32 v[166:167], v[166:167], s[84:85], v[102:103] op_sel_hi:[1,0,1] neg_hi:[0,0,1]
	v_pk_mul_f32 v[184:185], v[174:175], s[88:89] op_sel:[1,1] op_sel_hi:[0,1]
	v_pk_fma_f32 v[174:175], v[174:175], s[88:89], v[184:185] op_sel_hi:[1,0,1] neg_hi:[0,0,1]
	v_pk_mul_f32 v[186:187], v[112:113], s[84:85] op_sel:[1,1] op_sel_hi:[0,1]
	v_pk_fma_f32 v[112:113], v[112:113], s[84:85], v[186:187] op_sel_hi:[1,0,1] neg_hi:[0,0,1]
	v_pk_mul_f32 v[188:189], v[128:129], s[90:91] op_sel:[1,1] op_sel_hi:[0,1]
	v_pk_fma_f32 v[128:129], v[128:129], s[90:91], v[188:189] op_sel_hi:[1,0,1] neg_hi:[0,0,1]
	v_pk_mul_f32 v[168:169], v[114:115], s[88:89] op_sel:[1,1] op_sel_hi:[0,1]
	v_pk_fma_f32 v[114:115], v[114:115], s[88:89], v[168:169] op_sel_hi:[1,0,1] neg_hi:[0,0,1]
	v_pk_mul_f32 v[180:181], v[122:123], s[90:91] op_sel:[1,1] op_sel_hi:[0,1]
	v_pk_fma_f32 v[122:123], v[122:123], s[90:91], v[180:181] op_sel_hi:[1,0,1] neg_hi:[0,0,1]
	v_pk_mul_f32 v[126:127], v[130:131], s[98:99] op_sel:[1,1] op_sel_hi:[0,1]
	v_pk_fma_f32 v[130:131], v[130:131], s[98:99], v[126:127] op_sel_hi:[1,0,1] neg_hi:[0,0,1]
	v_pk_add_f32 v[118:119], v[100:101], v[116:117]
	v_pk_add_f32 v[182:183], v[100:101], v[116:117] neg_lo:[0,1] neg_hi:[0,1]
	v_pk_add_f32 v[110:111], v[108:109], v[124:125]
	v_pk_add_f32 v[102:103], v[108:109], v[124:125] neg_lo:[0,1] neg_hi:[0,1]
	v_pk_add_f32 v[100:101], v[118:119], v[110:111]
	v_pk_add_f32 v[116:117], v[118:119], v[110:111] neg_lo:[0,1] neg_hi:[0,1]
	v_pk_add_f32 v[108:109], v[182:183], v[102:103] op_sel:[0,1] op_sel_hi:[1,0] neg_lo:[0,1]
	v_pk_add_f32 v[124:125], v[182:183], v[102:103] op_sel:[0,1] op_sel_hi:[1,0] neg_hi:[0,1]
	v_pk_add_f32 v[184:185], v[178:179], v[166:167]
	v_pk_add_f32 v[186:187], v[178:179], v[166:167] neg_lo:[0,1] neg_hi:[0,1]
	v_pk_add_f32 v[188:189], v[176:177], v[174:175]
	v_pk_add_f32 v[168:169], v[176:177], v[174:175] neg_lo:[0,1] neg_hi:[0,1]
	v_pk_add_f32 v[178:179], v[184:185], v[188:189]
	v_pk_add_f32 v[166:167], v[184:185], v[188:189] neg_lo:[0,1] neg_hi:[0,1]
	v_pk_add_f32 v[176:177], v[186:187], v[168:169] op_sel:[0,1] op_sel_hi:[1,0] neg_lo:[0,1]
	v_pk_add_f32 v[174:175], v[186:187], v[168:169] op_sel:[0,1] op_sel_hi:[1,0] neg_hi:[0,1]
	v_pk_add_f32 v[180:181], v[104:105], v[120:121] op_sel:[0,1] op_sel_hi:[1,0] neg_lo:[0,1]
	v_pk_add_f32 v[126:127], v[104:105], v[120:121] op_sel:[0,1] op_sel_hi:[1,0] neg_hi:[0,1]
	v_pk_add_f32 v[118:119], v[112:113], v[128:129]
	v_pk_add_f32 v[182:183], v[112:113], v[128:129] neg_lo:[0,1] neg_hi:[0,1]
	v_pk_add_f32 v[104:105], v[180:181], v[118:119]
	v_pk_add_f32 v[120:121], v[180:181], v[118:119] neg_lo:[0,1] neg_hi:[0,1]
	v_pk_add_f32 v[112:113], v[126:127], v[182:183] op_sel:[0,1] op_sel_hi:[1,0] neg_lo:[0,1]
	v_pk_add_f32 v[128:129], v[126:127], v[182:183] op_sel:[0,1] op_sel_hi:[1,0] neg_hi:[0,1]
	v_pk_add_f32 v[110:111], v[106:107], v[122:123]
	v_pk_add_f32 v[102:103], v[106:107], v[122:123] neg_lo:[0,1] neg_hi:[0,1]
	v_pk_add_f32 v[184:185], v[114:115], v[130:131]
	v_pk_add_f32 v[186:187], v[114:115], v[130:131] neg_lo:[0,1] neg_hi:[0,1]
	v_pk_add_f32 v[106:107], v[110:111], v[184:185]
	v_pk_add_f32 v[122:123], v[110:111], v[184:185] neg_lo:[0,1] neg_hi:[0,1]
	v_pk_add_f32 v[114:115], v[102:103], v[186:187] op_sel:[0,1] op_sel_hi:[1,0] neg_lo:[0,1]
	v_pk_add_f32 v[130:131], v[102:103], v[186:187] op_sel:[0,1] op_sel_hi:[1,0] neg_hi:[0,1]
	ds_write_b64 v5, v[100:101]
	ds_write_b64 v5, v[178:179] offset:264
	ds_write_b64 v5, v[104:105] offset:528
	ds_write_b64 v5, v[106:107] offset:792
	ds_write_b64 v5, v[108:109] offset:1056
	ds_write_b64 v5, v[176:177] offset:1320
	ds_write_b64 v5, v[112:113] offset:1584
	ds_write_b64 v5, v[114:115] offset:1848
	ds_write_b64 v5, v[116:117] offset:2112
	ds_write_b64 v5, v[166:167] offset:2376
	ds_write_b64 v5, v[120:121] offset:2640
	ds_write_b64 v5, v[122:123] offset:2904
	ds_write_b64 v5, v[124:125] offset:3168
	ds_write_b64 v5, v[174:175] offset:3432
	ds_write_b64 v5, v[128:129] offset:3696
	ds_write_b64 v5, v[130:131] offset:3960
	s_waitcnt lgkmcnt(0)
	s_barrier
; #define LAS __attribute__((address_space(3)))
; __device__ __forceinline__ f32x2 cmulc(f32x2 a, f32x2 b) { return (f32x2){a.x * b.x + a.y * b.y, a.y * b.x - a.x * b.y}; }
; __device__ __forceinline__ void dft16_inv_lo(f32x2 (&x)[16]) {
;     constexpr float C1 = 0.92387953251128674f, S1 = 0.38268343236508977f, C2 = 0.70710678118654752f;
; #pragma unroll
;     for (int b = 0; b < 4; ++b) dft4<true>(x[b], x[4 + b], x[8 + b], x[12 + b]);
;     const f32x2 w1 = {C1, -S1}, w2 = {C2, -C2}, w3 = {S1, -C1}, w4 = {0.f, -1.f}, w6 = {-C2, -C2}, w9 = {-C1, S1};
;     x[5] = cmulc(x[5], w1); x[6] = cmulc(x[6], w2); x[7] = cmulc(x[7], w3);
;     x[9] = cmulc(x[9], w2); x[10] = cmulc(x[10], w4); x[11] = cmulc(x[11], w6);
;     x[13] = cmulc(x[13], w3); x[14] = cmulc(x[14], w6); x[15] = cmulc(x[15], w9);
;     f32x2 y[8];
; #pragma unroll
;     for (int c = 0; c < 4; ++c) { const f32x2 t0 = x[4 * c] + x[4 * c + 2], t1 = x[4 * c] - x[4 * c + 2], t2 = x[4 * c + 1] + x[4 * c + 3], t3 = x[4 * c + 1] - x[4 * c + 3];
;         y[c] = t0 + t2; y[4 + c] = t1 + (f32x2){-t3.y, t3.x}; }
; #pragma unroll
;     for (int k = 0; k < 8; ++k) x[k] = y[k];
; }
; __device__ __forceinline__ void fft_inv1(f32x2 (&x)[16], const LAS f32x2* B, int n2, const f32x2 (&w)[16]) {
;     asm volatile("" : "+v"(n2));
;     x[0] = B[fpad(n2)];
; #pragma unroll
;     for (int k = 1; k < 16; ++k) x[k] = cmulc(B[fpad(512 * k + n2)], w[k]);
;     dft16_inv_lo(x);
; }
	ds_read_b64 v[100:101], v3
	ds_read_b64 v[108:109], v3 offset:16896
	ds_read_b64 v[116:117], v3 offset:33792
	ds_read_b64 v[124:125], v3 offset:50688
	ds_read_b64 v[178:179], v3 offset:4224
	ds_read_b64 v[176:177], v3 offset:21120
	ds_read_b64 v[166:167], v3 offset:38016
	ds_read_b64 v[174:175], v3 offset:54912
	ds_read_b64 v[104:105], v3 offset:8448
	ds_read_b64 v[112:113], v3 offset:25344
	ds_read_b64 v[120:121], v3 offset:42240
	ds_read_b64 v[128:129], v3 offset:59136
	ds_read_b64 v[106:107], v3 offset:12672
	ds_read_b64 v[114:115], v3 offset:29568
	ds_read_b64 v[122:123], v3 offset:46464
	ds_read_b64 v[130:131], v3 offset:63360
	s_waitcnt lgkmcnt(14)
	v_pk_mul_f32 v[188:189], v[108:109], v[12:13] op_sel:[1,1] op_sel_hi:[0,1]
	v_pk_fma_f32 v[108:109], v[108:109], v[12:13], v[188:189] op_sel_hi:[1,0,1] neg_hi:[0,0,1]
	s_waitcnt lgkmcnt(13)
	v_pk_mul_f32 v[168:169], v[116:117], v[20:21] op_sel:[1,1] op_sel_hi:[0,1]
	v_pk_fma_f32 v[116:117], v[116:117], v[20:21], v[168:169] op_sel_hi:[1,0,1] neg_hi:[0,0,1]
	s_waitcnt lgkmcnt(12)
	v_pk_mul_f32 v[180:181], v[124:125], v[28:29] op_sel:[1,1] op_sel_hi:[0,1]
	v_pk_fma_f32 v[124:125], v[124:125], v[28:29], v[180:181] op_sel_hi:[1,0,1] neg_hi:[0,0,1]
	s_waitcnt lgkmcnt(11)
	v_pk_mul_f32 v[126:127], v[178:179], v[6:7] op_sel:[1,1] op_sel_hi:[0,1]
	v_pk_fma_f32 v[178:179], v[178:179], v[6:7], v[126:127] op_sel_hi:[1,0,1] neg_hi:[0,0,1]
	s_waitcnt lgkmcnt(10)
	v_pk_mul_f32 v[118:119], v[176:177], v[14:15] op_sel:[1,1] op_sel_hi:[0,1]
	v_pk_fma_f32 v[176:177], v[176:177], v[14:15], v[118:119] op_sel_hi:[1,0,1] neg_hi:[0,0,1]
	s_waitcnt lgkmcnt(9)
	v_pk_mul_f32 v[182:183], v[166:167], v[22:23] op_sel:[1,1] op_sel_hi:[0,1]
	v_pk_fma_f32 v[166:167], v[166:167], v[22:23], v[182:183] op_sel_hi:[1,0,1] neg_hi:[0,0,1]
	s_waitcnt lgkmcnt(8)
	v_pk_mul_f32 v[110:111], v[174:175], v[30:31] op_sel:[1,1] op_sel_hi:[0,1]
	v_pk_fma_f32 v[174:175], v[174:175], v[30:31], v[110:111] op_sel_hi:[1,0,1] neg_hi:[0,0,1]
	s_waitcnt lgkmcnt(7)
	v_pk_mul_f32 v[102:103], v[104:105], v[8:9] op_sel:[1,1] op_sel_hi:[0,1]
	v_pk_fma_f32 v[104:105], v[104:105], v[8:9], v[102:103] op_sel_hi:[1,0,1] neg_hi:[0,0,1]
	s_waitcnt lgkmcnt(6)
	v_pk_mul_f32 v[184:185], v[112:113], v[16:17] op_sel:[1,1] op_sel_hi:[0,1]
	v_pk_fma_f32 v[112:113], v[112:113], v[16:17], v[184:185] op_sel_hi:[1,0,1] neg_hi:[0,0,1]
	s_waitcnt lgkmcnt(5)
	v_pk_mul_f32 v[186:187], v[120:121], v[24:25] op_sel:[1,1] op_sel_hi:[0,1]
	v_pk_fma_f32 v[120:121], v[120:121], v[24:25], v[186:187] op_sel_hi:[1,0,1] neg_hi:[0,0,1]
	s_waitcnt lgkmcnt(4)
	v_pk_mul_f32 v[188:189], v[128:129], v[32:33] op_sel:[1,1] op_sel_hi:[0,1]
	v_pk_fma_f32 v[128:129], v[128:129], v[32:33], v[188:189] op_sel_hi:[1,0,1] neg_hi:[0,0,1]
	s_waitcnt lgkmcnt(3)
	v_pk_mul_f32 v[168:169], v[106:107], v[10:11] op_sel:[1,1] op_sel_hi:[0,1]
	v_pk_fma_f32 v[106:107], v[106:107], v[10:11], v[168:169] op_sel_hi:[1,0,1] neg_hi:[0,0,1]
	s_waitcnt lgkmcnt(2)
	v_pk_mul_f32 v[180:181], v[114:115], v[18:19] op_sel:[1,1] op_sel_hi:[0,1]
	v_pk_fma_f32 v[114:115], v[114:115], v[18:19], v[180:181] op_sel_hi:[1,0,1] neg_hi:[0,0,1]
	s_waitcnt lgkmcnt(1)
	v_pk_mul_f32 v[126:127], v[122:123], v[26:27] op_sel:[1,1] op_sel_hi:[0,1]
	v_pk_fma_f32 v[122:123], v[122:123], v[26:27], v[126:127] op_sel_hi:[1,0,1] neg_hi:[0,0,1]
	s_waitcnt lgkmcnt(0)
	v_pk_mul_f32 v[118:119], v[130:131], v[34:35] op_sel:[1,1] op_sel_hi:[0,1]
	v_pk_fma_f32 v[130:131], v[130:131], v[34:35], v[118:119] op_sel_hi:[1,0,1] neg_hi:[0,0,1]
	v_pk_add_f32 v[182:183], v[100:101], v[116:117]
	v_pk_add_f32 v[110:111], v[100:101], v[116:117] neg_lo:[0,1] neg_hi:[0,1]
	v_pk_add_f32 v[102:103], v[108:109], v[124:125]
	v_pk_add_f32 v[184:185], v[108:109], v[124:125] neg_lo:[0,1] neg_hi:[0,1]
	v_pk_add_f32 v[100:101], v[182:183], v[102:103]
	v_pk_add_f32 v[116:117], v[182:183], v[102:103] neg_lo:[0,1] neg_hi:[0,1]
	v_pk_add_f32 v[108:109], v[110:111], v[184:185] op_sel:[0,1] op_sel_hi:[1,0] neg_lo:[0,1]
	v_pk_add_f32 v[124:125], v[110:111], v[184:185] op_sel:[0,1] op_sel_hi:[1,0] neg_hi:[0,1]
	v_pk_add_f32 v[186:187], v[178:179], v[166:167]
	v_pk_add_f32 v[188:189], v[178:179], v[166:167] neg_lo:[0,1] neg_hi:[0,1]
	v_pk_add_f32 v[168:169], v[176:177], v[174:175]
	v_pk_add_f32 v[180:181], v[176:177], v[174:175] neg_lo:[0,1] neg_hi:[0,1]
	v_pk_add_f32 v[178:179], v[186:187], v[168:169]
	v_pk_add_f32 v[166:167], v[186:187], v[168:169] neg_lo:[0,1] neg_hi:[0,1]
	v_pk_add_f32 v[176:177], v[188:189], v[180:181] op_sel:[0,1] op_sel_hi:[1,0] neg_lo:[0,1]
	v_pk_add_f32 v[174:175], v[188:189], v[180:181] op_sel:[0,1] op_sel_hi:[1,0] neg_hi:[0,1]
	v_pk_add_f32 v[126:127], v[104:105], v[120:121]
	v_pk_add_f32 v[118:119], v[104:105], v[120:121] neg_lo:[0,1] neg_hi:[0,1]
	v_pk_add_f32 v[182:183], v[112:113], v[128:129]
	v_pk_add_f32 v[110:111], v[112:113], v[128:129] neg_lo:[0,1] neg_hi:[0,1]
	v_pk_add_f32 v[104:105], v[126:127], v[182:183]
	v_pk_add_f32 v[120:121], v[126:127], v[182:183] neg_lo:[0,1] neg_hi:[0,1]
	v_pk_add_f32 v[112:113], v[118:119], v[110:111] op_sel:[0,1] op_sel_hi:[1,0] neg_lo:[0,1]
	v_pk_add_f32 v[128:129], v[118:119], v[110:111] op_sel:[0,1] op_sel_hi:[1,0] neg_hi:[0,1]
	v_pk_add_f32 v[102:103], v[106:107], v[122:123]
	v_pk_add_f32 v[184:185], v[106:107], v[122:123] neg_lo:[0,1] neg_hi:[0,1]
	v_pk_add_f32 v[186:187], v[114:115], v[130:131]
	v_pk_add_f32 v[188:189], v[114:115], v[130:131] neg_lo:[0,1] neg_hi:[0,1]
	v_pk_add_f32 v[106:107], v[102:103], v[186:187]
	v_pk_add_f32 v[122:123], v[102:103], v[186:187] neg_lo:[0,1] neg_hi:[0,1]
	v_pk_add_f32 v[114:115], v[184:185], v[188:189] op_sel:[0,1] op_sel_hi:[1,0] neg_lo:[0,1]
; __device__ __forceinline__ f32x2 cmulc(f32x2 a, f32x2 b) { return (f32x2){a.x * b.x + a.y * b.y, a.y * b.x - a.x * b.y}; }
; #define WG_SYNC() do { asm volatile("s_waitcnt lgkmcnt(0)" ::: "memory"); __builtin_amdgcn_s_barrier(); asm volatile("" ::: "memory"); } while (0)
; __device__ __forceinline__ void dft16_inv_lo(f32x2 (&x)[16]) {
;     constexpr float C1 = 0.92387953251128674f, S1 = 0.38268343236508977f, C2 = 0.70710678118654752f;
; #pragma unroll
;     for (int b = 0; b < 4; ++b) dft4<true>(x[b], x[4 + b], x[8 + b], x[12 + b]);
;     const f32x2 w1 = {C1, -S1}, w2 = {C2, -C2}, w3 = {S1, -C1}, w4 = {0.f, -1.f}, w6 = {-C2, -C2}, w9 = {-C1, S1};
;     x[5] = cmulc(x[5], w1); x[6] = cmulc(x[6], w2); x[7] = cmulc(x[7], w3);
;     x[9] = cmulc(x[9], w2); x[10] = cmulc(x[10], w4); x[11] = cmulc(x[11], w6);
;     x[13] = cmulc(x[13], w3); x[14] = cmulc(x[14], w6); x[15] = cmulc(x[15], w9);
;     f32x2 y[8];
; #pragma unroll
;     for (int c = 0; c < 4; ++c) { const f32x2 t0 = x[4 * c] + x[4 * c + 2], t1 = x[4 * c] - x[4 * c + 2], t2 = x[4 * c + 1] + x[4 * c + 3], t3 = x[4 * c + 1] - x[4 * c + 3];
;         y[c] = t0 + t2; y[4 + c] = t1 + (f32x2){-t3.y, t3.x}; }
; #pragma unroll
;     for (int k = 0; k < 8; ++k) x[k] = y[k];
; }
; __device__ __forceinline__ void hyena_fft(LAS unsigned char* lds, int layer, int G, const int wave_s) {
;     ...
;             { const float fb0 = fbias[c];
; #pragma unroll
;               for (int r = 0; r < 8; ++r) { uz[r][0] = ux[r][0] * (x[r].x + fb0 * uz[r][0]); uz[r][1] = ux[r][1] * (x[r].y + fb0 * uz[r][1]); } }
;             WG_SYNC();
;             hy_stage(pl0, PHY, (HY / 4) + unit, jc, tid);
	v_pk_add_f32 v[130:131], v[184:185], v[188:189] op_sel:[0,1] op_sel_hi:[1,0] neg_hi:[0,1]
	v_pk_mul_f32 v[168:169], v[176:177], s[68:69] op_sel:[1,1] op_sel_hi:[0,1]
	v_pk_fma_f32 v[176:177], v[176:177], s[68:69], v[168:169] op_sel_hi:[1,0,1] neg_hi:[0,0,1]
	v_pk_mul_f32 v[180:181], v[112:113], s[84:85] op_sel:[1,1] op_sel_hi:[0,1]
	v_pk_fma_f32 v[112:113], v[112:113], s[84:85], v[180:181] op_sel_hi:[1,0,1] neg_hi:[0,0,1]
	v_pk_mul_f32 v[126:127], v[114:115], s[88:89] op_sel:[1,1] op_sel_hi:[0,1]
	v_pk_fma_f32 v[114:115], v[114:115], s[88:89], v[126:127] op_sel_hi:[1,0,1] neg_hi:[0,0,1]
	v_pk_mul_f32 v[118:119], v[166:167], s[84:85] op_sel:[1,1] op_sel_hi:[0,1]
	v_pk_fma_f32 v[166:167], v[166:167], s[84:85], v[118:119] op_sel_hi:[1,0,1] neg_hi:[0,0,1]
	v_pk_mul_f32 v[182:183], v[122:123], s[90:91] op_sel:[1,1] op_sel_hi:[0,1]
	v_pk_fma_f32 v[122:123], v[122:123], s[90:91], v[182:183] op_sel_hi:[1,0,1] neg_hi:[0,0,1]
	v_pk_mul_f32 v[110:111], v[174:175], s[88:89] op_sel:[1,1] op_sel_hi:[0,1]
	v_pk_fma_f32 v[174:175], v[174:175], s[88:89], v[110:111] op_sel_hi:[1,0,1] neg_hi:[0,0,1]
	v_pk_mul_f32 v[102:103], v[128:129], s[90:91] op_sel:[1,1] op_sel_hi:[0,1]
	v_pk_fma_f32 v[128:129], v[128:129], s[90:91], v[102:103] op_sel_hi:[1,0,1] neg_hi:[0,0,1]
	v_pk_mul_f32 v[184:185], v[130:131], s[98:99] op_sel:[1,1] op_sel_hi:[0,1]
	v_pk_fma_f32 v[130:131], v[130:131], s[98:99], v[184:185] op_sel_hi:[1,0,1] neg_hi:[0,0,1]
	v_pk_add_f32 v[186:187], v[100:101], v[104:105]
	v_pk_add_f32 v[188:189], v[100:101], v[104:105] neg_lo:[0,1] neg_hi:[0,1]
	v_pk_add_f32 v[168:169], v[178:179], v[106:107]
	v_pk_add_f32 v[180:181], v[178:179], v[106:107] neg_lo:[0,1] neg_hi:[0,1]
	v_pk_add_f32 v[100:101], v[186:187], v[168:169]
	v_pk_add_f32 v[178:179], v[188:189], v[180:181] op_sel:[0,1] op_sel_hi:[1,0] neg_lo:[0,1]
	v_pk_add_f32 v[126:127], v[108:109], v[112:113]
	v_pk_add_f32 v[118:119], v[108:109], v[112:113] neg_lo:[0,1] neg_hi:[0,1]
	v_pk_add_f32 v[182:183], v[176:177], v[114:115]
	v_pk_add_f32 v[110:111], v[176:177], v[114:115] neg_lo:[0,1] neg_hi:[0,1]
	v_pk_add_f32 v[108:109], v[126:127], v[182:183]
	v_pk_add_f32 v[176:177], v[118:119], v[110:111] op_sel:[0,1] op_sel_hi:[1,0] neg_lo:[0,1]
	v_pk_add_f32 v[102:103], v[116:117], v[120:121] op_sel:[0,1] op_sel_hi:[1,0] neg_lo:[0,1]
	v_pk_add_f32 v[184:185], v[116:117], v[120:121] op_sel:[0,1] op_sel_hi:[1,0] neg_hi:[0,1]
	v_pk_add_f32 v[186:187], v[166:167], v[122:123]
	v_pk_add_f32 v[188:189], v[166:167], v[122:123] neg_lo:[0,1] neg_hi:[0,1]
	v_pk_add_f32 v[116:117], v[102:103], v[186:187]
	v_pk_add_f32 v[166:167], v[184:185], v[188:189] op_sel:[0,1] op_sel_hi:[1,0] neg_lo:[0,1]
	v_pk_add_f32 v[168:169], v[124:125], v[128:129]
	v_pk_add_f32 v[180:181], v[124:125], v[128:129] neg_lo:[0,1] neg_hi:[0,1]
	v_pk_add_f32 v[126:127], v[174:175], v[130:131]
	v_pk_add_f32 v[118:119], v[174:175], v[130:131] neg_lo:[0,1] neg_hi:[0,1]
	v_pk_add_f32 v[124:125], v[168:169], v[126:127]
	v_pk_add_f32 v[174:175], v[180:181], v[118:119] op_sel:[0,1] op_sel_hi:[1,0] neg_lo:[0,1]
	s_load_dword s35, s[50:51], 0x0
	s_waitcnt lgkmcnt(0)
	v_mov_b32_e32 v194, s35
	v_pk_fma_f32 v[182:183], v[132:133], v[194:195], v[100:101] op_sel_hi:[1,0,1]
	v_pk_mul_f32 v[132:133], v[148:149], v[182:183]
	v_pk_fma_f32 v[110:111], v[134:135], v[194:195], v[108:109] op_sel_hi:[1,0,1]
	v_pk_mul_f32 v[134:135], v[150:151], v[110:111]
	v_pk_fma_f32 v[102:103], v[136:137], v[194:195], v[116:117] op_sel_hi:[1,0,1]
	v_pk_mul_f32 v[136:137], v[152:153], v[102:103]
	v_pk_fma_f32 v[184:185], v[138:139], v[194:195], v[124:125] op_sel_hi:[1,0,1]
	v_pk_mul_f32 v[138:139], v[154:155], v[184:185]
	v_pk_fma_f32 v[186:187], v[140:141], v[194:195], v[178:179] op_sel_hi:[1,0,1]
	v_pk_mul_f32 v[140:141], v[158:159], v[186:187]
	v_pk_fma_f32 v[188:189], v[142:143], v[194:195], v[176:177] op_sel_hi:[1,0,1]
	v_pk_mul_f32 v[142:143], v[160:161], v[188:189]
	v_pk_fma_f32 v[168:169], v[144:145], v[194:195], v[166:167] op_sel_hi:[1,0,1]
	v_pk_mul_f32 v[144:145], v[162:163], v[168:169]
	v_pk_fma_f32 v[180:181], v[146:147], v[194:195], v[174:175] op_sel_hi:[1,0,1]
	v_pk_mul_f32 v[146:147], v[164:165], v[180:181]
	s_waitcnt lgkmcnt(0)
	s_barrier
	s_waitcnt vmcnt(7)
	v_perm_b32 v126, 0, v58, s15
	v_perm_b32 v127, 0, v60, s15
	ds_write_b64 v206, v[126:127]
	s_waitcnt vmcnt(6)
	v_perm_b32 v118, 0, v62, s15
	v_perm_b32 v119, 0, v64, s15
	ds_write_b64 v206, v[118:119] offset:4096
	s_waitcnt vmcnt(5)
	v_perm_b32 v182, 0, v66, s15
	v_perm_b32 v183, 0, v68, s15
	ds_write_b64 v206, v[182:183] offset:8192
	s_waitcnt vmcnt(4)
	v_perm_b32 v110, 0, v70, s15
	v_perm_b32 v111, 0, v72, s15
	ds_write_b64 v206, v[110:111] offset:12288
	s_waitcnt vmcnt(3)
	v_perm_b32 v102, 0, v74, s15
	v_perm_b32 v103, 0, v76, s15
	ds_write_b64 v206, v[102:103] offset:16384
	s_waitcnt vmcnt(2)
	v_perm_b32 v184, 0, v78, s15
	v_perm_b32 v185, 0, v80, s15
	ds_write_b64 v206, v[184:185] offset:20480
	s_waitcnt vmcnt(1)
	v_perm_b32 v186, 0, v82, s15
	v_perm_b32 v187, 0, v84, s15
	ds_write_b64 v206, v[186:187] offset:24576
	s_waitcnt vmcnt(0)
	v_perm_b32 v188, 0, v86, s15
	v_perm_b32 v189, 0, v88, s15
	ds_write_b64 v206, v[188:189] offset:28672
	s_waitcnt lgkmcnt(0)
	s_barrier
; #define LAS __attribute__((address_space(3)))
; __device__ __forceinline__ void hy_sconv(const LAS float* plane, float w0, float w1, float w2, float cb, int n2, float (&u)[8][2]) {
;     asm volatile("" : "+v"(n2));
; #pragma unroll
;     for (int r = 0; r < 8; ++r)
; #pragma unroll
;         for (int b = 0; b < 2; ++b) { const int t = n2 + 512 * r, row = b * SEQ + t;
;             float a = cb + w1 * plane[row];
;             if (t > 0) a += w0 * plane[row - 1];
;             if (t < SEQ - 1) a += w2 * plane[row + 1];
;             u[r][b] = a; }
; }
	v_mov_b32_e32 v168, s17
	v_mov_b32_e32 v169, s23
	v_mov_b32_e32 v180, s25
	v_mov_b32_e32 v181, s26
	ds_read_b32 v126, v208
	ds_read_b32 v118, v210
	ds_read_b32 v182, v208 offset:4
	ds_read_b32 v127, v208 offset:16384
	ds_read_b32 v119, v210 offset:16384
	ds_read_b32 v183, v208 offset:16388
	ds_read_b32 v110, v208 offset:2048
	ds_read_b32 v102, v208 offset:2044
	ds_read_b32 v184, v208 offset:2052
	ds_read_b32 v111, v208 offset:18432
	ds_read_b32 v103, v208 offset:18428
	ds_read_b32 v185, v208 offset:18436
	s_waitcnt lgkmcnt(10)
	v_cndmask_b32_e64 v118, v118, 0, s[10:11]
	s_waitcnt lgkmcnt(7)
	v_cndmask_b32_e64 v119, v119, 0, s[10:11]
	v_pk_fma_f32 v[148:149], v[168:169], v[126:127], v[180:181] op_sel:[1,0,1]
	v_pk_fma_f32 v[148:149], v[168:169], v[118:119], v[148:149] op_sel_hi:[0,1,1]
	s_waitcnt lgkmcnt(6)
	v_pk_fma_f32 v[148:149], v[180:181], v[182:183], v[148:149] op_sel_hi:[0,1,1]
	s_waitcnt lgkmcnt(2)
	v_pk_fma_f32 v[150:151], v[168:169], v[110:111], v[180:181] op_sel:[1,0,1]
	s_waitcnt lgkmcnt(1)
	v_pk_fma_f32 v[150:151], v[168:169], v[102:103], v[150:151] op_sel_hi:[0,1,1]
	s_waitcnt lgkmcnt(0)
	v_pk_fma_f32 v[150:151], v[180:181], v[184:185], v[150:151] op_sel_hi:[0,1,1]
	ds_read_b32 v186, v208 offset:4096
	ds_read_b32 v188, v208 offset:4092
	ds_read_b32 v126, v208 offset:4100
	ds_read_b32 v187, v208 offset:20480
	ds_read_b32 v189, v208 offset:20476
	ds_read_b32 v127, v208 offset:20484
	ds_read_b32 v118, v208 offset:6144
	ds_read_b32 v182, v208 offset:6140
	ds_read_b32 v110, v208 offset:6148
	ds_read_b32 v119, v208 offset:22528
	ds_read_b32 v183, v208 offset:22524
	ds_read_b32 v111, v208 offset:22532
	s_waitcnt lgkmcnt(8)
	v_pk_fma_f32 v[152:153], v[168:169], v[186:187], v[180:181] op_sel:[1,0,1]
	s_waitcnt lgkmcnt(7)
	v_pk_fma_f32 v[152:153], v[168:169], v[188:189], v[152:153] op_sel_hi:[0,1,1]
	s_waitcnt lgkmcnt(6)
	v_pk_fma_f32 v[152:153], v[180:181], v[126:127], v[152:153] op_sel_hi:[0,1,1]
	s_waitcnt lgkmcnt(2)
	v_pk_fma_f32 v[154:155], v[168:169], v[118:119], v[180:181] op_sel:[1,0,1]
	s_waitcnt lgkmcnt(1)
	v_pk_fma_f32 v[154:155], v[168:169], v[182:183], v[154:155] op_sel_hi:[0,1,1]
	s_waitcnt lgkmcnt(0)
	v_pk_fma_f32 v[154:155], v[180:181], v[110:111], v[154:155] op_sel_hi:[0,1,1]
	ds_read_b32 v102, v208 offset:8192
	ds_read_b32 v184, v208 offset:8188
	ds_read_b32 v186, v208 offset:8196
	ds_read_b32 v103, v208 offset:24576
	ds_read_b32 v185, v208 offset:24572
	ds_read_b32 v187, v208 offset:24580
	ds_read_b32 v188, v208 offset:10240
	ds_read_b32 v126, v208 offset:10236
	ds_read_b32 v118, v208 offset:10244
	ds_read_b32 v189, v208 offset:26624
	ds_read_b32 v127, v208 offset:26620
	ds_read_b32 v119, v208 offset:26628
	s_waitcnt lgkmcnt(8)
	v_pk_fma_f32 v[158:159], v[168:169], v[102:103], v[180:181] op_sel:[1,0,1]
	s_waitcnt lgkmcnt(7)
	v_pk_fma_f32 v[158:159], v[168:169], v[184:185], v[158:159] op_sel_hi:[0,1,1]
	s_waitcnt lgkmcnt(6)
	v_pk_fma_f32 v[158:159], v[180:181], v[186:187], v[158:159] op_sel_hi:[0,1,1]
	s_waitcnt lgkmcnt(2)
	v_pk_fma_f32 v[160:161], v[168:169], v[188:189], v[180:181] op_sel:[1,0,1]
	s_waitcnt lgkmcnt(1)
	v_pk_fma_f32 v[160:161], v[168:169], v[126:127], v[160:161] op_sel_hi:[0,1,1]
	s_waitcnt lgkmcnt(0)
	v_pk_fma_f32 v[160:161], v[180:181], v[118:119], v[160:161] op_sel_hi:[0,1,1]
	ds_read_b32 v182, v208 offset:12288
	ds_read_b32 v110, v208 offset:12284
	ds_read_b32 v102, v208 offset:12292
	ds_read_b32 v183, v208 offset:28672
	ds_read_b32 v111, v208 offset:28668
	ds_read_b32 v103, v208 offset:28676
	ds_read_b32 v184, v208 offset:14336
	ds_read_b32 v186, v208 offset:14332
	ds_read_b32 v188, v208 offset:14340
	ds_read_b32 v185, v208 offset:30720
	ds_read_b32 v187, v208 offset:30716
	ds_read_b32 v189, v208 offset:30724
	s_waitcnt lgkmcnt(8)
	v_pk_fma_f32 v[162:163], v[168:169], v[182:183], v[180:181] op_sel:[1,0,1]
	s_waitcnt lgkmcnt(7)
	v_pk_fma_f32 v[162:163], v[168:169], v[110:111], v[162:163] op_sel_hi:[0,1,1]
	s_waitcnt lgkmcnt(6)
	v_pk_fma_f32 v[162:163], v[180:181], v[102:103], v[162:163] op_sel_hi:[0,1,1]
	s_waitcnt lgkmcnt(3)
	v_cndmask_b32_e64 v188, v188, 0, s[28:29]
	s_waitcnt lgkmcnt(0)
	v_cndmask_b32_e64 v189, v189, 0, s[28:29]
	v_pk_fma_f32 v[164:165], v[168:169], v[184:185], v[180:181] op_sel:[1,0,1]
	v_pk_fma_f32 v[164:165], v[168:169], v[186:187], v[164:165] op_sel_hi:[0,1,1]
	v_pk_fma_f32 v[164:165], v[180:181], v[188:189], v[164:165] op_sel_hi:[0,1,1]
	s_waitcnt lgkmcnt(0)
	s_barrier
; #define LAS __attribute__((address_space(3)))
; __device__ __forceinline__ f32x2 cmul(f32x2 a, f32x2 b) { return (f32x2){a.x * b.x - a.y * b.y, a.x * b.y + a.y * b.x}; }
; __device__ __forceinline__ void dft16_fwd_lo(f32x2 (&x)[16]) {
;     constexpr float C1 = 0.92387953251128674f, S1 = 0.38268343236508977f, C2 = 0.70710678118654752f;
; #pragma unroll
;     for (int b = 0; b < 4; ++b) { const f32x2 x0 = x[b], x1 = x[4 + b]; const f32x2 j1 = {x1.y, -x1.x};
;         x[b] = x0 + x1; x[4 + b] = x0 + j1; x[8 + b] = x0 - x1; x[12 + b] = x0 - j1; }
;     const f32x2 w1 = {C1, -S1}, w2 = {C2, -C2}, w3 = {S1, -C1}, w4 = {0.f, -1.f}, w6 = {-C2, -C2}, w9 = {-C1, S1};
;     x[5] = cmul(x[5], w1); x[6] = cmul(x[6], w2); x[7] = cmul(x[7], w3);
;     x[9] = cmul(x[9], w2); x[10] = cmul(x[10], w4); x[11] = cmul(x[11], w6);
;     x[13] = cmul(x[13], w3); x[14] = cmul(x[14], w6); x[15] = cmul(x[15], w9);
; #pragma unroll
;     for (int c = 0; c < 4; ++c) dft4<false>(x[4 * c], x[4 * c + 1], x[4 * c + 2], x[4 * c + 3]);
;     f32x2 y[16];
; #pragma unroll
;     for (int k = 0; k < 16; ++k) y[k] = x[4 * (k & 3) + (k >> 2)];
; #pragma unroll
;     for (int k = 0; k < 16; ++k) x[k] = y[k];
; }
; template <bool LO> __device__ __forceinline__ void fft_fwd1(f32x2 (&x)[16], LAS f32x2* B, int n2, const f32x2 (&w)[16]) {
;     asm volatile("" : "+v"(n2));
;     if (LO) dft16_fwd_lo(x); else dft16<false>(x);
;     B[fpad(n2)] = x[0];
; #pragma unroll
;     for (int k = 1; k < 16; ++k) B[fpad(512 * k + n2)] = cmul(x[k], w[k]);
; }
	v_pk_add_f32 v[104:105], v[132:133], v[140:141] neg_lo:[0,1] neg_hi:[0,1]
	v_pk_add_f32 v[106:107], v[132:133], v[140:141] op_sel:[0,1] op_sel_hi:[1,0] neg_lo:[0,1]
	v_pk_add_f32 v[126:127], v[132:133], v[140:141] op_sel:[0,1] op_sel_hi:[1,0] neg_hi:[0,1]
	v_pk_add_f32 v[100:101], v[132:133], v[140:141]
	v_pk_add_f32 v[112:113], v[134:135], v[142:143] neg_lo:[0,1] neg_hi:[0,1]
	v_pk_add_f32 v[114:115], v[134:135], v[142:143] op_sel:[0,1] op_sel_hi:[1,0] neg_lo:[0,1]
	v_pk_add_f32 v[118:119], v[134:135], v[142:143] op_sel:[0,1] op_sel_hi:[1,0] neg_hi:[0,1]
	v_pk_add_f32 v[108:109], v[134:135], v[142:143]
	v_pk_add_f32 v[120:121], v[136:137], v[144:145] neg_lo:[0,1] neg_hi:[0,1]
	v_pk_add_f32 v[122:123], v[136:137], v[144:145] op_sel:[0,1] op_sel_hi:[1,0] neg_lo:[0,1]
	v_pk_add_f32 v[182:183], v[136:137], v[144:145] op_sel:[0,1] op_sel_hi:[1,0] neg_hi:[0,1]
	v_pk_add_f32 v[116:117], v[136:137], v[144:145]
	v_pk_add_f32 v[128:129], v[138:139], v[146:147] neg_lo:[0,1] neg_hi:[0,1]
	v_pk_add_f32 v[130:131], v[138:139], v[146:147] op_sel:[0,1] op_sel_hi:[1,0] neg_lo:[0,1]
	v_pk_add_f32 v[110:111], v[138:139], v[146:147] op_sel:[0,1] op_sel_hi:[1,0] neg_hi:[0,1]
	v_pk_add_f32 v[124:125], v[138:139], v[146:147]
	v_pk_mul_f32 v[102:103], v[118:119], s[68:69] op_sel:[1,1] op_sel_hi:[0,1]
	v_pk_fma_f32 v[118:119], v[118:119], s[68:69], v[102:103] op_sel_hi:[1,0,1] neg_lo:[0,0,1]
	v_pk_mul_f32 v[184:185], v[182:183], s[84:85] op_sel:[1,1] op_sel_hi:[0,1]
	v_pk_fma_f32 v[182:183], v[182:183], s[84:85], v[184:185] op_sel_hi:[1,0,1] neg_lo:[0,0,1]
	v_pk_mul_f32 v[186:187], v[110:111], s[88:89] op_sel:[1,1] op_sel_hi:[0,1]
	v_pk_fma_f32 v[110:111], v[110:111], s[88:89], v[186:187] op_sel_hi:[1,0,1] neg_lo:[0,0,1]
	v_pk_mul_f32 v[188:189], v[112:113], s[84:85] op_sel:[1,1] op_sel_hi:[0,1]
	v_pk_fma_f32 v[112:113], v[112:113], s[84:85], v[188:189] op_sel_hi:[1,0,1] neg_lo:[0,0,1]
	v_pk_mul_f32 v[168:169], v[128:129], s[90:91] op_sel:[1,1] op_sel_hi:[0,1]
	v_pk_fma_f32 v[128:129], v[128:129], s[90:91], v[168:169] op_sel_hi:[1,0,1] neg_lo:[0,0,1]
	v_pk_mul_f32 v[180:181], v[114:115], s[88:89] op_sel:[1,1] op_sel_hi:[0,1]
	v_pk_fma_f32 v[114:115], v[114:115], s[88:89], v[180:181] op_sel_hi:[1,0,1] neg_lo:[0,0,1]
	v_pk_mul_f32 v[178:179], v[122:123], s[90:91] op_sel:[1,1] op_sel_hi:[0,1]
	v_pk_fma_f32 v[122:123], v[122:123], s[90:91], v[178:179] op_sel_hi:[1,0,1] neg_lo:[0,0,1]
	v_pk_mul_f32 v[176:177], v[130:131], s[98:99] op_sel:[1,1] op_sel_hi:[0,1]
	v_pk_fma_f32 v[130:131], v[130:131], s[98:99], v[176:177] op_sel_hi:[1,0,1] neg_lo:[0,0,1]
	v_pk_add_f32 v[166:167], v[100:101], v[116:117]
	v_pk_add_f32 v[174:175], v[100:101], v[116:117] neg_lo:[0,1] neg_hi:[0,1]
	v_pk_add_f32 v[102:103], v[108:109], v[124:125]
	v_pk_add_f32 v[184:185], v[108:109], v[124:125] neg_lo:[0,1] neg_hi:[0,1]
	v_pk_add_f32 v[100:101], v[166:167], v[102:103]
	v_pk_add_f32 v[116:117], v[166:167], v[102:103] neg_lo:[0,1] neg_hi:[0,1]
	v_pk_add_f32 v[108:109], v[174:175], v[184:185] op_sel:[0,1] op_sel_hi:[1,0] neg_hi:[0,1]
	v_pk_add_f32 v[124:125], v[174:175], v[184:185] op_sel:[0,1] op_sel_hi:[1,0] neg_lo:[0,1]
	v_pk_add_f32 v[186:187], v[126:127], v[182:183]
	v_pk_add_f32 v[188:189], v[126:127], v[182:183] neg_lo:[0,1] neg_hi:[0,1]
	v_pk_add_f32 v[168:169], v[118:119], v[110:111]
	v_pk_add_f32 v[180:181], v[118:119], v[110:111] neg_lo:[0,1] neg_hi:[0,1]
	v_pk_add_f32 v[126:127], v[186:187], v[168:169]
	v_pk_add_f32 v[182:183], v[186:187], v[168:169] neg_lo:[0,1] neg_hi:[0,1]
	v_pk_add_f32 v[118:119], v[188:189], v[180:181] op_sel:[0,1] op_sel_hi:[1,0] neg_hi:[0,1]
	v_pk_add_f32 v[110:111], v[188:189], v[180:181] op_sel:[0,1] op_sel_hi:[1,0] neg_lo:[0,1]
	v_pk_add_f32 v[178:179], v[104:105], v[120:121] op_sel:[0,1] op_sel_hi:[1,0] neg_hi:[0,1]
	v_pk_add_f32 v[176:177], v[104:105], v[120:121] op_sel:[0,1] op_sel_hi:[1,0] neg_lo:[0,1]
	v_pk_add_f32 v[166:167], v[112:113], v[128:129]
	v_pk_add_f32 v[174:175], v[112:113], v[128:129] neg_lo:[0,1] neg_hi:[0,1]
	v_pk_add_f32 v[104:105], v[178:179], v[166:167]
; #define LAS __attribute__((address_space(3)))
; __device__ __forceinline__ f32x2 cmul(f32x2 a, f32x2 b) { return (f32x2){a.x * b.x - a.y * b.y, a.x * b.y + a.y * b.x}; }
; __device__ __forceinline__ void dft16_fwd_lo(f32x2 (&x)[16]) {
;     constexpr float C1 = 0.92387953251128674f, S1 = 0.38268343236508977f, C2 = 0.70710678118654752f;
; #pragma unroll
;     for (int b = 0; b < 4; ++b) { const f32x2 x0 = x[b], x1 = x[4 + b]; const f32x2 j1 = {x1.y, -x1.x};
;         x[b] = x0 + x1; x[4 + b] = x0 + j1; x[8 + b] = x0 - x1; x[12 + b] = x0 - j1; }
;     const f32x2 w1 = {C1, -S1}, w2 = {C2, -C2}, w3 = {S1, -C1}, w4 = {0.f, -1.f}, w6 = {-C2, -C2}, w9 = {-C1, S1};
;     x[5] = cmul(x[5], w1); x[6] = cmul(x[6], w2); x[7] = cmul(x[7], w3);
;     x[9] = cmul(x[9], w2); x[10] = cmul(x[10], w4); x[11] = cmul(x[11], w6);
;     x[13] = cmul(x[13], w3); x[14] = cmul(x[14], w6); x[15] = cmul(x[15], w9);
; #pragma unroll
;     for (int c = 0; c < 4; ++c) dft4<false>(x[4 * c], x[4 * c + 1], x[4 * c + 2], x[4 * c + 3]);
;     f32x2 y[16];
; #pragma unroll
;     for (int k = 0; k < 16; ++k) y[k] = x[4 * (k & 3) + (k >> 2)];
; #pragma unroll
;     for (int k = 0; k < 16; ++k) x[k] = y[k];
; }
; template <bool LO> __device__ __forceinline__ void fft_fwd1(f32x2 (&x)[16], LAS f32x2* B, int n2, const f32x2 (&w)[16]) {
;     asm volatile("" : "+v"(n2));
;     if (LO) dft16_fwd_lo(x); else dft16<false>(x);
;     B[fpad(n2)] = x[0];
; #pragma unroll
;     for (int k = 1; k < 16; ++k) B[fpad(512 * k + n2)] = cmul(x[k], w[k]);
; }
	v_pk_add_f32 v[120:121], v[178:179], v[166:167] neg_lo:[0,1] neg_hi:[0,1]
	v_pk_add_f32 v[112:113], v[176:177], v[174:175] op_sel:[0,1] op_sel_hi:[1,0] neg_hi:[0,1]
	v_pk_add_f32 v[128:129], v[176:177], v[174:175] op_sel:[0,1] op_sel_hi:[1,0] neg_lo:[0,1]
	v_pk_add_f32 v[102:103], v[106:107], v[122:123]
	v_pk_add_f32 v[184:185], v[106:107], v[122:123] neg_lo:[0,1] neg_hi:[0,1]
	v_pk_add_f32 v[186:187], v[114:115], v[130:131]
	v_pk_add_f32 v[188:189], v[114:115], v[130:131] neg_lo:[0,1] neg_hi:[0,1]
	v_pk_add_f32 v[106:107], v[102:103], v[186:187]
	v_pk_add_f32 v[122:123], v[102:103], v[186:187] neg_lo:[0,1] neg_hi:[0,1]
	v_pk_add_f32 v[114:115], v[184:185], v[188:189] op_sel:[0,1] op_sel_hi:[1,0] neg_hi:[0,1]
	v_pk_add_f32 v[130:131], v[184:185], v[188:189] op_sel:[0,1] op_sel_hi:[1,0] neg_lo:[0,1]
	ds_write_b64 v3, v[100:101]
	v_pk_mul_f32 v[180:181], v[126:127], v[6:7] op_sel:[1,1] op_sel_hi:[0,1]
	v_pk_fma_f32 v[168:169], v[126:127], v[6:7], v[180:181] op_sel_hi:[1,0,1] neg_lo:[0,0,1]
	ds_write_b64 v3, v[168:169] offset:4224
	v_pk_mul_f32 v[176:177], v[104:105], v[8:9] op_sel:[1,1] op_sel_hi:[0,1]
	v_pk_fma_f32 v[178:179], v[104:105], v[8:9], v[176:177] op_sel_hi:[1,0,1] neg_lo:[0,0,1]
	ds_write_b64 v3, v[178:179] offset:8448
	v_pk_mul_f32 v[174:175], v[106:107], v[10:11] op_sel:[1,1] op_sel_hi:[0,1]
	v_pk_fma_f32 v[166:167], v[106:107], v[10:11], v[174:175] op_sel_hi:[1,0,1] neg_lo:[0,0,1]
	ds_write_b64 v3, v[166:167] offset:12672
	v_pk_mul_f32 v[184:185], v[108:109], v[12:13] op_sel:[1,1] op_sel_hi:[0,1]
	v_pk_fma_f32 v[102:103], v[108:109], v[12:13], v[184:185] op_sel_hi:[1,0,1] neg_lo:[0,0,1]
	ds_write_b64 v3, v[102:103] offset:16896
	v_pk_mul_f32 v[188:189], v[118:119], v[14:15] op_sel:[1,1] op_sel_hi:[0,1]
	v_pk_fma_f32 v[186:187], v[118:119], v[14:15], v[188:189] op_sel_hi:[1,0,1] neg_lo:[0,0,1]
	ds_write_b64 v3, v[186:187] offset:21120
	v_pk_mul_f32 v[168:169], v[112:113], v[16:17] op_sel:[1,1] op_sel_hi:[0,1]
	v_pk_fma_f32 v[180:181], v[112:113], v[16:17], v[168:169] op_sel_hi:[1,0,1] neg_lo:[0,0,1]
	ds_write_b64 v3, v[180:181] offset:25344
	v_pk_mul_f32 v[178:179], v[114:115], v[18:19] op_sel:[1,1] op_sel_hi:[0,1]
	v_pk_fma_f32 v[176:177], v[114:115], v[18:19], v[178:179] op_sel_hi:[1,0,1] neg_lo:[0,0,1]
	ds_write_b64 v3, v[176:177] offset:29568
	v_pk_mul_f32 v[166:167], v[116:117], v[20:21] op_sel:[1,1] op_sel_hi:[0,1]
	v_pk_fma_f32 v[174:175], v[116:117], v[20:21], v[166:167] op_sel_hi:[1,0,1] neg_lo:[0,0,1]
	ds_write_b64 v3, v[174:175] offset:33792
	v_pk_mul_f32 v[102:103], v[182:183], v[22:23] op_sel:[1,1] op_sel_hi:[0,1]
	v_pk_fma_f32 v[184:185], v[182:183], v[22:23], v[102:103] op_sel_hi:[1,0,1] neg_lo:[0,0,1]
	ds_write_b64 v3, v[184:185] offset:38016
	v_pk_mul_f32 v[186:187], v[120:121], v[24:25] op_sel:[1,1] op_sel_hi:[0,1]
	v_pk_fma_f32 v[188:189], v[120:121], v[24:25], v[186:187] op_sel_hi:[1,0,1] neg_lo:[0,0,1]
	ds_write_b64 v3, v[188:189] offset:42240
	v_pk_mul_f32 v[180:181], v[122:123], v[26:27] op_sel:[1,1] op_sel_hi:[0,1]
	v_pk_fma_f32 v[168:169], v[122:123], v[26:27], v[180:181] op_sel_hi:[1,0,1] neg_lo:[0,0,1]
	ds_write_b64 v3, v[168:169] offset:46464
	v_pk_mul_f32 v[176:177], v[124:125], v[28:29] op_sel:[1,1] op_sel_hi:[0,1]
	v_pk_fma_f32 v[178:179], v[124:125], v[28:29], v[176:177] op_sel_hi:[1,0,1] neg_lo:[0,0,1]
	ds_write_b64 v3, v[178:179] offset:50688
	v_pk_mul_f32 v[174:175], v[110:111], v[30:31] op_sel:[1,1] op_sel_hi:[0,1]
	v_pk_fma_f32 v[166:167], v[110:111], v[30:31], v[174:175] op_sel_hi:[1,0,1] neg_lo:[0,0,1]
	ds_write_b64 v3, v[166:167] offset:54912
	v_pk_mul_f32 v[184:185], v[128:129], v[32:33] op_sel:[1,1] op_sel_hi:[0,1]
	v_pk_fma_f32 v[102:103], v[128:129], v[32:33], v[184:185] op_sel_hi:[1,0,1] neg_lo:[0,0,1]
	ds_write_b64 v3, v[102:103] offset:59136
	v_pk_mul_f32 v[188:189], v[130:131], v[34:35] op_sel:[1,1] op_sel_hi:[0,1]
	v_pk_fma_f32 v[186:187], v[130:131], v[34:35], v[188:189] op_sel_hi:[1,0,1] neg_lo:[0,0,1]
	ds_write_b64 v3, v[186:187] offset:63360
	s_waitcnt lgkmcnt(0)
	s_barrier
	s_cbranch_vccz .Lhfft_st10
	s_sleep 6
